# attention loops (diff, GQA): per-tile s_barrier replaced by an LDS arrive-counter split barrier (arrive after K write, poll issued early, wait before V write)
# speedup vs baseline: 1.0049x; 1.0049x over previous
; __device__ __forceinline__ int v_st(int k, int c) { const int kk = (k & ~0xC) | ((k & 4) << 1) | ((k & 8) >> 1); return ((kk >> 3) * 4 + (c >> 5)) * 512 + ((kk & 7) * 32 + (c & 31)) * 2; }
; __device__ __forceinline__ int v_rd_base(int lane) { return ((lane & 3) << 3) | (((lane >> 2) & 3) << 6) | (((lane >> 4) & 1) << 5) | (((lane >> 5) & 1) << 8); }
; #define SLOAD(i, k0) do { sr_[i].vs0 = *reinterpret_cast<const bf16x8*>(&Vh[(long)((k0) + sr) * LDP + sc]); sr_[i].vs1 = *reinterpret_cast<const bf16x8*>(&Vh[(long)((k0) + 32 + sr) * LDP + sc]); \
;     sr_[i].ks0 = *reinterpret_cast<const bf16x8*>(&Kh[(long)((k0) + ksr) * LDP + ksc]); if (DK == 128) sr_[i].ks1 = *reinterpret_cast<const bf16x8*>(&Kh[(long)((k0) + 32 + ksr) * LDP + ksc]); } while (0)
; #define HOOK(P0, P1, j) do { if (NA) na_hook(P0, P1, krow0 + (j), q_row, q_col, win_r, win_c, rpb, inv_scale, hi); } while (0)
; template <int DK, bool NA, bool QL, int SD> ...
;     ...
;   char* ql = lds + Q_OFF + (wid * (DK / 16) * 64 + lane) * 16;
; #pragma unroll
;   for (int d = 0; d < 4; ++d) o[d] = f32x16{};
;   const bf16* Qw = Qb + (long)(wid * 32 + r32) * LDP + hi * 8;
; #pragma unroll
;   for (int d0 = 0; d0 < DK / 16; ++d0) { const bf16x8 qv = *reinterpret_cast<const bf16x8*>(Qw + d0 * 16); if (QL) *reinterpret_cast<bf16x8*>(ql + d0 * 1024) = qv; else qr[d0] = qv; }
;   const int sr = tid >> 4, sc = (tid & 15) * 8, vst0 = v_st(sr, sc), vst1 = v_st(32 + sr, sc);
;   const int ksr = DK == 128 ? sr : (tid >> 3), ksc = DK == 128 ? sc : (tid & 7) * 8;
;   const int vb0 = (int)(uintptr_t)V_lds + v_rd_base(lane);
;   struct { bf16x8 vs0, vs1, ks0, ks1; } sr_[SD];
;     ...
;   f32x16 pA0, pA1, pB0, pB1; float mnA, mnB, alA, alB; bf16x8 pa0, pa1, pa2, pa3;
;   constexpr int SE = 0, SO = SD - 1;
;   SLOAD(SE, 0); asm volatile("s_waitcnt vmcnt(0)" ::: "memory"); SWRITE(0, SE); __syncthreads();
;   qkt<DK, QL>(pA0, pA1, K_lds, qr, ql, r32, hi); HOOK(pA0, pA1, 0); partialSM(pA0, pA1, m_reg, mnA, alA, C, thrRaw);
.LBB0_658:
	s_and_b64 vcc, exec, s[0:1]
	s_cbranch_vccz .LBB0_679
	v_mov_b32_e32 v50, v188
	v_readlane_b32 s0, v253, 11
	v_readlane_b32 s1, v253, 12
	v_ashrrev_i32_e32 v53, 6, v50
	v_and_b32_e32 v51, 31, v50
	v_lshl_or_b32 v0, v53, 5, v51
	v_mov_b64_e32 v[2:3], s[0:1]
	s_movk_i32 s3, 0x2800
	v_mad_i64_i32 v[2:3], s[0:1], v0, s3, v[2:3]
	v_lshrrev_b32_e32 v0, 1, v50
	v_and_b32_e32 v0, 16, v0
	v_ashrrev_i32_e32 v52, 4, v50
	v_lshl_add_u64 v[30:31], v[2:3], 0, v[0:1]
	v_lshlrev_b32_e32 v54, 3, v50
	v_add_u32_e32 v55, 32, v52
	s_movk_i32 s9, 0x1400
	global_load_dwordx4 v[2:5], v[30:31], off
	global_load_dwordx4 v[6:9], v[30:31], off offset:32
	global_load_dwordx4 v[10:13], v[30:31], off offset:64
	global_load_dwordx4 v[14:17], v[30:31], off offset:96
	global_load_dwordx4 v[18:21], v[30:31], off offset:128
	global_load_dwordx4 v[22:25], v[30:31], off offset:160
	global_load_dwordx4 v[26:29], v[30:31], off offset:192
	s_nop 0
	global_load_dwordx4 v[30:33], v[30:31], off offset:224
	v_and_b32_e32 v71, 0x78, v54
	v_mad_i64_i32 v[34:35], s[0:1], v52, s9, 0
	v_mad_i64_i32 v[36:37], s[0:1], v55, s9, 0
	v_or_b32_e32 v34, v34, v71
	v_readlane_b32 s6, v253, 15
	v_or_b32_e32 v36, v36, v71
	v_readlane_b32 s4, v253, 13
	v_lshlrev_b64 v[42:43], 1, v[34:35]
	v_readlane_b32 s7, v253, 16
	v_lshlrev_b64 v[44:45], 1, v[36:37]
	v_readlane_b32 s5, v253, 14
	v_lshl_add_u64 v[34:35], s[6:7], 0, v[42:43]
	v_lshl_add_u64 v[38:39], s[6:7], 0, v[44:45]
	v_lshl_add_u64 v[42:43], s[4:5], 0, v[42:43]
	v_lshl_add_u64 v[46:47], s[4:5], 0, v[44:45]
	global_load_dwordx4 v[34:37], v[34:35], off
	s_nop 0
	global_load_dwordx4 v[38:41], v[38:39], off
	s_nop 0
	global_load_dwordx4 v[42:45], v[42:43], off
	s_nop 0
	global_load_dwordx4 v[46:49], v[46:47], off
	v_and_b32_e32 v72, 63, v50
	v_readlane_b32 s0, v254, 57
	v_lshlrev_b32_e32 v57, 4, v72
	v_and_b32_e32 v58, 0xfffff0, v52
	v_lshl_add_u32 v53, v53, 13, s0
	v_lshlrev_b32_e32 v59, 1, v52
	v_lshrrev_b32_e32 v60, 1, v52
	v_and_b32_e32 v61, 3, v52
	v_add_u32_e32 v153, v53, v57
	v_and_or_b32 v53, v59, 8, v58
	v_and_or_b32 v58, v60, 4, v61
	v_and_b32_e32 v60, 0xfffff0, v55
	v_lshlrev_b32_e32 v61, 1, v55
	v_and_b32_e32 v56, 0xf0, v50
	v_bfe_u32 v54, v54, 5, 2
	v_lshlrev_b32_e32 v62, 8, v52
	v_lshlrev_b32_e32 v59, 1, v71
	v_lshlrev_b32_e32 v55, 8, v55
	v_lshrrev_b32_e32 v53, 1, v53
	v_and_or_b32 v60, v61, 8, v60
	v_bitop3_b32 v61, v59, v62, v56 bitop3:0xde
	v_bitop3_b32 v55, v59, v55, v56 bitop3:0xde
	v_or_b32_e32 v53, v53, v54
	v_lshrrev_b32_e32 v56, 1, v60
	v_lshlrev_b32_e32 v58, 6, v58
	v_and_b32_e32 v63, 48, v59
	v_lshlrev_b32_e32 v53, 9, v53
	v_or_b32_e32 v54, v56, v54
	v_or3_b32 v53, v53, v58, v63
	v_lshlrev_b32_e32 v54, 9, v54
	v_or3_b32 v54, v54, v58, v63
	v_add_u32_e32 v209, 0, v53
	v_lshlrev_b32_e32 v53, 8, v51
	v_add_u32_e32 v177, 0, v61
	v_add_u32_e32 v208, 0, v55
	v_add_u32_e32 v210, 0, v54
	v_and_b32_e32 v54, 0x3fffffc0, v50
	s_add_i32 s0, 0, 0x10000
	v_lshl_add_u32 v148, v54, 2, s0
	v_readlane_b32 s12, v254, 62
	s_cmp_lg_u32 0, -1
	v_readlane_b32 s13, v254, 63
	v_readlane_b32 s14, v255, 0
	v_readlane_b32 s15, v255, 1
	s_mov_b32 s8, -1
	s_cselect_b32 s2, 0, 0
	v_readlane_b32 s16, v255, 2
	v_readlane_b32 s17, v255, 3
	s_waitcnt vmcnt(11)
	ds_write_b128 v153, v[2:5]
	s_waitcnt vmcnt(10)
	ds_write_b128 v153, v[6:9] offset:1024
	s_waitcnt vmcnt(9)
	ds_write_b128 v153, v[10:13] offset:2048
	s_waitcnt vmcnt(8)
	ds_write_b128 v153, v[14:17] offset:3072
	s_waitcnt vmcnt(7)
	ds_write_b128 v153, v[18:21] offset:4096
	s_waitcnt vmcnt(6)
	ds_write_b128 v153, v[22:25] offset:5120
	s_waitcnt vmcnt(5)
	ds_write_b128 v153, v[26:29] offset:6144
	s_waitcnt vmcnt(4)
	ds_write_b128 v153, v[30:33] offset:7168
	v_lshlrev_b32_e32 v2, 4, v50
	v_and_b32_e32 v58, 0xf0, v2
	v_bitop3_b32 v2, v0, v53, v58 bitop3:0xde
	v_add_u32_e32 v159, 0, v2
	s_waitcnt vmcnt(0)
	s_waitcnt vmcnt(3)
	ds_write_b128 v209, v[34:37]
	s_waitcnt vmcnt(2)
	ds_write_b128 v210, v[38:41]
	s_waitcnt vmcnt(1)
	ds_write_b128 v177, v[42:45] offset:32768
	s_waitcnt vmcnt(0)
	ds_write_b128 v208, v[46:49] offset:32768
	s_waitcnt lgkmcnt(0)
	s_barrier
	ds_read_b128 v[2:5], v159 offset:32768
	ds_read_b128 v[6:9], v153
	ds_read_b128 v[10:13], v159 offset:40960
	ds_read_b128 v[14:17], v153 offset:1024
	s_waitcnt lgkmcnt(2)
	v_mfma_f32_32x32x16_bf16 v[34:49], v[2:5], v[6:9], 0
	v_or_b32_e32 v2, 32, v0
	v_bitop3_b32 v2, v2, v53, v58 bitop3:0xde
	v_add_u32_e32 v207, 0, v2
	v_readlane_b32 s18, v255, 4
	v_readlane_b32 s19, v255, 5
	v_readlane_b32 s20, v255, 6
	v_readlane_b32 s21, v255, 7
	s_waitcnt lgkmcnt(1)
	v_mfma_f32_32x32x16_bf16 v[18:33], v[10:13], v[6:9], 0
	ds_read_b128 v[2:5], v207 offset:32768
	ds_read_b128 v[6:9], v207 offset:40960
	v_readlane_b32 s22, v255, 8
	v_readlane_b32 s23, v255, 9
	v_readlane_b32 s24, v255, 10
	v_readlane_b32 s25, v255, 11
	v_readlane_b32 s26, v255, 12
	v_readlane_b32 s27, v255, 13
	s_waitcnt lgkmcnt(1)
	v_mfma_f32_32x32x16_bf16 v[34:49], v[2:5], v[14:17], v[34:49]
	v_or_b32_e32 v2, 64, v0
	v_bitop3_b32 v2, v2, v53, v58 bitop3:0xde
	v_add_u32_e32 v161, 0, v2
	s_mov_b32 s12, s13
	s_mov_b32 s14, s13
	s_mov_b32 s15, s13
	s_mov_b32 s1, s13
	s_waitcnt lgkmcnt(0)
	v_mfma_f32_32x32x16_bf16 v[18:33], v[6:9], v[14:17], v[18:33]
	ds_read_b128 v[2:5], v161 offset:32768
	ds_read_b128 v[6:9], v153 offset:2048
	ds_read_b128 v[10:13], v161 offset:40960
	ds_read_b128 v[14:17], v153 offset:3072
	s_mov_b32 s16, s13
	s_mov_b32 s17, s13
	s_mov_b32 s18, s13
	s_mov_b32 s19, s13
	s_mov_b32 s20, s13
	s_mov_b32 s21, s13
	s_waitcnt lgkmcnt(2)
	v_mfma_f32_32x32x16_bf16 v[34:49], v[2:5], v[6:9], v[34:49]
	v_or_b32_e32 v2, 0x60, v0
	v_bitop3_b32 v2, v2, v53, v58 bitop3:0xde
	v_add_u32_e32 v160, 0, v2
	s_mov_b32 s22, s13
	s_mov_b32 s23, s13
	s_mov_b32 s24, s13
	s_mov_b32 s25, s13
	s_waitcnt lgkmcnt(1)
; #define SLOAD(i, k0) do { sr_[i].vs0 = *reinterpret_cast<const bf16x8*>(&Vh[(long)((k0) + sr) * LDP + sc]); sr_[i].vs1 = *reinterpret_cast<const bf16x8*>(&Vh[(long)((k0) + 32 + sr) * LDP + sc]); \
;     sr_[i].ks0 = *reinterpret_cast<const bf16x8*>(&Kh[(long)((k0) + ksr) * LDP + ksc]); if (DK == 128) sr_[i].ks1 = *reinterpret_cast<const bf16x8*>(&Kh[(long)((k0) + 32 + ksr) * LDP + ksc]); } while (0)
; #define HOOK(P0, P1, j) do { if (NA) na_hook(P0, P1, krow0 + (j), q_row, q_col, win_r, win_c, rpb, inv_scale, hi); } while (0)
; __device__ __forceinline__ void partialSM(f32x16& p0, f32x16& p1, float& m_reg, float& mn, float& alpha, float C, float thrRaw) {
;   float pmax = p0[0];
; #pragma unroll
;   for (int r = 1; r < 16; ++r) pmax = fmaxf(pmax, p0[r]);
; #pragma unroll
;   for (int r = 0; r < 16; ++r) pmax = fmaxf(pmax, p1[r]);
;   { auto rr = __builtin_amdgcn_permlane32_swap(__float_as_uint(pmax), __float_as_uint(pmax), false, false);
;     pmax = fmaxf(__uint_as_float(rr[0]), __uint_as_float(rr[1])); }
;   if (__builtin_expect(__all(pmax - m_reg <= thrRaw), 1)) { mn = m_reg; alpha = 1.f; }
;   else { mn = fmaxf(m_reg, pmax); alpha = __builtin_amdgcn_exp2f((m_reg - mn) * C); m_reg = mn; }
;   float mnC = -mn * C;
; #pragma unroll
;   for (int r = 0; r < 16; ++r) p0[r] = fmaf(p0[r], C, mnC);
; #pragma unroll
;   for (int r = 0; r < 16; ++r) p1[r] = fmaf(p1[r], C, mnC);
; #pragma unroll
;   for (int r = 0; r < 16; ++r) p0[r] = __builtin_amdgcn_exp2f(p0[r]);
; }
; template <int DK, bool NA, bool QL, int SD> ...
;     ...
;   qkt<DK, QL>(pA0, pA1, K_lds, qr, ql, r32, hi); HOOK(pA0, pA1, 0); partialSM(pA0, pA1, m_reg, mnA, alA, C, thrRaw);
;   SLOAD(SO, KVBLK); if (SD == 2) { if (2 < NT) SLOAD(SE, 2 * KVBLK); }
	v_mfma_f32_32x32x16_bf16 v[18:33], v[10:13], v[6:9], v[18:33]
	ds_read_b128 v[2:5], v160 offset:32768
	ds_read_b128 v[6:9], v160 offset:40960
	s_mov_b32 s26, s13
	s_mov_b32 s27, s13
	v_mov_b32_e32 v150, 0
	v_lshl_add_u32 v149, v51, 2, v148
	v_mov_b32_e32 v51, v150
	s_waitcnt lgkmcnt(1)
	v_mfma_f32_32x32x16_bf16 v[34:49], v[2:5], v[14:17], v[34:49]
	v_or_b32_e32 v2, 0x80, v0
	v_bitop3_b32 v2, v2, v53, v58 bitop3:0xde
	v_add_u32_e32 v158, 0, v2
	s_waitcnt lgkmcnt(0)
	v_mfma_f32_32x32x16_bf16 v[18:33], v[6:9], v[14:17], v[18:33]
	ds_read_b128 v[2:5], v158 offset:32768
	ds_read_b128 v[6:9], v153 offset:4096
	ds_read_b128 v[10:13], v158 offset:40960
	ds_read_b128 v[14:17], v153 offset:5120
	s_waitcnt lgkmcnt(2)
	v_mfma_f32_32x32x16_bf16 v[34:49], v[2:5], v[6:9], v[34:49]
	v_or_b32_e32 v2, 0xa0, v0
	v_bitop3_b32 v2, v2, v53, v58 bitop3:0xde
	v_add_u32_e32 v156, 0, v2
	ds_read_b128 v[2:5], v156 offset:32768
	s_waitcnt lgkmcnt(2)
	v_mfma_f32_32x32x16_bf16 v[18:33], v[10:13], v[6:9], v[18:33]
	v_lshlrev_b32_e32 v10, 3, v72
	v_and_b32_e32 v6, 0xc0, v57
	v_and_or_b32 v11, v10, 24, v6
	ds_read_b128 v[6:9], v156 offset:40960
	v_lshlrev_b32_e32 v12, 1, v50
	s_waitcnt lgkmcnt(0)
	v_mfma_f32_32x32x16_bf16 v[18:33], v[6:9], v[14:17], v[18:33]
	ds_read_b128 v[6:9], v153 offset:6144
	v_mfma_f32_32x32x16_bf16 v[34:49], v[2:5], v[14:17], v[34:49]
	v_and_b32_e32 v2, 32, v12
	v_and_b32_e32 v3, 0x100, v10
	v_or3_b32 v73, v11, v2, v3
	v_or_b32_e32 v2, 0xc0, v0
	v_bitop3_b32 v2, v2, v53, v58 bitop3:0xde
	v_add_u32_e32 v157, 0, v2
	ds_read_b128 v[2:5], v157 offset:32768
	s_waitcnt lgkmcnt(0)
	v_mfma_f32_32x32x16_bf16 v[34:49], v[2:5], v[6:9], v[34:49]
	v_or_b32_e32 v2, 0xe0, v0
	v_bitop3_b32 v2, v2, v53, v58 bitop3:0xde
	v_add_u32_e32 v176, 0, v2
	ds_read_b128 v[10:13], v157 offset:40960
	ds_read_b128 v[54:57], v153 offset:7168
	ds_read_b128 v[2:5], v176 offset:32768
	ds_read_b128 v[58:61], v176 offset:40960
	v_add_u32_e32 v152, s2, v73
	s_waitcnt lgkmcnt(3)
	v_mfma_f32_32x32x16_bf16 v[18:33], v[10:13], v[6:9], v[18:33]
	v_writelane_b32 v254, s0, 62
	s_nop 1
	v_writelane_b32 v255, s2, 0
	v_writelane_b32 v255, s3, 1
	v_writelane_b32 v255, s4, 2
	v_writelane_b32 v255, s5, 3
	s_waitcnt lgkmcnt(1)
	v_mfma_f32_32x32x16_bf16 v[34:49], v[2:5], v[54:57], v[34:49]
	v_writelane_b32 v255, s6, 4
	v_writelane_b32 v255, s7, 5
	v_writelane_b32 v255, s8, 6
	v_writelane_b32 v255, s9, 7
	v_writelane_b32 v255, s10, 8
	v_writelane_b32 v255, s11, 9
	v_writelane_b32 v255, s12, 10
	s_waitcnt lgkmcnt(0)
	v_mfma_f32_32x32x16_bf16 v[18:33], v[58:61], v[54:57], v[18:33]
	s_nop 2
	v_max_f32_e32 v53, v35, v35
	v_max_f32_e32 v54, v34, v34
	v_max_f32_e32 v53, v54, v53
	v_max3_f32 v53, v53, v36, v37
	v_max3_f32 v53, v53, v38, v39
	v_max3_f32 v53, v53, v40, v41
	v_max3_f32 v53, v53, v42, v43
	v_max3_f32 v53, v53, v44, v45
	v_max3_f32 v53, v53, v46, v47
	v_max3_f32 v53, v53, v48, v49
	v_max3_f32 v53, v53, v18, v19
	v_max3_f32 v53, v53, v20, v21
	v_max3_f32 v53, v53, v22, v23
	v_max3_f32 v53, v53, v24, v25
	v_max3_f32 v53, v53, v26, v27
	v_max3_f32 v53, v53, v28, v29
	v_max3_f32 v53, v53, v30, v31
	v_max3_f32 v53, v53, v32, v33
	v_mov_b32_e32 v70, v53
	v_writelane_b32 v255, s13, 11
	s_nop 0
	v_permlane32_swap_b32_e32 v53, v70
	v_writelane_b32 v255, s14, 12
	v_add_u32_e32 v54, 64, v52
	v_add_u32_e32 v56, 0x60, v52
	v_max_f32_e32 v70, v70, v70
	v_max_f32_e32 v53, v53, v53
	v_writelane_b32 v254, s1, 63
	v_writelane_b32 v255, s15, 13
	v_mad_i64_i32 v[54:55], s[0:1], v54, s9, 0
	v_mad_i64_i32 v[56:57], s[0:1], v56, s9, 0
	v_max_f32_e32 v53, v53, v70
	v_add_f32_e32 v70, 0x7149f2ca, v53
	s_mov_b32 s0, 0x42b504f3
	v_max_f32_e32 v53, 0xf149f2ca, v53
	v_cmp_ge_f32_e32 vcc, s0, v70
	v_sub_f32_e32 v70, 0xf149f2ca, v53
	v_mul_f32_e32 v70, 0x3e0293ee, v70
	v_exp_f32_e32 v70, v70
	s_cmp_eq_u64 vcc, exec
	s_cselect_b64 vcc, -1, 0
	v_cndmask_b32_e32 v134, v53, v199, vcc
	v_cndmask_b32_e64 v211, v70, 1.0, vcc
	v_mul_f32_e32 v70, 0xbe0293ee, v134
	v_fmamk_f32 v53, v34, 0x3e0293ee, v70
	v_add_u32_e32 v34, 0xa0, v52
	v_or_b32_e32 v54, v54, v71
	v_or_b32_e32 v56, v56, v71
	v_fmamk_f32 v74, v35, 0x3e0293ee, v70
	v_fmamk_f32 v77, v38, 0x3e0293ee, v70
	v_mad_i64_i32 v[34:35], s[0:1], v34, s9, 0
	v_add_u32_e32 v38, 0x80, v52
	v_lshlrev_b64 v[62:63], 1, v[54:55]
	v_lshlrev_b64 v[64:65], 1, v[56:57]
	v_fmamk_f32 v78, v39, 0x3e0293ee, v70
	v_or_b32_e32 v34, v34, v71
	v_mad_i64_i32 v[38:39], s[0:1], v38, s9, 0
	v_lshl_add_u64 v[54:55], s[6:7], 0, v[62:63]
	v_lshl_add_u64 v[58:59], s[6:7], 0, v[64:65]
	v_lshl_add_u64 v[62:63], s[4:5], 0, v[62:63]
	v_lshl_add_u64 v[66:67], s[4:5], 0, v[64:65]
	v_lshlrev_b64 v[34:35], 1, v[34:35]
	v_or_b32_e32 v38, v38, v71
	global_load_dwordx4 v[54:57], v[54:55], off
	s_nop 0
	global_load_dwordx4 v[58:61], v[58:59], off
	s_nop 0
	global_load_dwordx4 v[62:65], v[62:63], off
	s_nop 0
	global_load_dwordx4 v[66:69], v[66:67], off
	v_fmamk_f32 v75, v36, 0x3e0293ee, v70
	v_fmamk_f32 v76, v37, 0x3e0293ee, v70
	v_lshl_add_u64 v[36:37], s[4:5], 0, v[34:35]
	v_lshlrev_b64 v[38:39], 1, v[38:39]
	v_lshl_add_u64 v[34:35], s[6:7], 0, v[34:35]
	v_fmamk_f32 v79, v40, 0x3e0293ee, v70
	v_fmamk_f32 v80, v41, 0x3e0293ee, v70
	v_lshl_add_u64 v[40:41], s[4:5], 0, v[38:39]
	global_load_dwordx4 v[102:105], v[36:37], off
	global_load_dwordx4 v[98:101], v[40:41], off
	v_lshl_add_u64 v[36:37], s[6:7], 0, v[38:39]
	global_load_dwordx4 v[110:113], v[34:35], off
	global_load_dwordx4 v[106:109], v[36:37], off
	v_mov_b32_e32 v36, v70
	s_mov_b32 s0, 0x3e0293ee
	s_addk_i32 s2, 0x4000
	v_fmamk_f32 v42, v42, 0x3e0293ee, v70
	v_fmamk_f32 v43, v43, 0x3e0293ee, v70
	v_fmamk_f32 v44, v44, 0x3e0293ee, v70
	v_fmamk_f32 v45, v45, 0x3e0293ee, v70
	v_fmamk_f32 v46, v46, 0x3e0293ee, v70
	v_fmamk_f32 v34, v47, 0x3e0293ee, v70
	v_fmamk_f32 v35, v48, 0x3e0293ee, v70
	v_fmac_f32_e32 v36, 0x3e0293ee, v49
	v_pk_fma_f32 v[126:127], v[18:19], s[0:1], v[70:71] op_sel_hi:[1,0,0]
	v_add_u32_e32 v151, s2, v73
	v_mad_i64_i32 v[18:19], s[2:3], v52, s3, 0
	v_mov_b64_e32 v[2:3], s[12:13]
	v_pk_fma_f32 v[124:125], v[20:21], s[0:1], v[70:71] op_sel_hi:[1,0,0]
	v_exp_f32_e32 v145, v53
	v_exp_f32_e32 v216, v74
	v_exp_f32_e32 v131, v75
	v_exp_f32_e32 v215, v76
	v_exp_f32_e32 v132, v77
	v_exp_f32_e32 v144, v78
	v_exp_f32_e32 v133, v79
	v_exp_f32_e32 v143, v80
	v_exp_f32_e32 v140, v42
	v_exp_f32_e32 v142, v43
	v_exp_f32_e32 v139, v44
	v_exp_f32_e32 v141, v45
	v_exp_f32_e32 v136, v46
	v_exp_f32_e32 v138, v34
	v_exp_f32_e32 v135, v35
	v_exp_f32_e32 v137, v36
	v_and_b32_e32 v20, 15, v50
	v_readlane_b32 s2, v254, 30
	v_mov_b64_e32 v[16:17], s[26:27]
	s_waitcnt vmcnt(4)
; #define SBAR() __builtin_amdgcn_sched_barrier(0)
; #define SWAIT() do { if (SD == 1) asm volatile("s_waitcnt vmcnt(0)" ::: "memory"); else if (DK == 128) asm volatile("s_waitcnt vmcnt(4)" ::: "memory"); else asm volatile("s_waitcnt vmcnt(3)" ::: "memory"); } while (0)
; #define HOOK(P0, P1, j) do { if (NA) na_hook(P0, P1, krow0 + (j), q_row, q_col, win_r, win_c, rpb, inv_scale, hi); } while (0)
; template <int DK, bool NA, bool QL, int SD> ...
;     ...
;   for (int d = 0; d < 4; ++d) o[d] = f32x16{};
;     ...
;   SWAIT(); SWRITE(1, SO); __syncthreads();
;   for (int j = 1; j + 1 < NT; j += 2) {
;     SBAR(); qkt<DK, QL>(pB0, pB1, (bf16*)((char*)K_lds + SHM_K), qr, ql, r32, hi); HOOK(pB0, pB1, j);
;     finishSM(pA0, pA1, alA, l_reg, pa0, pa1, pa2, pa3); SBAR();
	v_lshl_or_b32 v18, v20, 4, v18
	v_readlane_b32 s3, v254, 31
	v_mov_b64_e32 v[4:5], s[14:15]
	v_mov_b64_e32 v[6:7], s[16:17]
	v_mov_b64_e32 v[8:9], s[18:19]
	v_mov_b64_e32 v[10:11], s[20:21]
	v_mov_b64_e32 v[12:13], s[22:23]
	v_mov_b64_e32 v[14:15], s[24:25]
	v_pk_fma_f32 v[120:121], v[32:33], s[0:1], v[70:71] op_sel_hi:[1,0,0]
	v_pk_fma_f32 v[122:123], v[30:31], s[0:1], v[70:71] op_sel_hi:[1,0,0]
	v_pk_fma_f32 v[128:129], v[28:29], s[0:1], v[70:71] op_sel_hi:[1,0,0]
	v_pk_fma_f32 v[114:115], v[26:27], s[0:1], v[70:71] op_sel_hi:[1,0,0]
	v_pk_fma_f32 v[116:117], v[24:25], s[0:1], v[70:71] op_sel_hi:[1,0,0]
	v_pk_fma_f32 v[118:119], v[22:23], s[0:1], v[70:71] op_sel_hi:[1,0,0]
	v_lshl_add_u64 v[146:147], s[2:3], 0, v[18:19]
	v_mov_b64_e32 v[32:33], v[16:17]
	s_waitcnt vmcnt(7)
	ds_write_b128 v209, v[54:57] offset:16384
	s_waitcnt vmcnt(6)
	ds_write_b128 v210, v[58:61] offset:16384
	s_waitcnt vmcnt(5)
	ds_write_b128 v177, v[62:65] offset:49152
	s_waitcnt vmcnt(4)
	ds_write_b128 v208, v[66:69] offset:49152
	v_cmp_gt_u32_e64 s[0:1], 32, v72
	v_mov_b64_e32 v[30:31], v[14:15]
	v_mov_b64_e32 v[28:29], v[12:13]
	v_mov_b64_e32 v[26:27], v[10:11]
	v_mov_b64_e32 v[24:25], v[8:9]
	v_mov_b64_e32 v[22:23], v[6:7]
	v_mov_b64_e32 v[20:21], v[4:5]
	v_mov_b64_e32 v[18:19], v[2:3]
	v_mov_b32_e32 v34, 0
	v_mov_b32_e32 v35, v150
	v_mov_b32_e32 v36, v150
	v_mov_b32_e32 v37, v150
	v_mov_b32_e32 v38, v150
	v_mov_b32_e32 v39, v150
	v_mov_b32_e32 v40, v150
	v_mov_b32_e32 v41, v150
	v_mov_b32_e32 v42, v150
	v_mov_b32_e32 v43, v150
	v_mov_b32_e32 v44, v150
	v_mov_b32_e32 v45, v150
	v_mov_b32_e32 v46, v150
	v_mov_b32_e32 v47, v150
	v_mov_b32_e32 v48, v150
	v_mov_b32_e32 v49, v150
	v_mov_b32_e32 v50, 0
	v_mov_b32_e32 v52, v150
	v_mov_b32_e32 v53, v150
	v_mov_b32_e32 v54, v150
	v_mov_b32_e32 v55, v150
	v_mov_b32_e32 v56, v150
	v_mov_b32_e32 v57, v150
	v_mov_b32_e32 v58, v150
	v_mov_b32_e32 v59, v150
	v_mov_b32_e32 v60, v150
	v_mov_b32_e32 v61, v150
	v_mov_b32_e32 v62, v150
	v_mov_b32_e32 v63, v150
	v_mov_b32_e32 v64, v150
	v_mov_b32_e32 v65, v150
	v_mov_b32_e32 v162, 0x27e00
	v_mov_b32_e32 v178, 0
	v_mov_b32_e32 v179, 1
	v_mov_b32_e32 v180, 8
	ds_write_b32 v162, v178
	s_waitcnt lgkmcnt(0)
	s_barrier
.LBB0_660:
	ds_read_b128 v[66:69], v153
	ds_read_b128 v[70:73], v159 offset:49152
	ds_read_b128 v[74:77], v159 offset:57344
	ds_read_b128 v[218:221], v153 offset:1024
	ds_read_b128 v[222:225], v207 offset:49152
	ds_read_b128 v[226:229], v207 offset:57344
	v_add_f32_e32 v130, 0, v145
	v_add_f32_e32 v130, v216, v130
	s_waitcnt lgkmcnt(4)
	v_mfma_f32_32x32x16_bf16 v[82:97], v[70:73], v[66:69], 0
	v_add_f32_e32 v130, v131, v130
	v_add_f32_e32 v130, v215, v130
	v_add_f32_e32 v130, v132, v130
	v_add_f32_e32 v130, v144, v130
	v_add_f32_e32 v130, v133, v130
	v_add_f32_e32 v130, v143, v130
	v_add_f32_e32 v130, v140, v130
	s_waitcnt lgkmcnt(3)
	v_mfma_f32_32x32x16_bf16 v[66:81], v[74:77], v[66:69], 0
	v_add_f32_e32 v130, v142, v130
	v_add_f32_e32 v130, v139, v130
	v_add_f32_e32 v130, v141, v130
	v_exp_f32_e32 v126, v126
	v_add_f32_e32 v130, v136, v130
	v_exp_f32_e32 v127, v127
	v_add_f32_e32 v130, v138, v130
	s_waitcnt lgkmcnt(1)
	v_mfma_f32_32x32x16_bf16 v[82:97], v[222:225], v[218:221], v[82:97]
	v_exp_f32_e32 v124, v124
	v_add_f32_e32 v130, v135, v130
	v_exp_f32_e32 v125, v125
	v_add_f32_e32 v130, v137, v130
	v_exp_f32_e32 v118, v118
	v_add_f32_e32 v130, v126, v130
	v_exp_f32_e32 v119, v119
	s_waitcnt lgkmcnt(0)
	v_mfma_f32_32x32x16_bf16 v[66:81], v[226:229], v[218:221], v[66:81]
	ds_read_b128 v[218:221], v153 offset:2048
	ds_read_b128 v[222:225], v161 offset:49152
	ds_read_b128 v[226:229], v161 offset:57344
	v_add_f32_e32 v130, v127, v130
	v_exp_f32_e32 v116, v116
	v_add_f32_e32 v130, v124, v130
	v_exp_f32_e32 v117, v117
	v_add_f32_e32 v130, v125, v130
	v_exp_f32_e32 v114, v114
	s_waitcnt lgkmcnt(1)
	v_mfma_f32_32x32x16_bf16 v[82:97], v[222:225], v[218:221], v[82:97]
	v_add_f32_e32 v130, v118, v130
	v_exp_f32_e32 v115, v115
	v_add_f32_e32 v130, v119, v130
	v_exp_f32_e32 v128, v128
	v_add_f32_e32 v130, v116, v130
	v_exp_f32_e32 v129, v129
	v_add_f32_e32 v130, v117, v130
	s_waitcnt lgkmcnt(0)
	v_mfma_f32_32x32x16_bf16 v[66:81], v[226:229], v[218:221], v[66:81]
	ds_read_b128 v[218:221], v153 offset:3072
	ds_read_b128 v[222:225], v160 offset:49152
	ds_read_b128 v[226:229], v160 offset:57344
	v_exp_f32_e32 v122, v122
	v_add_f32_e32 v130, v114, v130
	v_exp_f32_e32 v123, v123
	v_add_f32_e32 v130, v115, v130
	v_exp_f32_e32 v120, v120
	v_add_f32_e32 v130, v128, v130
	s_waitcnt lgkmcnt(1)
	v_mfma_f32_32x32x16_bf16 v[82:97], v[222:225], v[218:221], v[82:97]
	v_exp_f32_e32 v121, v121
	v_add_f32_e32 v130, v129, v130
	v_add_f32_e32 v130, v122, v130
	v_add_f32_e32 v130, v123, v130
	v_add_f32_e32 v130, v120, v130
	v_add_f32_e32 v212, v121, v130
	v_mov_b32_e32 v213, v212
	s_waitcnt lgkmcnt(0)
	v_mfma_f32_32x32x16_bf16 v[66:81], v[226:229], v[218:221], v[66:81]
	ds_read_b128 v[218:221], v153 offset:4096
	ds_read_b128 v[222:225], v158 offset:49152
	ds_read_b128 v[226:229], v158 offset:57344
	v_permlane32_swap_b32_e32 v212, v213
	s_waitcnt lgkmcnt(1)
	v_mfma_f32_32x32x16_bf16 v[82:97], v[222:225], v[218:221], v[82:97]
	s_waitcnt lgkmcnt(0)
	v_mfma_f32_32x32x16_bf16 v[66:81], v[226:229], v[218:221], v[66:81]
	ds_read_b128 v[218:221], v153 offset:5120
	ds_read_b128 v[222:225], v156 offset:49152
	ds_read_b128 v[226:229], v156 offset:57344
	s_waitcnt lgkmcnt(1)
	v_mfma_f32_32x32x16_bf16 v[82:97], v[222:225], v[218:221], v[82:97]
	s_waitcnt lgkmcnt(0)
	v_mfma_f32_32x32x16_bf16 v[66:81], v[226:229], v[218:221], v[66:81]
	ds_read_b128 v[218:221], v153 offset:6144
	ds_read_b128 v[222:225], v157 offset:49152
	ds_read_b128 v[226:229], v157 offset:57344
	s_waitcnt lgkmcnt(1)
; #define SBAR() __builtin_amdgcn_sched_barrier(0)
; #define SLOAD(i, k0) do { sr_[i].vs0 = *reinterpret_cast<const bf16x8*>(&Vh[(long)((k0) + sr) * LDP + sc]); sr_[i].vs1 = *reinterpret_cast<const bf16x8*>(&Vh[(long)((k0) + 32 + sr) * LDP + sc]); \
;     sr_[i].ks0 = *reinterpret_cast<const bf16x8*>(&Kh[(long)((k0) + ksr) * LDP + ksc]); if (DK == 128) sr_[i].ks1 = *reinterpret_cast<const bf16x8*>(&Kh[(long)((k0) + 32 + ksr) * LDP + ksc]); } while (0)
; #define SWAIT() do { if (SD == 1) asm volatile("s_waitcnt vmcnt(0)" ::: "memory"); else if (DK == 128) asm volatile("s_waitcnt vmcnt(4)" ::: "memory"); else asm volatile("s_waitcnt vmcnt(3)" ::: "memory"); } while (0)
; #define HOOK(P0, P1, j) do { if (NA) na_hook(P0, P1, krow0 + (j), q_row, q_col, win_r, win_c, rpb, inv_scale, hi); } while (0)
; template <int D0> __device__ __forceinline__ void pv_one(f32x16& od, int vb, bf16x8 pa0, bf16x8 pa1, bf16x8 pa2, bf16x8 pa3) {
;   const s16x4 l0 = tr_read<v_rd_off(D0, 0, 0)>(vb), h0 = tr_read<v_rd_off(D0, 0, 1)>(vb), l1 = tr_read<v_rd_off(D0, 1, 0)>(vb), h1 = tr_read<v_rd_off(D0, 1, 1)>(vb);
;   const s16x4 l2 = tr_read<v_rd_off(D0, 2, 0)>(vb), h2 = tr_read<v_rd_off(D0, 2, 1)>(vb), l3 = tr_read<v_rd_off(D0, 3, 0)>(vb), h3 = tr_read<v_rd_off(D0, 3, 1)>(vb);
;   asm volatile("s_waitcnt lgkmcnt(0)" ::: "memory"); SBAR();
;     ...
;   od = __builtin_amdgcn_mfma_f32_32x32x16_bf16(pa0, PK(l0, h0), od, 0, 0, 0);
;   od = __builtin_amdgcn_mfma_f32_32x32x16_bf16(pa1, PK(l1, h1), od, 0, 0, 0);
;   od = __builtin_amdgcn_mfma_f32_32x32x16_bf16(pa2, PK(l2, h2), od, 0, 0, 0);
;   od = __builtin_amdgcn_mfma_f32_32x32x16_bf16(pa3, PK(l3, h3), od, 0, 0, 0);
;     ...
; }
; template <int DK, bool NA, bool QL, int SD> ...
;     ...
;     SBAR(); qkt<DK, QL>(pB0, pB1, (bf16*)((char*)K_lds + SHM_K), qr, ql, r32, hi); HOOK(pB0, pB1, j);
;     finishSM(pA0, pA1, alA, l_reg, pa0, pa1, pa2, pa3); SBAR();
;     SLOAD(SO, (j + SD) * KVBLK); SBAR();
;     pv_d0(o, vb0, pa0, pa1, pa2, pa3); partialSM(pB0, pB1, m_reg, mnB, alB, C, thrRaw);
;     __syncthreads(); SWAIT(); SWRITE(0, SE);
	v_mfma_f32_32x32x16_bf16 v[82:97], v[222:225], v[218:221], v[82:97]
	s_waitcnt lgkmcnt(0)
	v_mfma_f32_32x32x16_bf16 v[66:81], v[226:229], v[218:221], v[66:81]
	ds_read_b128 v[218:221], v153 offset:7168
	ds_read_b128 v[222:225], v176 offset:49152
	ds_read_b128 v[226:229], v176 offset:57344
	v_cvt_pk_bf16_f32 v130, v145, v216
	v_cvt_pk_bf16_f32 v131, v131, v215
	v_cvt_pk_bf16_f32 v132, v132, v144
	v_cvt_pk_bf16_f32 v133, v133, v143
	v_cvt_pk_bf16_f32 v140, v140, v142
	v_cvt_pk_bf16_f32 v141, v139, v141
	s_waitcnt lgkmcnt(1)
	v_mfma_f32_32x32x16_bf16 v[82:97], v[222:225], v[218:221], v[82:97]
	v_cvt_pk_bf16_f32 v142, v136, v138
	v_cvt_pk_bf16_f32 v143, v135, v137
	v_cvt_pk_bf16_f32 v136, v126, v127
	v_cvt_pk_bf16_f32 v137, v124, v125
	v_cvt_pk_bf16_f32 v138, v118, v119
	v_cvt_pk_bf16_f32 v139, v116, v117
	v_cvt_pk_bf16_f32 v214, v114, v115
	s_waitcnt lgkmcnt(0)
	v_mfma_f32_32x32x16_bf16 v[66:81], v[226:229], v[218:221], v[66:81]
	v_cvt_pk_bf16_f32 v215, v128, v129
	v_cvt_pk_bf16_f32 v216, v122, v123
	v_permlane32_swap_b32_e32 v130, v132
	v_cvt_pk_bf16_f32 v217, v120, v121
	v_permlane32_swap_b32_e32 v214, v216
	v_permlane32_swap_b32_e32 v131, v133
	v_permlane32_swap_b32_e32 v140, v142
	v_permlane32_swap_b32_e32 v141, v143
	v_permlane32_swap_b32_e32 v136, v138
	v_permlane32_swap_b32_e32 v137, v139
	v_permlane32_swap_b32_e32 v215, v217
	s_mov_b32 s2, 0xfff10000
	v_add_co_u32_e32 v118, vcc, s2, v146
	s_mov_b32 s2, 0xfff60000
	s_nop 0
	v_addc_co_u32_e32 v119, vcc, -1, v147, vcc
	v_add_co_u32_e32 v122, vcc, s2, v146
	s_nop 1
	v_addc_co_u32_e32 v123, vcc, -1, v147, vcc
	global_load_dwordx4 v[114:117], v[118:119], off
	s_nop 0
	global_load_dwordx4 v[118:121], v[118:119], off offset:-512
	s_nop 0
	global_load_dwordx4 v[126:129], v[122:123], off
	s_nop 0
	global_load_dwordx4 v[122:125], v[122:123], off offset:-512
	ds_read_b64_tr_b16 v[218:219], v152 offset:0
	ds_read_b64_tr_b16 v[220:221], v152 offset:0x800
	ds_read_b64_tr_b16 v[222:223], v152 offset:0x1000
	ds_read_b64_tr_b16 v[224:225], v152 offset:0x1800
	ds_read_b64_tr_b16 v[226:227], v152 offset:0x2000
	ds_read_b64_tr_b16 v[228:229], v152 offset:0x2800
	ds_read_b64_tr_b16 v[230:231], v152 offset:0x3000
	ds_read_b64_tr_b16 v[232:233], v152 offset:0x3800
	s_waitcnt lgkmcnt(6)
	s_nop 0
	v_mfma_f32_32x32x16_bf16 v[18:33], v[130:133], v[218:221], v[18:33]
	ds_read_b64_tr_b16 v[218:219], v152 offset:0x200
	ds_read_b64_tr_b16 v[220:221], v152 offset:0xa00
	s_waitcnt lgkmcnt(6)
	v_mfma_f32_32x32x16_bf16 v[18:33], v[140:143], v[222:225], v[18:33]
	ds_read_b64_tr_b16 v[222:223], v152 offset:0x1200
	ds_read_b64_tr_b16 v[224:225], v152 offset:0x1a00
	s_waitcnt lgkmcnt(6)
	v_mfma_f32_32x32x16_bf16 v[18:33], v[136:139], v[226:229], v[18:33]
	ds_read_b64_tr_b16 v[226:227], v152 offset:0x2200
	ds_read_b64_tr_b16 v[228:229], v152 offset:0x2a00
	s_waitcnt lgkmcnt(6)
	v_mfma_f32_32x32x16_bf16 v[18:33], v[214:217], v[230:233], v[18:33]
	ds_read_b64_tr_b16 v[230:231], v152 offset:0x3200
	ds_read_b64_tr_b16 v[232:233], v152 offset:0x3a00
	s_waitcnt lgkmcnt(6)
	v_mfma_f32_32x32x16_bf16 v[50:65], v[130:133], v[218:221], v[50:65]
	ds_read_b64_tr_b16 v[218:219], v152 offset:0x400
	ds_read_b64_tr_b16 v[220:221], v152 offset:0xc00
	s_waitcnt lgkmcnt(6)
	v_mfma_f32_32x32x16_bf16 v[50:65], v[140:143], v[222:225], v[50:65]
	ds_read_b64_tr_b16 v[222:223], v152 offset:0x1400
	ds_read_b64_tr_b16 v[224:225], v152 offset:0x1c00
	s_waitcnt lgkmcnt(6)
	v_mfma_f32_32x32x16_bf16 v[50:65], v[136:139], v[226:229], v[50:65]
	ds_read_b64_tr_b16 v[226:227], v152 offset:0x2400
	ds_read_b64_tr_b16 v[228:229], v152 offset:0x2c00
	s_waitcnt lgkmcnt(6)
	v_mfma_f32_32x32x16_bf16 v[50:65], v[214:217], v[230:233], v[50:65]
	ds_read_b64_tr_b16 v[230:231], v152 offset:0x3400
	ds_read_b64_tr_b16 v[232:233], v152 offset:0x3c00
	s_waitcnt lgkmcnt(6)
	v_mfma_f32_32x32x16_bf16 v[2:17], v[130:133], v[218:221], v[2:17]
	ds_read_b64_tr_b16 v[218:219], v152 offset:0x600
	ds_read_b64_tr_b16 v[220:221], v152 offset:0xe00
	s_waitcnt lgkmcnt(6)
	v_mfma_f32_32x32x16_bf16 v[2:17], v[140:143], v[222:225], v[2:17]
	ds_read_b64_tr_b16 v[222:223], v152 offset:0x1600
	ds_read_b64_tr_b16 v[224:225], v152 offset:0x1e00
	s_waitcnt lgkmcnt(6)
	v_mfma_f32_32x32x16_bf16 v[2:17], v[136:139], v[226:229], v[2:17]
	ds_read_b64_tr_b16 v[226:227], v152 offset:0x2600
	ds_read_b64_tr_b16 v[228:229], v152 offset:0x2e00
	s_waitcnt lgkmcnt(6)
	v_mfma_f32_32x32x16_bf16 v[2:17], v[214:217], v[230:233], v[2:17]
	ds_read_b64_tr_b16 v[230:231], v152 offset:0x3600
	ds_read_b64_tr_b16 v[232:233], v152 offset:0x3e00
	s_waitcnt lgkmcnt(6)
	v_mfma_f32_32x32x16_bf16 v[34:49], v[130:133], v[218:221], v[34:49]
	v_max_f32_e32 v130, v83, v83
	v_max_f32_e32 v131, v82, v82
	v_max_f32_e32 v130, v131, v130
	v_max3_f32 v130, v130, v84, v85
	v_max3_f32 v130, v130, v86, v87
	v_max3_f32 v130, v130, v88, v89
	v_max3_f32 v130, v130, v90, v91
	v_max3_f32 v130, v130, v92, v93
	v_max3_f32 v130, v130, v94, v95
	s_waitcnt lgkmcnt(4)
	v_mfma_f32_32x32x16_bf16 v[34:49], v[140:143], v[222:225], v[34:49]
	v_max3_f32 v130, v130, v96, v97
	v_max3_f32 v130, v130, v66, v67
	v_max3_f32 v130, v130, v68, v69
	v_max3_f32 v130, v130, v70, v71
	v_max3_f32 v130, v130, v72, v73
	v_max3_f32 v130, v130, v74, v75
	v_max3_f32 v130, v130, v76, v77
	v_max3_f32 v130, v130, v78, v79
	s_waitcnt lgkmcnt(2)
	v_mfma_f32_32x32x16_bf16 v[34:49], v[136:139], v[226:229], v[34:49]
	v_max3_f32 v130, v130, v80, v81
	v_mov_b32_e32 v131, v130
	s_nop 1
	v_permlane32_swap_b32_e32 v130, v131
	v_max_f32_e32 v131, v131, v131
	v_max_f32_e32 v130, v130, v130
	v_max_f32_e32 v130, v130, v131
	v_sub_f32_e32 v131, v130, v134
	s_mov_b32 s2, 0x42b504f3
	v_cmp_ge_f32_e32 vcc, s2, v131
	v_max_f32_e32 v131, v134, v134
	v_max_f32_e32 v130, v131, v130
	s_waitcnt lgkmcnt(0)
	v_mfma_f32_32x32x16_bf16 v[34:49], v[214:217], v[230:233], v[34:49]
	v_sub_f32_e32 v131, v134, v130
	v_mul_f32_e32 v131, 0x3e0293ee, v131
	v_exp_f32_e32 v131, v131
	s_cmp_eq_u64 vcc, exec
	s_cselect_b64 s[2:3], -1, 0
	s_waitcnt vmcnt(4)
	v_cndmask_b32_e64 v214, v131, 1.0, s[2:3]
	v_cmp_gt_f32_e32 vcc, 1.0, v214
	s_waitcnt vmcnt(4)
	ds_write_b128 v177, v[98:101] offset:32768
	ds_write_b128 v208, v[102:105] offset:32768
	s_mov_b64 s[6:7], exec
	s_mov_b64 exec, 1
	ds_add_u32 v162, v179
	s_mov_b64 exec, s[6:7]
	s_cbranch_vccz .LBB0_664
; #define SBAR() __builtin_amdgcn_sched_barrier(0)
; #define RESC(a) do { if (__any((a) < 1.f)) { if (hi == 0) al_l[r32] = (a); asm volatile("s_waitcnt lgkmcnt(0)" ::: "memory"); \
;     _Pragma("unroll") for (int d = 0; d < 4; ++d) _Pragma("unroll") for (int r = 0; r < 16; ++r) o[d][r] *= al_l[crow(r, hi)]; } } while (0)
; #define HOOK(P0, P1, j) do { if (NA) na_hook(P0, P1, krow0 + (j), q_row, q_col, win_r, win_c, rpb, inv_scale, hi); } while (0)
; template <int DK, bool NA, bool QL, int SD> ...
;     ...
;     RESC(alB); __syncthreads();
;     SBAR(); qkt<DK, QL>(pA0, pA1, K_lds, qr, ql, r32, hi); HOOK(pA0, pA1, j + 1);
;     finishSM(pB0, pB1, alB, l_reg, pa0, pa1, pa2, pa3); SBAR();
	s_and_saveexec_b64 s[4:5], s[0:1]
	ds_write_b32 v149, v214 offset:128
	s_or_b64 exec, exec, s[4:5]
	s_waitcnt lgkmcnt(0)
	v_add_u32_e32 v131, v148, v0
	ds_read_b128 v[136:139], v131 offset:128
	ds_read_b128 v[140:143], v131 offset:160
	ds_read_b128 v[216:219], v131 offset:192
	ds_read_b128 v[220:223], v131 offset:224
	s_waitcnt lgkmcnt(3)
	v_pk_mul_f32 v[50:51], v[136:137], v[50:51]
	v_pk_mul_f32 v[52:53], v[52:53], v[138:139]
	s_waitcnt lgkmcnt(2)
	v_pk_mul_f32 v[54:55], v[54:55], v[140:141]
	v_pk_mul_f32 v[56:57], v[56:57], v[142:143]
	s_waitcnt lgkmcnt(1)
	v_pk_mul_f32 v[58:59], v[58:59], v[216:217]
	v_pk_mul_f32 v[60:61], v[60:61], v[218:219]
	s_waitcnt lgkmcnt(0)
	v_pk_mul_f32 v[62:63], v[62:63], v[220:221]
	v_pk_mul_f32 v[30:31], v[30:31], v[220:221]
	v_pk_mul_f32 v[26:27], v[26:27], v[216:217]
	v_pk_mul_f32 v[22:23], v[22:23], v[140:141]
	v_pk_mul_f32 v[32:33], v[32:33], v[222:223]
	v_pk_mul_f32 v[28:29], v[28:29], v[218:219]
	v_pk_mul_f32 v[24:25], v[24:25], v[142:143]
	v_pk_mul_f32 v[20:21], v[20:21], v[138:139]
	v_pk_mul_f32 v[18:19], v[18:19], v[136:137]
	v_pk_mul_f32 v[64:65], v[64:65], v[222:223]
	v_pk_mul_f32 v[34:35], v[136:137], v[34:35]
	v_pk_mul_f32 v[36:37], v[36:37], v[138:139]
	v_pk_mul_f32 v[38:39], v[38:39], v[140:141]
	v_pk_mul_f32 v[40:41], v[40:41], v[142:143]
	v_pk_mul_f32 v[42:43], v[42:43], v[216:217]
	v_pk_mul_f32 v[44:45], v[44:45], v[218:219]
	v_pk_mul_f32 v[46:47], v[46:47], v[220:221]
	v_pk_mul_f32 v[14:15], v[14:15], v[220:221]
	v_pk_mul_f32 v[10:11], v[10:11], v[216:217]
	v_pk_mul_f32 v[6:7], v[6:7], v[140:141]
	v_pk_mul_f32 v[16:17], v[16:17], v[222:223]
	v_pk_mul_f32 v[12:13], v[12:13], v[218:219]
	v_pk_mul_f32 v[8:9], v[8:9], v[142:143]
	v_pk_mul_f32 v[4:5], v[4:5], v[138:139]
	v_pk_mul_f32 v[2:3], v[2:3], v[136:137]
	v_pk_mul_f32 v[48:49], v[48:49], v[222:223]
.LBB0_664:
	ds_read_b32 v178, v162
	v_cndmask_b32_e64 v215, v130, v134, s[2:3]
	v_mul_f32_e32 v216, 0xbe0293ee, v215
	v_fmamk_f32 v82, v82, 0x3e0293ee, v216
	v_fmamk_f32 v83, v83, 0x3e0293ee, v216
	v_fmamk_f32 v84, v84, 0x3e0293ee, v216
	v_fmamk_f32 v85, v85, 0x3e0293ee, v216
	v_fmamk_f32 v86, v86, 0x3e0293ee, v216
	v_fmamk_f32 v87, v87, 0x3e0293ee, v216
	v_fmamk_f32 v88, v88, 0x3e0293ee, v216
	v_fmamk_f32 v89, v89, 0x3e0293ee, v216
	v_fmamk_f32 v90, v90, 0x3e0293ee, v216
	v_fmamk_f32 v91, v91, 0x3e0293ee, v216
	v_fmamk_f32 v92, v92, 0x3e0293ee, v216
	v_fmamk_f32 v93, v93, 0x3e0293ee, v216
	v_fmamk_f32 v94, v94, 0x3e0293ee, v216
	v_fmamk_f32 v95, v95, 0x3e0293ee, v216
	v_fmamk_f32 v96, v96, 0x3e0293ee, v216
	v_fmamk_f32 v97, v97, 0x3e0293ee, v216
	v_exp_f32_e32 v130, v82
	v_exp_f32_e32 v145, v83
	v_exp_f32_e32 v131, v84
	v_exp_f32_e32 v144, v85
	v_exp_f32_e32 v132, v86
	v_exp_f32_e32 v143, v87
	v_exp_f32_e32 v133, v88
	v_exp_f32_e32 v142, v89
	v_exp_f32_e32 v134, v90
	v_exp_f32_e32 v141, v91
	v_exp_f32_e32 v135, v92
	v_exp_f32_e32 v140, v93
	v_exp_f32_e32 v136, v94
	v_exp_f32_e32 v139, v95
	v_exp_f32_e32 v137, v96
	v_exp_f32_e32 v138, v97
	v_fmamk_f32 v218, v71, 0x3e0293ee, v216
	v_fmamk_f32 v217, v78, 0x3e0293ee, v216
	s_add_i32 s8, s8, 2
	v_fmamk_f32 v225, v66, 0x3e0293ee, v216
	v_fmamk_f32 v226, v67, 0x3e0293ee, v216
	v_fmamk_f32 v227, v68, 0x3e0293ee, v216
	v_fmamk_f32 v228, v69, 0x3e0293ee, v216
	v_fmamk_f32 v229, v70, 0x3e0293ee, v216
	v_fmamk_f32 v219, v72, 0x3e0293ee, v216
	v_fmamk_f32 v220, v73, 0x3e0293ee, v216
	v_fmamk_f32 v221, v74, 0x3e0293ee, v216
	v_fmamk_f32 v222, v75, 0x3e0293ee, v216
	v_fmamk_f32 v223, v76, 0x3e0293ee, v216
	v_fmamk_f32 v224, v77, 0x3e0293ee, v216
	v_fmamk_f32 v230, v79, 0x3e0293ee, v216
	v_fmamk_f32 v231, v80, 0x3e0293ee, v216
	v_fmac_f32_e32 v216, 0x3e0293ee, v81
	v_mov_b32_e32 v155, 0
.Lsb_gq0_w:
	s_waitcnt lgkmcnt(0)
	v_cmp_ge_u32_e64 s[6:7], v178, v180
	s_cmp_lg_u64 s[6:7], 0
	s_cbranch_scc1 .Lsb_gq0_d
	v_add_u32_e32 v155, 1, v155
	v_readfirstlane_b32 s6, v155
	s_cmpk_lt_u32 s6, 0x4000
	s_cbranch_scc0 .Lsb_gq0_d
	ds_read_b32 v178, v162
	s_branch .Lsb_gq0_w
.Lsb_gq0_d:
	v_add_u32_e32 v180, 8, v180
	ds_write_b128 v209, v[106:109]
	ds_write_b128 v210, v[110:113]
	ds_read_b128 v[66:69], v153
	ds_read_b128 v[70:73], v159 offset:32768
	ds_read_b128 v[74:77], v159 offset:40960
	ds_read_b128 v[232:235], v153 offset:1024
	ds_read_b128 v[236:239], v207 offset:32768
	ds_read_b128 v[240:243], v207 offset:40960
	v_exp_f32_e32 v174, v219
	v_exp_f32_e32 v219, v221
	s_waitcnt lgkmcnt(4)
	v_mfma_f32_32x32x16_bf16 v[82:97], v[70:73], v[66:69], 0
	v_exp_f32_e32 v221, v223
	v_exp_f32_e32 v223, v217
	v_add_f32_e32 v217, 0, v130
	v_add_f32_e32 v217, v145, v217
	v_add_f32_e32 v217, v131, v217
	v_add_f32_e32 v217, v144, v217
	v_add_f32_e32 v217, v132, v217
	s_waitcnt lgkmcnt(3)
	v_mfma_f32_32x32x16_bf16 v[66:81], v[74:77], v[66:69], 0
	v_add_f32_e32 v217, v143, v217
	v_add_f32_e32 v217, v133, v217
	v_add_f32_e32 v217, v142, v217
	v_add_f32_e32 v217, v134, v217
	v_add_f32_e32 v217, v141, v217
	v_add_f32_e32 v217, v135, v217
	v_add_f32_e32 v217, v140, v217
	s_waitcnt lgkmcnt(1)
	v_mfma_f32_32x32x16_bf16 v[82:97], v[236:239], v[232:235], v[82:97]
	v_exp_f32_e32 v164, v225
	v_add_f32_e32 v217, v136, v217
	v_exp_f32_e32 v165, v226
	v_add_f32_e32 v217, v139, v217
	v_exp_f32_e32 v166, v227
	v_add_f32_e32 v217, v137, v217
	v_exp_f32_e32 v167, v228
	s_waitcnt lgkmcnt(0)
	v_mfma_f32_32x32x16_bf16 v[66:81], v[240:243], v[232:235], v[66:81]
	ds_read_b128 v[232:235], v153 offset:2048
	ds_read_b128 v[236:239], v161 offset:32768
	ds_read_b128 v[240:243], v161 offset:40960
	v_add_f32_e32 v217, v138, v217
	v_exp_f32_e32 v172, v229
	v_add_f32_e32 v217, v164, v217
	v_exp_f32_e32 v173, v218
	v_add_f32_e32 v217, v165, v217
	v_add_f32_e32 v217, v166, v217
	s_waitcnt lgkmcnt(1)
; #define SBAR() __builtin_amdgcn_sched_barrier(0)
; #define SLOAD(i, k0) do { sr_[i].vs0 = *reinterpret_cast<const bf16x8*>(&Vh[(long)((k0) + sr) * LDP + sc]); sr_[i].vs1 = *reinterpret_cast<const bf16x8*>(&Vh[(long)((k0) + 32 + sr) * LDP + sc]); \
;     sr_[i].ks0 = *reinterpret_cast<const bf16x8*>(&Kh[(long)((k0) + ksr) * LDP + ksc]); if (DK == 128) sr_[i].ks1 = *reinterpret_cast<const bf16x8*>(&Kh[(long)((k0) + 32 + ksr) * LDP + ksc]); } while (0)
; #define HOOK(P0, P1, j) do { if (NA) na_hook(P0, P1, krow0 + (j), q_row, q_col, win_r, win_c, rpb, inv_scale, hi); } while (0)
; template <int D0> __device__ __forceinline__ void pv_one(f32x16& od, int vb, bf16x8 pa0, bf16x8 pa1, bf16x8 pa2, bf16x8 pa3) {
;   const s16x4 l0 = tr_read<v_rd_off(D0, 0, 0)>(vb), h0 = tr_read<v_rd_off(D0, 0, 1)>(vb), l1 = tr_read<v_rd_off(D0, 1, 0)>(vb), h1 = tr_read<v_rd_off(D0, 1, 1)>(vb);
;   const s16x4 l2 = tr_read<v_rd_off(D0, 2, 0)>(vb), h2 = tr_read<v_rd_off(D0, 2, 1)>(vb), l3 = tr_read<v_rd_off(D0, 3, 0)>(vb), h3 = tr_read<v_rd_off(D0, 3, 1)>(vb);
;   asm volatile("s_waitcnt lgkmcnt(0)" ::: "memory"); SBAR();
;     ...
;   od = __builtin_amdgcn_mfma_f32_32x32x16_bf16(pa0, PK(l0, h0), od, 0, 0, 0);
;   od = __builtin_amdgcn_mfma_f32_32x32x16_bf16(pa1, PK(l1, h1), od, 0, 0, 0);
;   od = __builtin_amdgcn_mfma_f32_32x32x16_bf16(pa2, PK(l2, h2), od, 0, 0, 0);
;   od = __builtin_amdgcn_mfma_f32_32x32x16_bf16(pa3, PK(l3, h3), od, 0, 0, 0);
;     ...
; }
; template <int DK, bool NA, bool QL, int SD> ...
;     ...
;     SBAR(); qkt<DK, QL>(pA0, pA1, K_lds, qr, ql, r32, hi); HOOK(pA0, pA1, j + 1);
;     finishSM(pB0, pB1, alB, l_reg, pa0, pa1, pa2, pa3); SBAR();
;     if (SD == 1 || j + 3 < NT) SLOAD(SE, (j + 1 + SD) * KVBLK); SBAR();
;     pv_d0(o, vb0 + (int)SHM_V, pa0, pa1, pa2, pa3); partialSM(pA0, pA1, m_reg, mnA, alA, C, thrRaw);
	v_mfma_f32_32x32x16_bf16 v[82:97], v[236:239], v[232:235], v[82:97]
	v_exp_f32_e32 v175, v220
	v_add_f32_e32 v217, v167, v217
	v_add_f32_e32 v217, v172, v217
	v_exp_f32_e32 v220, v222
	v_add_f32_e32 v217, v173, v217
	v_add_f32_e32 v217, v174, v217
	v_exp_f32_e32 v222, v224
	s_waitcnt lgkmcnt(0)
	v_mfma_f32_32x32x16_bf16 v[66:81], v[240:243], v[232:235], v[66:81]
	ds_read_b128 v[232:235], v153 offset:3072
	ds_read_b128 v[236:239], v160 offset:32768
	ds_read_b128 v[240:243], v160 offset:40960
	v_add_f32_e32 v217, v175, v217
	v_add_f32_e32 v217, v219, v217
	v_exp_f32_e32 v224, v230
	v_add_f32_e32 v217, v220, v217
	v_exp_f32_e32 v225, v231
	v_add_f32_e32 v217, v221, v217
	s_waitcnt lgkmcnt(1)
	v_mfma_f32_32x32x16_bf16 v[82:97], v[236:239], v[232:235], v[82:97]
	v_exp_f32_e32 v216, v216
	v_add_f32_e32 v217, v222, v217
	v_add_f32_e32 v217, v223, v217
	v_add_f32_e32 v217, v224, v217
	v_add_f32_e32 v217, v225, v217
	v_add_f32_e32 v217, v216, v217
	v_mov_b32_e32 v218, v217
	s_waitcnt lgkmcnt(0)
	v_mfma_f32_32x32x16_bf16 v[66:81], v[240:243], v[232:235], v[66:81]
	ds_read_b128 v[232:235], v153 offset:4096
	ds_read_b128 v[236:239], v158 offset:32768
	ds_read_b128 v[240:243], v158 offset:40960
	v_permlane32_swap_b32_e32 v217, v218
	s_waitcnt lgkmcnt(1)
	v_mfma_f32_32x32x16_bf16 v[82:97], v[236:239], v[232:235], v[82:97]
	s_waitcnt lgkmcnt(0)
	v_mfma_f32_32x32x16_bf16 v[66:81], v[240:243], v[232:235], v[66:81]
	ds_read_b128 v[232:235], v153 offset:5120
	ds_read_b128 v[236:239], v156 offset:32768
	ds_read_b128 v[240:243], v156 offset:40960
	s_waitcnt lgkmcnt(1)
	v_mfma_f32_32x32x16_bf16 v[82:97], v[236:239], v[232:235], v[82:97]
	s_waitcnt lgkmcnt(0)
	v_mfma_f32_32x32x16_bf16 v[66:81], v[240:243], v[232:235], v[66:81]
	ds_read_b128 v[232:235], v153 offset:6144
	ds_read_b128 v[236:239], v157 offset:32768
	ds_read_b128 v[240:243], v157 offset:40960
	s_waitcnt lgkmcnt(1)
	v_mfma_f32_32x32x16_bf16 v[82:97], v[236:239], v[232:235], v[82:97]
	s_waitcnt lgkmcnt(0)
	v_mfma_f32_32x32x16_bf16 v[66:81], v[240:243], v[232:235], v[66:81]
	ds_read_b128 v[232:235], v153 offset:7168
	ds_read_b128 v[236:239], v176 offset:32768
	ds_read_b128 v[240:243], v176 offset:40960
	v_cvt_pk_bf16_f32 v130, v130, v145
	v_cvt_pk_bf16_f32 v131, v131, v144
	v_cvt_pk_bf16_f32 v132, v132, v143
	v_cvt_pk_bf16_f32 v133, v133, v142
	v_cvt_pk_bf16_f32 v134, v134, v141
	v_cvt_pk_bf16_f32 v135, v135, v140
	s_waitcnt lgkmcnt(1)
	v_mfma_f32_32x32x16_bf16 v[82:97], v[236:239], v[232:235], v[82:97]
	v_cvt_pk_bf16_f32 v136, v136, v139
	v_cvt_pk_bf16_f32 v137, v137, v138
	v_cvt_pk_bf16_f32 v138, v164, v165
	v_cvt_pk_bf16_f32 v139, v166, v167
	v_cvt_pk_bf16_f32 v140, v172, v173
	v_cvt_pk_bf16_f32 v141, v174, v175
	v_cvt_pk_bf16_f32 v142, v219, v220
	s_waitcnt lgkmcnt(0)
	v_mfma_f32_32x32x16_bf16 v[66:81], v[240:243], v[232:235], v[66:81]
	v_cvt_pk_bf16_f32 v143, v221, v222
	v_cvt_pk_bf16_f32 v144, v223, v224
	v_cvt_pk_bf16_f32 v145, v225, v216
	v_permlane32_swap_b32_e32 v130, v132
	v_permlane32_swap_b32_e32 v131, v133
	v_permlane32_swap_b32_e32 v134, v136
	v_permlane32_swap_b32_e32 v135, v137
	v_permlane32_swap_b32_e32 v138, v140
	v_permlane32_swap_b32_e32 v139, v141
	v_permlane32_swap_b32_e32 v142, v144
	v_permlane32_swap_b32_e32 v143, v145
	s_cmp_gt_u32 s8, 60
	s_cselect_b64 s[4:5], -1, 0
	s_and_b64 vcc, exec, s[4:5]
	s_cbranch_vccnz .Lod_gqa
	v_add_co_u32_e32 v98, vcc, 0xfffb0000, v146
	s_nop 1
	v_addc_co_u32_e32 v99, vcc, -1, v147, vcc
	global_load_dwordx4 v[106:109], v[98:99], off
	s_nop 0
	global_load_dwordx4 v[98:101], v[98:99], off offset:-512
	s_nop 0
	global_load_dwordx4 v[110:113], v[146:147], off
	global_load_dwordx4 v[102:105], v[146:147], off offset:-512
.LBB0_666:
	ds_read_b64_tr_b16 v[220:221], v151 offset:0
	ds_read_b64_tr_b16 v[222:223], v151 offset:0x800
	ds_read_b64_tr_b16 v[224:225], v151 offset:0x1000
	ds_read_b64_tr_b16 v[226:227], v151 offset:0x1800
	ds_read_b64_tr_b16 v[228:229], v151 offset:0x2000
	ds_read_b64_tr_b16 v[230:231], v151 offset:0x2800
	ds_read_b64_tr_b16 v[232:233], v151 offset:0x3000
	ds_read_b64_tr_b16 v[234:235], v151 offset:0x3800
	s_waitcnt lgkmcnt(6)
	s_nop 0
	v_mfma_f32_32x32x16_bf16 v[18:33], v[130:133], v[220:223], v[18:33]
	ds_read_b64_tr_b16 v[220:221], v151 offset:0x200
	ds_read_b64_tr_b16 v[222:223], v151 offset:0xa00
	s_waitcnt lgkmcnt(6)
	v_mfma_f32_32x32x16_bf16 v[18:33], v[134:137], v[224:227], v[18:33]
	ds_read_b64_tr_b16 v[224:225], v151 offset:0x1200
	ds_read_b64_tr_b16 v[226:227], v151 offset:0x1a00
	s_waitcnt lgkmcnt(6)
	v_mfma_f32_32x32x16_bf16 v[18:33], v[138:141], v[228:231], v[18:33]
	ds_read_b64_tr_b16 v[228:229], v151 offset:0x2200
	ds_read_b64_tr_b16 v[230:231], v151 offset:0x2a00
	s_waitcnt lgkmcnt(6)
	v_mfma_f32_32x32x16_bf16 v[18:33], v[142:145], v[232:235], v[18:33]
	ds_read_b64_tr_b16 v[232:233], v151 offset:0x3200
	ds_read_b64_tr_b16 v[234:235], v151 offset:0x3a00
	s_waitcnt lgkmcnt(6)
	v_mfma_f32_32x32x16_bf16 v[50:65], v[130:133], v[220:223], v[50:65]
	ds_read_b64_tr_b16 v[220:221], v151 offset:0x400
	ds_read_b64_tr_b16 v[222:223], v151 offset:0xc00
	s_waitcnt lgkmcnt(6)
	v_mfma_f32_32x32x16_bf16 v[50:65], v[134:137], v[224:227], v[50:65]
	ds_read_b64_tr_b16 v[224:225], v151 offset:0x1400
	ds_read_b64_tr_b16 v[226:227], v151 offset:0x1c00
	s_waitcnt lgkmcnt(6)
	v_mfma_f32_32x32x16_bf16 v[50:65], v[138:141], v[228:231], v[50:65]
	ds_read_b64_tr_b16 v[228:229], v151 offset:0x2400
	ds_read_b64_tr_b16 v[230:231], v151 offset:0x2c00
	s_waitcnt lgkmcnt(6)
	v_mfma_f32_32x32x16_bf16 v[50:65], v[142:145], v[232:235], v[50:65]
	ds_read_b64_tr_b16 v[232:233], v151 offset:0x3400
	ds_read_b64_tr_b16 v[234:235], v151 offset:0x3c00
	s_waitcnt lgkmcnt(6)
; #define SWAIT() do { if (SD == 1) asm volatile("s_waitcnt vmcnt(0)" ::: "memory"); else if (DK == 128) asm volatile("s_waitcnt vmcnt(4)" ::: "memory"); else asm volatile("s_waitcnt vmcnt(3)" ::: "memory"); } while (0)
; #define RESC(a) do { if (__any((a) < 1.f)) { if (hi == 0) al_l[r32] = (a); asm volatile("s_waitcnt lgkmcnt(0)" ::: "memory"); \
;     _Pragma("unroll") for (int d = 0; d < 4; ++d) _Pragma("unroll") for (int r = 0; r < 16; ++r) o[d][r] *= al_l[crow(r, hi)]; } } while (0)
; template <int DK, bool NA, bool QL, int SD> ...
;     ...
;     pv_d0(o, vb0 + (int)SHM_V, pa0, pa1, pa2, pa3); partialSM(pA0, pA1, m_reg, mnA, alA, C, thrRaw);
;     __syncthreads(); SWAIT(); SWRITE(1, SO);
;     RESC(alA); __syncthreads();
	v_mfma_f32_32x32x16_bf16 v[2:17], v[130:133], v[220:223], v[2:17]
	ds_read_b64_tr_b16 v[220:221], v151 offset:0x600
	ds_read_b64_tr_b16 v[222:223], v151 offset:0xe00
	s_waitcnt lgkmcnt(6)
	v_mfma_f32_32x32x16_bf16 v[2:17], v[134:137], v[224:227], v[2:17]
	ds_read_b64_tr_b16 v[224:225], v151 offset:0x1600
	ds_read_b64_tr_b16 v[226:227], v151 offset:0x1e00
	s_waitcnt lgkmcnt(6)
	v_mfma_f32_32x32x16_bf16 v[2:17], v[138:141], v[228:231], v[2:17]
	ds_read_b64_tr_b16 v[228:229], v151 offset:0x2600
	ds_read_b64_tr_b16 v[230:231], v151 offset:0x2e00
	s_waitcnt lgkmcnt(6)
	v_mfma_f32_32x32x16_bf16 v[2:17], v[142:145], v[232:235], v[2:17]
	ds_read_b64_tr_b16 v[232:233], v151 offset:0x3600
	ds_read_b64_tr_b16 v[234:235], v151 offset:0x3e00
	s_waitcnt lgkmcnt(6)
	v_mfma_f32_32x32x16_bf16 v[34:49], v[130:133], v[220:223], v[34:49]
	v_max_f32_e32 v130, v83, v83
	v_max_f32_e32 v131, v82, v82
	v_max_f32_e32 v130, v131, v130
	v_max3_f32 v130, v130, v84, v85
	v_max3_f32 v130, v130, v86, v87
	v_max3_f32 v130, v130, v88, v89
	v_max3_f32 v130, v130, v90, v91
	v_max3_f32 v130, v130, v92, v93
	v_max3_f32 v130, v130, v94, v95
	s_waitcnt lgkmcnt(4)
	v_mfma_f32_32x32x16_bf16 v[34:49], v[134:137], v[224:227], v[34:49]
	v_max3_f32 v130, v130, v96, v97
	v_max3_f32 v130, v130, v66, v67
	v_max3_f32 v130, v130, v68, v69
	v_max3_f32 v130, v130, v70, v71
	v_max3_f32 v130, v130, v72, v73
	v_max3_f32 v130, v130, v74, v75
	v_max3_f32 v130, v130, v76, v77
	v_max3_f32 v130, v130, v78, v79
	s_waitcnt lgkmcnt(2)
	v_mfma_f32_32x32x16_bf16 v[34:49], v[138:141], v[228:231], v[34:49]
	v_max3_f32 v130, v130, v80, v81
	v_mov_b32_e32 v131, v130
	s_nop 1
	v_permlane32_swap_b32_e32 v130, v131
	v_max_f32_e32 v131, v131, v131
	v_max_f32_e32 v130, v130, v130
	v_max_f32_e32 v130, v130, v131
	v_sub_f32_e32 v131, v130, v215
	s_mov_b32 s2, 0x42b504f3
	v_cmp_ge_f32_e32 vcc, s2, v131
	v_max_f32_e32 v131, v215, v215
	v_max_f32_e32 v131, v131, v130
	s_waitcnt lgkmcnt(0)
	v_mfma_f32_32x32x16_bf16 v[34:49], v[142:145], v[232:235], v[34:49]
	v_sub_f32_e32 v130, v215, v131
	v_mul_f32_e32 v130, 0x3e0293ee, v130
	v_exp_f32_e32 v130, v130
	s_cmp_eq_u64 vcc, exec
	s_cselect_b64 s[2:3], -1, 0
	s_waitcnt vmcnt(4)
	v_cndmask_b32_e64 v130, v130, 1.0, s[2:3]
	v_cmp_gt_f32_e32 vcc, 1.0, v130
	v_mov_b64_e32 v[244:245], v[114:115]
	v_mov_b64_e32 v[246:247], v[116:117]
	v_mov_b64_e32 v[194:195], v[126:127]
	v_mov_b64_e32 v[196:197], v[128:129]
	ds_write_b128 v177, v[118:121] offset:49152
	ds_write_b128 v208, v[122:125] offset:49152
	s_mov_b64 s[6:7], exec
	s_mov_b64 exec, 1
	ds_add_u32 v162, v179
	s_mov_b64 exec, s[6:7]
	s_cbranch_vccz .LBB0_670
	s_and_saveexec_b64 s[6:7], s[0:1]
	ds_write_b32 v149, v130 offset:128
	s_or_b64 exec, exec, s[6:7]
	s_waitcnt lgkmcnt(0)
	v_add_u32_e32 v126, v148, v0
	ds_read_b128 v[114:117], v126 offset:128
	ds_read_b128 v[118:121], v126 offset:160
	ds_read_b128 v[122:125], v126 offset:192
	ds_read_b128 v[126:129], v126 offset:224
	s_waitcnt lgkmcnt(3)
	v_pk_mul_f32 v[50:51], v[114:115], v[50:51]
	v_pk_mul_f32 v[52:53], v[52:53], v[116:117]
	s_waitcnt lgkmcnt(2)
	v_pk_mul_f32 v[54:55], v[54:55], v[118:119]
	v_pk_mul_f32 v[56:57], v[56:57], v[120:121]
	s_waitcnt lgkmcnt(1)
	v_pk_mul_f32 v[58:59], v[58:59], v[122:123]
	v_pk_mul_f32 v[60:61], v[60:61], v[124:125]
	s_waitcnt lgkmcnt(0)
	v_pk_mul_f32 v[62:63], v[62:63], v[126:127]
	v_pk_mul_f32 v[30:31], v[30:31], v[126:127]
	v_pk_mul_f32 v[26:27], v[26:27], v[122:123]
	v_pk_mul_f32 v[22:23], v[22:23], v[118:119]
	v_pk_mul_f32 v[32:33], v[32:33], v[128:129]
	v_pk_mul_f32 v[28:29], v[28:29], v[124:125]
	v_pk_mul_f32 v[24:25], v[24:25], v[120:121]
	v_pk_mul_f32 v[20:21], v[20:21], v[116:117]
	v_pk_mul_f32 v[18:19], v[18:19], v[114:115]
	v_pk_mul_f32 v[64:65], v[64:65], v[128:129]
	v_pk_mul_f32 v[34:35], v[114:115], v[34:35]
	v_pk_mul_f32 v[36:37], v[36:37], v[116:117]
	v_pk_mul_f32 v[38:39], v[38:39], v[118:119]
	v_pk_mul_f32 v[40:41], v[40:41], v[120:121]
	v_pk_mul_f32 v[42:43], v[42:43], v[122:123]
	v_pk_mul_f32 v[44:45], v[44:45], v[124:125]
	v_pk_mul_f32 v[46:47], v[46:47], v[126:127]
	v_pk_mul_f32 v[14:15], v[14:15], v[126:127]
	v_pk_mul_f32 v[10:11], v[10:11], v[122:123]
	v_pk_mul_f32 v[6:7], v[6:7], v[118:119]
	v_pk_mul_f32 v[16:17], v[16:17], v[128:129]
	v_pk_mul_f32 v[12:13], v[12:13], v[124:125]
	v_pk_mul_f32 v[8:9], v[8:9], v[120:121]
	v_pk_mul_f32 v[4:5], v[4:5], v[116:117]
	v_pk_mul_f32 v[2:3], v[2:3], v[114:115]
	v_pk_mul_f32 v[48:49], v[48:49], v[128:129]
.LBB0_670:
	ds_read_b32 v178, v162
	v_cndmask_b32_e64 v134, v131, v215, s[2:3]
	v_mul_f32_e32 v120, 0xbe0293ee, v134
	v_mov_b32_e32 v121, v120
	v_fmamk_f32 v82, v82, 0x3e0293ee, v120
	v_fmamk_f32 v83, v83, 0x3e0293ee, v120
	v_fmamk_f32 v84, v84, 0x3e0293ee, v120
	v_fmamk_f32 v85, v85, 0x3e0293ee, v120
	v_fmamk_f32 v86, v86, 0x3e0293ee, v120
	v_fmamk_f32 v87, v87, 0x3e0293ee, v120
	v_fmamk_f32 v88, v88, 0x3e0293ee, v120
	v_fmamk_f32 v89, v89, 0x3e0293ee, v120
	v_fmamk_f32 v90, v90, 0x3e0293ee, v120
	v_fmamk_f32 v91, v91, 0x3e0293ee, v120
	v_fmamk_f32 v92, v92, 0x3e0293ee, v120
	v_fmamk_f32 v93, v93, 0x3e0293ee, v120
	v_fmamk_f32 v94, v94, 0x3e0293ee, v120
	v_fmamk_f32 v95, v95, 0x3e0293ee, v120
	v_fmamk_f32 v96, v96, 0x3e0293ee, v120
	v_fmac_f32_e32 v121, 0x3e0293ee, v97
	s_mov_b32 s2, 0x3e0293ee
	v_exp_f32_e32 v145, v82
	v_exp_f32_e32 v216, v83
	v_exp_f32_e32 v131, v84
	v_exp_f32_e32 v215, v85
	v_exp_f32_e32 v132, v86
	v_exp_f32_e32 v144, v87
	v_exp_f32_e32 v133, v88
	v_exp_f32_e32 v143, v89
	v_exp_f32_e32 v140, v90
	v_exp_f32_e32 v142, v91
	v_exp_f32_e32 v139, v92
	v_exp_f32_e32 v141, v93
	v_exp_f32_e32 v136, v94
	v_exp_f32_e32 v138, v95
	v_exp_f32_e32 v135, v96
	v_exp_f32_e32 v137, v121
	v_pk_fma_f32 v[126:127], v[66:67], s[2:3], v[120:121] op_sel_hi:[1,0,0]
	v_add_f32_e32 v66, v212, v213
	v_pk_fma_f32 v[124:125], v[68:69], s[2:3], v[120:121] op_sel_hi:[1,0,0]
	v_pk_fma_f32 v[118:119], v[70:71], s[2:3], v[120:121] op_sel_hi:[1,0,0]
	v_pk_fma_f32 v[116:117], v[72:73], s[2:3], v[120:121] op_sel_hi:[1,0,0]
	v_pk_fma_f32 v[114:115], v[74:75], s[2:3], v[120:121] op_sel_hi:[1,0,0]
	v_pk_fma_f32 v[128:129], v[76:77], s[2:3], v[120:121] op_sel_hi:[1,0,0]
	v_pk_fma_f32 v[122:123], v[78:79], s[2:3], v[120:121] op_sel_hi:[1,0,0]
	v_pk_fma_f32 v[120:121], v[80:81], s[2:3], v[120:121] op_sel_hi:[1,0,0]
	v_fmac_f32_e32 v66, v211, v150
	v_add_f32_e32 v150, v217, v218
	s_mov_b64 s[2:3], 0x140000
	v_fmac_f32_e32 v150, v66, v214
	v_lshl_add_u64 v[146:147], v[146:147], 0, s[2:3]
	s_and_b64 vcc, exec, s[4:5]
	v_mov_b32_e32 v155, 0

; #define SWAIT() do { if (SD == 1) asm volatile("s_waitcnt vmcnt(0)" ::: "memory"); else if (DK == 128) asm volatile("s_waitcnt vmcnt(4)" ::: "memory"); else asm volatile("s_waitcnt vmcnt(3)" ::: "memory"); } while (0)
; #define RESC(a) do { if (__any((a) < 1.f)) { if (hi == 0) al_l[r32] = (a); asm volatile("s_waitcnt lgkmcnt(0)" ::: "memory"); \
;     _Pragma("unroll") for (int d = 0; d < 4; ++d) _Pragma("unroll") for (int r = 0; r < 16; ++r) o[d][r] *= al_l[crow(r, hi)]; } } while (0)
; template <int DK, bool NA, bool QL, int SD> ...
;     ...
;     __syncthreads(); SWAIT(); SWRITE(1, SO);
;     RESC(alA); __syncthreads();
.Lsb_gq1_d:
	v_add_u32_e32 v180, 8, v180
	s_cbranch_vccnz .LBB0_672
	v_mov_b32_e32 v211, v130
	ds_write_b128 v209, v[244:247] offset:16384
	ds_write_b128 v210, v[194:197] offset:16384
	s_branch .LBB0_660

; __device__ __forceinline__ int v_st(int k, int c) { const int kk = (k & ~0xC) | ((k & 4) << 1) | ((k & 8) >> 1); return ((kk >> 3) * 4 + (c >> 5)) * 512 + ((kk & 7) * 32 + (c & 31)) * 2; }
; __device__ __forceinline__ int v_rd_base(int lane) { return ((lane & 3) << 3) | (((lane >> 2) & 3) << 6) | (((lane >> 4) & 1) << 5) | (((lane >> 5) & 1) << 8); }
; #define SLOAD(i, k0) do { sr_[i].vs0 = *reinterpret_cast<const bf16x8*>(&Vh[(long)((k0) + sr) * LDP + sc]); sr_[i].vs1 = *reinterpret_cast<const bf16x8*>(&Vh[(long)((k0) + 32 + sr) * LDP + sc]); \
;     sr_[i].ks0 = *reinterpret_cast<const bf16x8*>(&Kh[(long)((k0) + ksr) * LDP + ksc]); if (DK == 128) sr_[i].ks1 = *reinterpret_cast<const bf16x8*>(&Kh[(long)((k0) + 32 + ksr) * LDP + ksc]); } while (0)
; #define HOOK(P0, P1, j) do { if (NA) na_hook(P0, P1, krow0 + (j), q_row, q_col, win_r, win_c, rpb, inv_scale, hi); } while (0)
; template <int DK, bool NA, bool QL, int SD> ...
;     ...
;   const bf16* Qw = Qb + (long)(wid * 32 + r32) * LDP + hi * 8;
; #pragma unroll
;   for (int d0 = 0; d0 < DK / 16; ++d0) { const bf16x8 qv = *reinterpret_cast<const bf16x8*>(Qw + d0 * 16); if (QL) *reinterpret_cast<bf16x8*>(ql + d0 * 1024) = qv; else qr[d0] = qv; }
;   const int sr = tid >> 4, sc = (tid & 15) * 8, vst0 = v_st(sr, sc), vst1 = v_st(32 + sr, sc);
;   const int ksr = DK == 128 ? sr : (tid >> 3), ksc = DK == 128 ? sc : (tid & 7) * 8;
;   const int vb0 = (int)(uintptr_t)V_lds + v_rd_base(lane);
;   struct { bf16x8 vs0, vs1, ks0, ks1; } sr_[SD];
;     ...
;   f32x16 pA0, pA1, pB0, pB1; float mnA, mnB, alA, alB; bf16x8 pa0, pa1, pa2, pa3;
;   constexpr int SE = 0, SO = SD - 1;
;   SLOAD(SE, 0); asm volatile("s_waitcnt vmcnt(0)" ::: "memory"); SWRITE(0, SE); __syncthreads();
;   qkt<DK, QL>(pA0, pA1, K_lds, qr, ql, r32, hi); HOOK(pA0, pA1, 0); partialSM(pA0, pA1, m_reg, mnA, alA, C, thrRaw);
.LBB0_680:
	s_andn2_b64 vcc, exec, s[0:1]
	s_cbranch_vccnz .LBB0_369
	v_mov_b32_e32 v73, v188
	v_readlane_b32 s0, v253, 17
	v_readlane_b32 s1, v253, 18
	v_ashrrev_i32_e32 v74, 4, v73
	v_lshlrev_b32_e32 v16, 3, v73
	v_add_u32_e32 v18, 32, v74
	v_ashrrev_i32_e32 v75, 3, v73
	v_mov_b64_e32 v[50:51], s[0:1]
	s_movk_i32 s3, 0x2800
	v_and_b32_e32 v0, 0x78, v16
	v_mad_i64_i32 v[2:3], s[0:1], v74, s3, v[50:51]
	v_mad_i64_i32 v[4:5], s[0:1], v18, s3, v[50:51]
	v_mad_i64_i32 v[10:11], s[0:1], v75, s3, v[50:51]
	v_lshlrev_b32_e32 v52, 1, v0
	v_mov_b32_e32 v53, v1
	v_ashrrev_i32_e32 v0, 1, v73
	s_movk_i32 s0, 0xffe0
	v_lshlrev_b32_e32 v17, 4, v73
	v_lshl_add_u64 v[2:3], v[2:3], 0, v[52:53]
	v_lshl_add_u64 v[6:7], v[4:5], 0, v[52:53]
	v_bfi_b32 v0, s0, v0, v73
	v_readlane_b32 s0, v253, 9
	global_load_dwordx4 v[2:5], v[2:3], off offset:2048
	s_nop 0
	global_load_dwordx4 v[6:9], v[6:7], off offset:2048
	v_and_b32_e32 v54, 0x70, v17
	v_mov_b32_e32 v55, v1
	v_readlane_b32 s1, v253, 10
	v_lshl_add_u64 v[10:11], v[10:11], 0, v[54:55]
	global_load_dwordx4 v[10:13], v[10:11], off offset:1024
	v_mov_b64_e32 v[14:15], s[0:1]
	v_mad_i64_i32 v[14:15], s[0:1], v0, s3, v[14:15]
	v_lshrrev_b32_e32 v0, 1, v73
	v_and_b32_e32 v0, 16, v0
	v_lshl_add_u64 v[14:15], v[14:15], 0, v[0:1]
	global_load_dwordx4 v[110:113], v[14:15], off
	global_load_dwordx4 v[106:109], v[14:15], off offset:32
	global_load_dwordx4 v[98:101], v[14:15], off offset:64
	global_load_dwordx4 v[102:105], v[14:15], off offset:96
	v_add_u32_e32 v84, 64, v74
	v_add_u32_e32 v88, 0x60, v74
	v_add_u32_e32 v92, 64, v75
	v_mad_i64_i32 v[84:85], s[0:1], v84, s3, v[50:51]
	v_mad_i64_i32 v[88:89], s[0:1], v88, s3, v[50:51]
	v_mad_i64_i32 v[92:93], s[0:1], v92, s3, v[50:51]
	v_lshl_add_u64 v[84:85], v[84:85], 0, v[52:53]
	v_lshl_add_u64 v[88:89], v[88:89], 0, v[52:53]
	v_lshl_add_u64 v[92:93], v[92:93], 0, v[54:55]
	global_load_dwordx4 v[84:87], v[84:85], off offset:2048
	global_load_dwordx4 v[88:91], v[88:89], off offset:2048
	global_load_dwordx4 v[92:95], v[92:93], off offset:1024
	v_and_b32_e32 v20, 0xfffff0, v74
	v_lshlrev_b32_e32 v21, 1, v74
	v_lshrrev_b32_e32 v22, 1, v74
	v_and_b32_e32 v24, 3, v74
	v_and_or_b32 v20, v21, 8, v20
	v_and_or_b32 v21, v22, 4, v24
	v_and_b32_e32 v22, 0xfffff0, v18
	v_lshlrev_b32_e32 v18, 1, v18
	v_bfe_u32 v23, v16, 5, 2
	v_lshrrev_b32_e32 v14, 1, v20
	v_and_or_b32 v18, v18, 8, v22
	v_and_b32_e32 v76, 31, v73
	v_or_b32_e32 v14, v14, v23
	v_lshrrev_b32_e32 v18, 1, v18
	v_and_b32_e32 v25, 48, v17
	v_lshlrev_b32_e32 v60, 7, v76
	v_and_b32_e32 v16, 0x70, v16
	v_lshlrev_b32_e32 v15, 6, v21
	v_lshlrev_b32_e32 v14, 9, v14
	v_or_b32_e32 v18, v18, v23
	v_and_b32_e32 v19, 0x70, v73
	v_lshlrev_b32_e32 v26, 7, v75
	v_bitop3_b32 v24, v0, v60, v16 bitop3:0xde
	v_or3_b32 v14, v14, v15, v25
	v_lshlrev_b32_e32 v18, 9, v18
	v_bitop3_b32 v19, v54, v26, v19 bitop3:0xde
	v_add_u32_e32 v212, 0, v24
	v_or3_b32 v15, v18, v15, v25
	v_add_u32_e32 v214, 0, v14
	v_add_u32_e32 v213, 0, v19
	s_waitcnt vmcnt(0)
	v_add_u32_e32 v215, 0, v15
	s_add_i32 s8, 0, 0x10000
	v_and_b32_e32 v77, 63, v73
	v_add_u32_e32 v68, 64, v75
	v_mad_i64_i32 v[58:59], s[0:1], v74, s3, 0
	v_mad_i64_i32 v[56:57], s[0:1], v75, s3, 0
	v_mad_i64_i32 v[68:69], s[0:1], v68, s3, v[50:51]
	s_cmp_lg_u32 0, -1
	s_cselect_b32 s2, 0, 0
	v_lshl_add_u64 v[68:69], v[68:69], 0, v[54:55]
	s_waitcnt vmcnt(6)
	ds_write_b128 v214, v[2:5]
	s_waitcnt vmcnt(5)
	ds_write_b128 v215, v[6:9]
	s_waitcnt vmcnt(4)
	ds_write_b128 v213, v[10:13] offset:32768
	s_waitcnt lgkmcnt(0)
	s_barrier
	ds_read_b128 v[2:5], v212 offset:32768
	ds_read_b128 v[6:9], v212 offset:36864
	s_waitcnt vmcnt(3) lgkmcnt(1)
	v_mfma_f32_32x32x16_bf16 v[18:33], v[2:5], v[110:113], 0
	v_or_b32_e32 v2, 32, v0
	v_bitop3_b32 v2, v2, v60, v16 bitop3:0xde
	v_add_u32_e32 v216, 0, v2
	ds_read_b128 v[2:5], v216 offset:32768
	v_lshlrev_b32_e32 v10, 1, v73
	v_lshlrev_b32_e32 v11, 3, v77
	v_and_b32_e32 v12, 0xc0, v17
	s_waitcnt lgkmcnt(1)
	v_mfma_f32_32x32x16_bf16 v[34:49], v[6:9], v[110:113], 0
	v_and_b32_e32 v6, 0x3fffffc0, v73
	v_lshl_add_u32 v207, v6, 2, s8
	ds_read_b128 v[6:9], v216 offset:36864
	v_and_b32_e32 v10, 32, v10
	v_readlane_b32 s16, v254, 62
	v_readlane_b32 s17, v254, 63
	v_readlane_b32 s18, v255, 0
	s_waitcnt vmcnt(2) lgkmcnt(1)
	v_mfma_f32_32x32x16_bf16 v[18:33], v[2:5], v[106:109], v[18:33]
	v_or_b32_e32 v2, 64, v0
	v_bitop3_b32 v2, v2, v60, v16 bitop3:0xde
	v_add_u32_e32 v217, 0, v2
	ds_read_b128 v[2:5], v217 offset:32768
	v_readlane_b32 s19, v255, 1
	v_readlane_b32 s20, v255, 2
	v_readlane_b32 s21, v255, 3
	s_waitcnt lgkmcnt(1)
	v_mfma_f32_32x32x16_bf16 v[34:49], v[6:9], v[106:109], v[34:49]
	v_and_or_b32 v6, v11, 24, v12
	v_and_b32_e32 v7, 0x100, v11
	v_or3_b32 v78, v6, v10, v7
	ds_read_b128 v[6:9], v217 offset:36864
	v_readlane_b32 s22, v255, 4
	v_readlane_b32 s23, v255, 5
	v_readlane_b32 s24, v255, 6
	s_waitcnt vmcnt(1) lgkmcnt(1)
	v_mfma_f32_32x32x16_bf16 v[18:33], v[2:5], v[98:101], v[18:33]
	v_or_b32_e32 v2, 0x60, v0
	v_bitop3_b32 v2, v2, v60, v16 bitop3:0xde
	v_add_u32_e32 v218, 0, v2
	ds_read_b128 v[2:5], v218 offset:32768
	ds_read_b128 v[60:63], v218 offset:36864
	v_readlane_b32 s25, v255, 7
	v_readlane_b32 s26, v255, 8
	s_waitcnt lgkmcnt(2)
	v_mfma_f32_32x32x16_bf16 v[34:49], v[6:9], v[98:101], v[34:49]
	v_readlane_b32 s27, v255, 9
	v_readlane_b32 s28, v255, 10
	v_readlane_b32 s29, v255, 11
	v_readlane_b32 s30, v255, 12
	v_readlane_b32 s31, v255, 13
	s_mov_b32 s16, s17
	v_add_u32_e32 v211, s2, v78
	s_waitcnt vmcnt(0) lgkmcnt(1)
	v_mfma_f32_32x32x16_bf16 v[18:33], v[2:5], v[102:105], v[18:33]
	s_mov_b32 s18, s17
	s_mov_b32 s19, s17
	s_mov_b32 s20, s17
	s_mov_b32 s21, s17
	s_mov_b32 s22, s17
	s_mov_b32 s23, s17
	s_mov_b32 s24, s17
	s_waitcnt lgkmcnt(0)
; #define SLOAD(i, k0) do { sr_[i].vs0 = *reinterpret_cast<const bf16x8*>(&Vh[(long)((k0) + sr) * LDP + sc]); sr_[i].vs1 = *reinterpret_cast<const bf16x8*>(&Vh[(long)((k0) + 32 + sr) * LDP + sc]); \
;     sr_[i].ks0 = *reinterpret_cast<const bf16x8*>(&Kh[(long)((k0) + ksr) * LDP + ksc]); if (DK == 128) sr_[i].ks1 = *reinterpret_cast<const bf16x8*>(&Kh[(long)((k0) + 32 + ksr) * LDP + ksc]); } while (0)
; #define SWAIT() do { if (SD == 1) asm volatile("s_waitcnt vmcnt(0)" ::: "memory"); else if (DK == 128) asm volatile("s_waitcnt vmcnt(4)" ::: "memory"); else asm volatile("s_waitcnt vmcnt(3)" ::: "memory"); } while (0)
; __device__ __forceinline__ void partialSM(f32x16& p0, f32x16& p1, float& m_reg, float& mn, float& alpha, float C, float thrRaw) {
;   float pmax = p0[0];
; #pragma unroll
;   for (int r = 1; r < 16; ++r) pmax = fmaxf(pmax, p0[r]);
; #pragma unroll
;   for (int r = 0; r < 16; ++r) pmax = fmaxf(pmax, p1[r]);
;   { auto rr = __builtin_amdgcn_permlane32_swap(__float_as_uint(pmax), __float_as_uint(pmax), false, false);
;     pmax = fmaxf(__uint_as_float(rr[0]), __uint_as_float(rr[1])); }
;   if (__builtin_expect(__all(pmax - m_reg <= thrRaw), 1)) { mn = m_reg; alpha = 1.f; }
;   else { mn = fmaxf(m_reg, pmax); alpha = __builtin_amdgcn_exp2f((m_reg - mn) * C); m_reg = mn; }
;   float mnC = -mn * C;
; #pragma unroll
;   for (int r = 0; r < 16; ++r) p0[r] = fmaf(p0[r], C, mnC);
; #pragma unroll
;   for (int r = 0; r < 16; ++r) p1[r] = fmaf(p1[r], C, mnC);
; #pragma unroll
;   for (int r = 0; r < 16; ++r) p0[r] = __builtin_amdgcn_exp2f(p0[r]);
; }
; template <int DK, bool NA, bool QL, int SD> ...
;     ...
;   SLOAD(SO, KVBLK); if (SD == 2) { if (2 < NT) SLOAD(SE, 2 * KVBLK); }
;   SWAIT(); SWRITE(1, SO); __syncthreads();
	v_mfma_f32_32x32x16_bf16 v[34:49], v[60:63], v[102:105], v[34:49]
	s_nop 2
	v_max_f32_e32 v60, v19, v19
	v_max_f32_e32 v61, v18, v18
	v_max_f32_e32 v60, v61, v60
	v_max3_f32 v60, v60, v20, v21
	v_max3_f32 v60, v60, v22, v23
	v_max3_f32 v60, v60, v24, v25
	v_max3_f32 v60, v60, v26, v27
	v_max3_f32 v60, v60, v28, v29
	v_max3_f32 v60, v60, v30, v31
	v_max3_f32 v60, v60, v32, v33
	v_max3_f32 v60, v60, v34, v35
	v_max3_f32 v60, v60, v36, v37
	v_max3_f32 v60, v60, v38, v39
	v_max3_f32 v60, v60, v40, v41
	v_max3_f32 v72, v60, v42, v43
	v_max3_f32 v72, v72, v44, v45
	v_max3_f32 v72, v72, v46, v47
	v_max3_f32 v72, v72, v48, v49
	v_mov_b32_e32 v79, v72
	s_nop 1
	v_permlane32_swap_b32_e32 v72, v79
	v_add_u32_e32 v60, 64, v74
	v_add_u32_e32 v62, 0x60, v74
	v_max_f32_e32 v79, v79, v79
	v_max_f32_e32 v72, v72, v72
	v_mad_i64_i32 v[60:61], s[0:1], v60, s3, v[50:51]
	v_mad_i64_i32 v[62:63], s[0:1], v62, s3, v[50:51]
	v_max_f32_e32 v72, v72, v79
	v_add_f32_e32 v79, 0x7149f2ca, v72
	s_mov_b32 s0, 0x42800000
	v_max_f32_e32 v72, 0xf149f2ca, v72
	v_cmp_ge_f32_e32 vcc, s0, v79
	v_sub_f32_e32 v79, 0xf149f2ca, v72
	v_mul_f32_e32 v79, 0x3e38aa3b, v79
	v_exp_f32_e32 v79, v79
	s_cmp_eq_u64 vcc, exec
	s_cselect_b64 vcc, -1, 0
	v_cndmask_b32_e32 v142, v72, v199, vcc
	v_mul_f32_e32 v72, 0xbe38aa3b, v142
	v_cndmask_b32_e64 v219, v79, 1.0, vcc
	v_fmamk_f32 v79, v18, 0x3e38aa3b, v72
	v_add_u32_e32 v18, 0x80, v75
	v_fmamk_f32 v80, v19, 0x3e38aa3b, v72
	v_mad_i64_i32 v[18:19], s[0:1], v18, s3, v[50:51]
	v_lshl_add_u64 v[60:61], v[60:61], 0, v[52:53]
	v_lshl_add_u64 v[64:65], v[62:63], 0, v[52:53]
	v_lshl_add_u64 v[18:19], v[18:19], 0, v[54:55]
	s_nop 0
	v_fmamk_f32 v81, v20, 0x3e38aa3b, v72
	v_add_u32_e32 v20, 0x80, v74
	global_load_dwordx4 v[122:125], v[18:19], off offset:1024
	v_add_u32_e32 v18, 0xa0, v74
	v_mad_i64_i32 v[18:19], s[0:1], v18, s3, v[50:51]
	v_fmamk_f32 v82, v21, 0x3e38aa3b, v72
	v_lshl_add_u64 v[18:19], v[18:19], 0, v[52:53]
	v_mad_i64_i32 v[20:21], s[0:1], v20, s3, v[50:51]
	v_lshl_add_u64 v[20:21], v[20:21], 0, v[52:53]
	global_load_dwordx4 v[118:121], v[18:19], off offset:2048
	global_load_dwordx4 v[114:117], v[20:21], off offset:2048
	v_mov_b32_e32 v20, v72
	v_fmamk_f32 v22, v22, 0x3e38aa3b, v72
	v_fmamk_f32 v23, v23, 0x3e38aa3b, v72
	v_fmamk_f32 v24, v24, 0x3e38aa3b, v72
	v_fmamk_f32 v25, v25, 0x3e38aa3b, v72
	v_fmamk_f32 v26, v26, 0x3e38aa3b, v72
	v_fmamk_f32 v27, v27, 0x3e38aa3b, v72
	v_fmamk_f32 v28, v28, 0x3e38aa3b, v72
	v_fmamk_f32 v29, v29, 0x3e38aa3b, v72
	v_fmamk_f32 v30, v30, 0x3e38aa3b, v72
	v_fmamk_f32 v18, v31, 0x3e38aa3b, v72
	v_fmamk_f32 v19, v32, 0x3e38aa3b, v72
	v_fmac_f32_e32 v20, 0x3e38aa3b, v33
	s_mov_b32 s25, s17
	s_mov_b32 s26, s17
	s_mov_b32 s27, s17
	s_mov_b32 s28, s17
	s_mov_b32 s29, s17
	s_mov_b32 s30, s17
	s_mov_b32 s31, s17
	v_mov_b64_e32 v[2:3], s[16:17]
	v_exp_f32_e32 v177, v79
	v_exp_f32_e32 v226, v80
	v_exp_f32_e32 v161, v81
	v_exp_f32_e32 v223, v82
	v_exp_f32_e32 v153, v22
	v_exp_f32_e32 v176, v23
	v_exp_f32_e32 v152, v24
	v_exp_f32_e32 v160, v25
	v_exp_f32_e32 v149, v26
	v_exp_f32_e32 v151, v27
	v_exp_f32_e32 v147, v28
	v_exp_f32_e32 v150, v29
	v_exp_f32_e32 v145, v30
	v_exp_f32_e32 v148, v18
	v_exp_f32_e32 v144, v19
	v_exp_f32_e32 v146, v20
	s_addk_i32 s2, 0x4000
	v_and_b32_e32 v18, 15, v73
	v_mov_b64_e32 v[16:17], s[30:31]
	s_waitcnt vmcnt(3)
	v_add_u32_e32 v210, s2, v78
	v_lshl_or_b32 v58, v18, 4, v58
	v_readlane_b32 s2, v254, 34
	v_and_b32_e32 v18, 7, v73
	v_mov_b64_e32 v[4:5], s[18:19]
	v_mov_b64_e32 v[6:7], s[20:21]
	v_mov_b64_e32 v[8:9], s[22:23]
	v_mov_b64_e32 v[10:11], s[24:25]
	v_mov_b64_e32 v[12:13], s[26:27]
	v_mov_b64_e32 v[14:15], s[28:29]
	s_mov_b32 s0, 0x3e38aa3b
	v_readlane_b32 s3, v254, 35
	v_lshl_or_b32 v56, v18, 4, v56
	v_mov_b32_e32 v209, 0
	v_mov_b64_e32 v[32:33], v[16:17]
	s_mov_b32 s9, 1
	s_mov_b32 s13, s17
	v_pk_fma_f32 v[132:133], v[48:49], s[0:1], v[72:73] op_sel_hi:[1,0,0]
	v_pk_fma_f32 v[134:135], v[46:47], s[0:1], v[72:73] op_sel_hi:[1,0,0]
	v_pk_fma_f32 v[140:141], v[44:45], s[0:1], v[72:73] op_sel_hi:[1,0,0]
	v_pk_fma_f32 v[126:127], v[42:43], s[0:1], v[72:73] op_sel_hi:[1,0,0]
	v_pk_fma_f32 v[128:129], v[40:41], s[0:1], v[72:73] op_sel_hi:[1,0,0]
	v_pk_fma_f32 v[130:131], v[38:39], s[0:1], v[72:73] op_sel_hi:[1,0,0]
	v_pk_fma_f32 v[136:137], v[36:37], s[0:1], v[72:73] op_sel_hi:[1,0,0]
	v_pk_fma_f32 v[138:139], v[34:35], s[0:1], v[72:73] op_sel_hi:[1,0,0]
	s_waitcnt vmcnt(5)
	ds_write_b128 v214, v[84:87] offset:16384
	s_waitcnt vmcnt(4)
	ds_write_b128 v215, v[88:91] offset:16384
	s_waitcnt vmcnt(3)
	ds_write_b128 v213, v[92:95] offset:49152
	v_cmp_gt_u32_e64 s[0:1], 32, v77
	v_lshl_add_u32 v208, v76, 2, v207
	v_lshl_add_u64 v[156:157], s[2:3], 0, v[58:59]
	v_lshl_add_u64 v[158:159], s[2:3], 0, v[56:57]
	v_mov_b64_e32 v[30:31], v[14:15]
	v_mov_b64_e32 v[28:29], v[12:13]
	v_mov_b64_e32 v[26:27], v[10:11]
	v_mov_b64_e32 v[24:25], v[8:9]
	v_mov_b64_e32 v[22:23], v[6:7]
	v_mov_b64_e32 v[20:21], v[4:5]
	v_mov_b64_e32 v[18:19], v[2:3]
	v_mov_b32_e32 v34, 0
	v_mov_b32_e32 v35, v209
	v_mov_b32_e32 v36, v209
	v_mov_b32_e32 v37, v209
	v_mov_b32_e32 v38, v209
	v_mov_b32_e32 v39, v209
	v_mov_b32_e32 v40, v209
	v_mov_b32_e32 v41, v209
	v_mov_b32_e32 v42, v209
	v_mov_b32_e32 v43, v209
	v_mov_b32_e32 v44, v209
	v_mov_b32_e32 v45, v209
	v_mov_b32_e32 v46, v209
	v_mov_b32_e32 v47, v209
	v_mov_b32_e32 v48, v209
	v_mov_b32_e32 v49, v209
	v_mov_b32_e32 v50, 0
	v_mov_b32_e32 v51, v209
	v_mov_b32_e32 v52, v209
	v_mov_b32_e32 v53, v209
	v_mov_b32_e32 v54, v209
	v_mov_b32_e32 v55, v209
	v_mov_b32_e32 v56, v209
	v_mov_b32_e32 v57, v209
	v_mov_b32_e32 v58, v209
	v_mov_b32_e32 v59, v209
	v_mov_b32_e32 v60, v209
	v_mov_b32_e32 v61, v209
	v_mov_b32_e32 v62, v209
	v_mov_b32_e32 v63, v209
	v_mov_b32_e32 v64, v209
	v_mov_b32_e32 v65, v209
	v_mov_b32_e32 v162, 0x27e00
	v_mov_b32_e32 v178, 0
	v_mov_b32_e32 v179, 1
	v_mov_b32_e32 v180, 8
	ds_write_b32 v162, v178
	s_waitcnt lgkmcnt(0)
	s_barrier
; #define SBAR() __builtin_amdgcn_sched_barrier(0)
; #define SLOAD(i, k0) do { sr_[i].vs0 = *reinterpret_cast<const bf16x8*>(&Vh[(long)((k0) + sr) * LDP + sc]); sr_[i].vs1 = *reinterpret_cast<const bf16x8*>(&Vh[(long)((k0) + 32 + sr) * LDP + sc]); \
;     sr_[i].ks0 = *reinterpret_cast<const bf16x8*>(&Kh[(long)((k0) + ksr) * LDP + ksc]); if (DK == 128) sr_[i].ks1 = *reinterpret_cast<const bf16x8*>(&Kh[(long)((k0) + 32 + ksr) * LDP + ksc]); } while (0)
; #define HOOK(P0, P1, j) do { if (NA) na_hook(P0, P1, krow0 + (j), q_row, q_col, win_r, win_c, rpb, inv_scale, hi); } while (0)
; template <int DK, bool NA, bool QL, int SD> ...
;     ...
;     SBAR(); qkt<DK, QL>(pB0, pB1, (bf16*)((char*)K_lds + SHM_K), qr, ql, r32, hi); HOOK(pB0, pB1, j);
;     finishSM(pA0, pA1, alA, l_reg, pa0, pa1, pa2, pa3); SBAR();
;     SLOAD(SO, (j + SD) * KVBLK); SBAR();
;     pv_d0(o, vb0, pa0, pa1, pa2, pa3); partialSM(pB0, pB1, m_reg, mnB, alB, C, thrRaw);
.LBB0_682:
	ds_read_b128 v[66:69], v212 offset:49152
	ds_read_b128 v[70:73], v212 offset:53248
	v_exp_f32_e32 v143, v138
	v_add_f32_e32 v138, 0, v177
	v_add_f32_e32 v138, v226, v138
	s_waitcnt lgkmcnt(1)
	v_mfma_f32_32x32x16_bf16 v[82:97], v[66:69], v[110:113], 0
	v_add_f32_e32 v138, v161, v138
	v_add_f32_e32 v138, v223, v138
	v_add_f32_e32 v138, v153, v138
	ds_read_b128 v[228:231], v216 offset:49152
	ds_read_b128 v[232:235], v216 offset:53248
	v_add_f32_e32 v138, v176, v138
	v_add_f32_e32 v138, v152, v138
	v_add_f32_e32 v138, v160, v138
	s_waitcnt lgkmcnt(2)
	v_mfma_f32_32x32x16_bf16 v[66:81], v[70:73], v[110:113], 0
	v_add_f32_e32 v138, v149, v138
	v_add_f32_e32 v138, v151, v138
	v_add_f32_e32 v138, v147, v138
	v_add_f32_e32 v138, v150, v138
	v_add_f32_e32 v138, v145, v138
	v_exp_f32_e32 v164, v139
	v_add_f32_e32 v138, v148, v138
	s_waitcnt lgkmcnt(1)
	v_mfma_f32_32x32x16_bf16 v[82:97], v[228:231], v[106:109], v[82:97]
	v_exp_f32_e32 v136, v136
	v_add_f32_e32 v138, v144, v138
	v_exp_f32_e32 v137, v137
	v_add_f32_e32 v138, v146, v138
	v_exp_f32_e32 v130, v130
	v_add_f32_e32 v138, v143, v138
	v_exp_f32_e32 v131, v131
	s_waitcnt lgkmcnt(0)
	v_mfma_f32_32x32x16_bf16 v[66:81], v[232:235], v[106:109], v[66:81]
	ds_read_b128 v[228:231], v217 offset:49152
	ds_read_b128 v[232:235], v217 offset:53248
	v_add_f32_e32 v138, v164, v138
	v_exp_f32_e32 v128, v128
	v_add_f32_e32 v138, v136, v138
	v_exp_f32_e32 v129, v129
	v_add_f32_e32 v138, v137, v138
	v_exp_f32_e32 v126, v126
	s_waitcnt lgkmcnt(1)
	v_mfma_f32_32x32x16_bf16 v[82:97], v[228:231], v[98:101], v[82:97]
	v_add_f32_e32 v138, v130, v138
	v_exp_f32_e32 v127, v127
	v_add_f32_e32 v138, v131, v138
	v_exp_f32_e32 v165, v140
	v_add_f32_e32 v138, v128, v138
	v_exp_f32_e32 v166, v141
	v_add_f32_e32 v138, v129, v138
	s_waitcnt lgkmcnt(0)
	v_mfma_f32_32x32x16_bf16 v[66:81], v[232:235], v[98:101], v[66:81]
	ds_read_b128 v[228:231], v218 offset:49152
	ds_read_b128 v[232:235], v218 offset:53248
	v_exp_f32_e32 v134, v134
	v_add_f32_e32 v138, v126, v138
	v_exp_f32_e32 v135, v135
	v_add_f32_e32 v138, v127, v138
	v_exp_f32_e32 v132, v132
	v_add_f32_e32 v138, v165, v138
	s_waitcnt lgkmcnt(1)
	v_mfma_f32_32x32x16_bf16 v[82:97], v[228:231], v[102:105], v[82:97]
	v_exp_f32_e32 v133, v133
	v_add_f32_e32 v138, v166, v138
	v_add_f32_e32 v138, v134, v138
	v_add_f32_e32 v138, v135, v138
	v_add_f32_e32 v138, v132, v138
	v_add_f32_e32 v220, v133, v138
	v_mov_b32_e32 v221, v220
	s_waitcnt lgkmcnt(0)
	v_mfma_f32_32x32x16_bf16 v[66:81], v[232:235], v[102:105], v[66:81]
	v_cvt_pk_bf16_f32 v138, v177, v226
	v_cvt_pk_bf16_f32 v139, v161, v223
	v_cvt_pk_bf16_f32 v140, v153, v176
	v_cvt_pk_bf16_f32 v141, v152, v160
	v_cvt_pk_bf16_f32 v222, v149, v151
	v_cvt_pk_bf16_f32 v223, v147, v150
	v_cvt_pk_bf16_f32 v224, v145, v148
	v_permlane32_swap_b32_e32 v220, v221
	v_permlane32_swap_b32_e32 v138, v140
	v_cvt_pk_bf16_f32 v225, v144, v146
	v_permlane32_swap_b32_e32 v222, v224
	v_cvt_pk_bf16_f32 v144, v143, v164
	v_cvt_pk_bf16_f32 v145, v136, v137
	v_cvt_pk_bf16_f32 v146, v130, v131
	v_cvt_pk_bf16_f32 v147, v128, v129
	v_cvt_pk_bf16_f32 v148, v126, v127
	v_cvt_pk_bf16_f32 v149, v165, v166
	v_cvt_pk_bf16_f32 v150, v134, v135
	v_cvt_pk_bf16_f32 v151, v132, v133
	v_permlane32_swap_b32_e32 v139, v141
	v_permlane32_swap_b32_e32 v223, v225
	v_permlane32_swap_b32_e32 v144, v146
	v_permlane32_swap_b32_e32 v145, v147
	v_permlane32_swap_b32_e32 v148, v150
	v_permlane32_swap_b32_e32 v149, v151
	v_readlane_b32 s2, v254, 32
	v_readlane_b32 s3, v254, 33
	s_mov_b32 s4, 0xe0e0000
	s_mov_b32 s5, 0xe130000
	v_lshl_add_u64 v[160:161], v[156:157], 0, s[2:3]
	v_add_co_u32_e32 v126, vcc, s4, v160
	v_lshl_add_u64 v[176:177], v[158:159], 0, s[2:3]
	s_nop 0
	v_addc_co_u32_e32 v127, vcc, 0, v161, vcc
	v_add_co_u32_e32 v130, vcc, s5, v160
	s_nop 1
	v_addc_co_u32_e32 v131, vcc, 0, v161, vcc
	v_add_co_u32_e32 v134, vcc, s4, v176
	global_load_dwordx4 v[126:129], v[126:127], off offset:2048
	s_nop 0
	global_load_dwordx4 v[130:133], v[130:131], off offset:2048
	v_addc_co_u32_e32 v135, vcc, 0, v177, vcc
	global_load_dwordx4 v[134:137], v[134:135], off offset:1024
	ds_read_b64_tr_b16 v[226:227], v211 offset:0
	ds_read_b64_tr_b16 v[228:229], v211 offset:0x800
	ds_read_b64_tr_b16 v[230:231], v211 offset:0x1000
	ds_read_b64_tr_b16 v[232:233], v211 offset:0x1800
	ds_read_b64_tr_b16 v[234:235], v211 offset:0x2000
	ds_read_b64_tr_b16 v[236:237], v211 offset:0x2800
	ds_read_b64_tr_b16 v[238:239], v211 offset:0x3000
	ds_read_b64_tr_b16 v[240:241], v211 offset:0x3800
	s_waitcnt lgkmcnt(6)
	s_nop 0
	v_mfma_f32_32x32x16_bf16 v[18:33], v[138:141], v[226:229], v[18:33]
	ds_read_b64_tr_b16 v[226:227], v211 offset:0x200
	ds_read_b64_tr_b16 v[228:229], v211 offset:0xa00
	s_waitcnt lgkmcnt(6)
	v_mfma_f32_32x32x16_bf16 v[18:33], v[222:225], v[230:233], v[18:33]
	ds_read_b64_tr_b16 v[230:231], v211 offset:0x1200
	ds_read_b64_tr_b16 v[232:233], v211 offset:0x1a00
	s_waitcnt lgkmcnt(6)
	v_mfma_f32_32x32x16_bf16 v[18:33], v[144:147], v[234:237], v[18:33]
	ds_read_b64_tr_b16 v[234:235], v211 offset:0x2200
	ds_read_b64_tr_b16 v[236:237], v211 offset:0x2a00
	s_waitcnt lgkmcnt(6)
	v_mfma_f32_32x32x16_bf16 v[18:33], v[148:151], v[238:241], v[18:33]
	ds_read_b64_tr_b16 v[238:239], v211 offset:0x3200
	ds_read_b64_tr_b16 v[240:241], v211 offset:0x3a00
	s_waitcnt lgkmcnt(6)
	v_mfma_f32_32x32x16_bf16 v[2:17], v[138:141], v[226:229], v[2:17]
	ds_read_b64_tr_b16 v[226:227], v211 offset:0x400
	ds_read_b64_tr_b16 v[228:229], v211 offset:0xc00
	s_waitcnt lgkmcnt(6)
	v_mfma_f32_32x32x16_bf16 v[2:17], v[222:225], v[230:233], v[2:17]
	ds_read_b64_tr_b16 v[230:231], v211 offset:0x1400
	ds_read_b64_tr_b16 v[232:233], v211 offset:0x1c00
	s_waitcnt lgkmcnt(6)
; #define SWAIT() do { if (SD == 1) asm volatile("s_waitcnt vmcnt(0)" ::: "memory"); else if (DK == 128) asm volatile("s_waitcnt vmcnt(4)" ::: "memory"); else asm volatile("s_waitcnt vmcnt(3)" ::: "memory"); } while (0)
; #define RESC(a) do { if (__any((a) < 1.f)) { if (hi == 0) al_l[r32] = (a); asm volatile("s_waitcnt lgkmcnt(0)" ::: "memory"); \
;     _Pragma("unroll") for (int d = 0; d < 4; ++d) _Pragma("unroll") for (int r = 0; r < 16; ++r) o[d][r] *= al_l[crow(r, hi)]; } } while (0)
; template <int DK, bool NA, bool QL, int SD> ...
;     ...
;     pv_d0(o, vb0, pa0, pa1, pa2, pa3); partialSM(pB0, pB1, m_reg, mnB, alB, C, thrRaw);
;     __syncthreads(); SWAIT(); SWRITE(0, SE);
;     RESC(alB); __syncthreads();
	v_mfma_f32_32x32x16_bf16 v[2:17], v[144:147], v[234:237], v[2:17]
	ds_read_b64_tr_b16 v[234:235], v211 offset:0x2400
	ds_read_b64_tr_b16 v[236:237], v211 offset:0x2c00
	s_waitcnt lgkmcnt(6)
	v_mfma_f32_32x32x16_bf16 v[2:17], v[148:151], v[238:241], v[2:17]
	ds_read_b64_tr_b16 v[238:239], v211 offset:0x3400
	ds_read_b64_tr_b16 v[240:241], v211 offset:0x3c00
	s_waitcnt lgkmcnt(6)
	v_mfma_f32_32x32x16_bf16 v[50:65], v[138:141], v[226:229], v[50:65]
	ds_read_b64_tr_b16 v[226:227], v211 offset:0x600
	ds_read_b64_tr_b16 v[228:229], v211 offset:0xe00
	s_waitcnt lgkmcnt(6)
	v_mfma_f32_32x32x16_bf16 v[50:65], v[222:225], v[230:233], v[50:65]
	ds_read_b64_tr_b16 v[230:231], v211 offset:0x1600
	ds_read_b64_tr_b16 v[232:233], v211 offset:0x1e00
	s_waitcnt lgkmcnt(6)
	v_mfma_f32_32x32x16_bf16 v[50:65], v[144:147], v[234:237], v[50:65]
	ds_read_b64_tr_b16 v[234:235], v211 offset:0x2600
	ds_read_b64_tr_b16 v[236:237], v211 offset:0x2e00
	s_waitcnt lgkmcnt(6)
	v_mfma_f32_32x32x16_bf16 v[50:65], v[148:151], v[238:241], v[50:65]
	ds_read_b64_tr_b16 v[238:239], v211 offset:0x3600
	ds_read_b64_tr_b16 v[240:241], v211 offset:0x3e00
	s_waitcnt lgkmcnt(6)
	v_mfma_f32_32x32x16_bf16 v[34:49], v[138:141], v[226:229], v[34:49]
	v_max_f32_e32 v138, v83, v83
	v_max_f32_e32 v139, v82, v82
	v_max_f32_e32 v138, v139, v138
	v_max3_f32 v138, v138, v84, v85
	v_max3_f32 v138, v138, v86, v87
	v_max3_f32 v138, v138, v88, v89
	v_max3_f32 v138, v138, v90, v91
	v_max3_f32 v138, v138, v92, v93
	v_max3_f32 v138, v138, v94, v95
	s_waitcnt lgkmcnt(4)
	v_mfma_f32_32x32x16_bf16 v[34:49], v[222:225], v[230:233], v[34:49]
	v_max3_f32 v138, v138, v96, v97
	v_max3_f32 v138, v138, v66, v67
	v_max3_f32 v138, v138, v68, v69
	v_max3_f32 v138, v138, v70, v71
	v_max3_f32 v138, v138, v72, v73
	v_max3_f32 v138, v138, v74, v75
	v_max3_f32 v138, v138, v76, v77
	v_max3_f32 v138, v138, v78, v79
	s_waitcnt lgkmcnt(2)
	v_mfma_f32_32x32x16_bf16 v[34:49], v[144:147], v[234:237], v[34:49]
	v_max3_f32 v138, v138, v80, v81
	v_mov_b32_e32 v139, v138
	s_nop 1
	v_permlane32_swap_b32_e32 v138, v139
	v_max_f32_e32 v139, v139, v139
	v_max_f32_e32 v138, v138, v138
	v_max_f32_e32 v138, v138, v139
	v_sub_f32_e32 v139, v138, v142
	s_mov_b32 s2, 0x42800000
	v_cmp_ge_f32_e32 vcc, s2, v139
	v_max_f32_e32 v139, v142, v142
	v_max_f32_e32 v138, v139, v138
	s_waitcnt lgkmcnt(0)
	v_mfma_f32_32x32x16_bf16 v[34:49], v[148:151], v[238:241], v[34:49]
	v_sub_f32_e32 v139, v142, v138
	v_mul_f32_e32 v139, 0x3e38aa3b, v139
	v_exp_f32_e32 v139, v139
	s_cmp_eq_u64 vcc, exec
	s_cselect_b64 s[2:3], -1, 0
	s_waitcnt vmcnt(3)
	v_cndmask_b32_e64 v222, v139, 1.0, s[2:3]
	v_cmp_gt_f32_e32 vcc, 1.0, v222
	s_waitcnt vmcnt(3)
	ds_write_b128 v213, v[122:125] offset:32768
	s_mov_b64 s[6:7], exec
	s_mov_b64 exec, 1
	ds_add_u32 v162, v179
	s_mov_b64 exec, s[6:7]
	s_cbranch_vccz .LBB0_686
	s_and_saveexec_b64 s[4:5], s[0:1]
	ds_write_b32 v208, v222 offset:128
	s_or_b64 exec, exec, s[4:5]
	s_waitcnt lgkmcnt(0)
	v_add_u32_e32 v139, v207, v0
	ds_read_b128 v[144:147], v139 offset:128
	ds_read_b128 v[148:151], v139 offset:160
	ds_read_b128 v[224:227], v139 offset:192
	ds_read_b128 v[228:231], v139 offset:224
	s_waitcnt lgkmcnt(3)
	v_pk_mul_f32 v[2:3], v[144:145], v[2:3]
	v_pk_mul_f32 v[4:5], v[4:5], v[146:147]
	s_waitcnt lgkmcnt(2)
	v_pk_mul_f32 v[6:7], v[6:7], v[148:149]
	v_pk_mul_f32 v[8:9], v[8:9], v[150:151]
	s_waitcnt lgkmcnt(1)
	v_pk_mul_f32 v[10:11], v[10:11], v[224:225]
	v_pk_mul_f32 v[12:13], v[12:13], v[226:227]
	s_waitcnt lgkmcnt(0)
	v_pk_mul_f32 v[14:15], v[14:15], v[228:229]
	v_pk_mul_f32 v[30:31], v[30:31], v[228:229]
	v_pk_mul_f32 v[26:27], v[26:27], v[224:225]
	v_pk_mul_f32 v[22:23], v[22:23], v[148:149]
	v_pk_mul_f32 v[32:33], v[32:33], v[230:231]
	v_pk_mul_f32 v[28:29], v[28:29], v[226:227]
	v_pk_mul_f32 v[24:25], v[24:25], v[150:151]
	v_pk_mul_f32 v[20:21], v[20:21], v[146:147]
	v_pk_mul_f32 v[18:19], v[18:19], v[144:145]
	v_pk_mul_f32 v[16:17], v[16:17], v[230:231]
	v_pk_mul_f32 v[34:35], v[144:145], v[34:35]
	v_pk_mul_f32 v[36:37], v[36:37], v[146:147]
	v_pk_mul_f32 v[38:39], v[38:39], v[148:149]
	v_pk_mul_f32 v[40:41], v[40:41], v[150:151]
	v_pk_mul_f32 v[42:43], v[42:43], v[224:225]
	v_pk_mul_f32 v[44:45], v[44:45], v[226:227]
	v_pk_mul_f32 v[46:47], v[46:47], v[228:229]
	v_pk_mul_f32 v[62:63], v[62:63], v[228:229]
	v_pk_mul_f32 v[58:59], v[58:59], v[224:225]
	v_pk_mul_f32 v[54:55], v[54:55], v[148:149]
	v_pk_mul_f32 v[64:65], v[64:65], v[230:231]
	v_pk_mul_f32 v[60:61], v[60:61], v[226:227]
	v_pk_mul_f32 v[56:57], v[56:57], v[150:151]
	v_pk_mul_f32 v[52:53], v[52:53], v[146:147]
	v_pk_mul_f32 v[50:51], v[50:51], v[144:145]
	v_pk_mul_f32 v[48:49], v[48:49], v[230:231]
.LBB0_686:
	ds_read_b32 v178, v162
	v_cndmask_b32_e64 v223, v138, v142, s[2:3]
	v_mul_f32_e32 v224, 0xbe38aa3b, v223
	v_fmamk_f32 v82, v82, 0x3e38aa3b, v224
	v_fmamk_f32 v83, v83, 0x3e38aa3b, v224
	v_fmamk_f32 v84, v84, 0x3e38aa3b, v224
	v_fmamk_f32 v85, v85, 0x3e38aa3b, v224
	v_fmamk_f32 v86, v86, 0x3e38aa3b, v224
	v_fmamk_f32 v87, v87, 0x3e38aa3b, v224
	v_fmamk_f32 v88, v88, 0x3e38aa3b, v224
	v_fmamk_f32 v89, v89, 0x3e38aa3b, v224
	v_fmamk_f32 v90, v90, 0x3e38aa3b, v224
	v_fmamk_f32 v91, v91, 0x3e38aa3b, v224
	v_fmamk_f32 v92, v92, 0x3e38aa3b, v224
	v_fmamk_f32 v93, v93, 0x3e38aa3b, v224
	v_fmamk_f32 v94, v94, 0x3e38aa3b, v224
	v_fmamk_f32 v95, v95, 0x3e38aa3b, v224
	v_fmamk_f32 v96, v96, 0x3e38aa3b, v224
	v_fmamk_f32 v97, v97, 0x3e38aa3b, v224
	v_exp_f32_e32 v138, v82
	v_exp_f32_e32 v153, v83
	v_exp_f32_e32 v139, v84
	v_exp_f32_e32 v152, v85
	v_exp_f32_e32 v140, v86
	v_exp_f32_e32 v151, v87
	v_exp_f32_e32 v141, v88
	v_exp_f32_e32 v150, v89
	v_exp_f32_e32 v142, v90
	v_exp_f32_e32 v149, v91
	v_exp_f32_e32 v143, v92
	v_exp_f32_e32 v148, v93
	v_exp_f32_e32 v144, v94
	v_exp_f32_e32 v147, v95
	v_exp_f32_e32 v145, v96
	v_exp_f32_e32 v146, v97
	v_fmamk_f32 v233, v66, 0x3e38aa3b, v224
	v_fmamk_f32 v234, v67, 0x3e38aa3b, v224
	v_fmamk_f32 v235, v68, 0x3e38aa3b, v224
	v_fmamk_f32 v236, v69, 0x3e38aa3b, v224
	v_fmamk_f32 v237, v70, 0x3e38aa3b, v224
	v_fmamk_f32 v226, v71, 0x3e38aa3b, v224
	v_fmamk_f32 v227, v72, 0x3e38aa3b, v224
	v_fmamk_f32 v228, v73, 0x3e38aa3b, v224
	v_fmamk_f32 v229, v74, 0x3e38aa3b, v224
	v_fmamk_f32 v230, v75, 0x3e38aa3b, v224
	v_fmamk_f32 v231, v76, 0x3e38aa3b, v224
	v_fmamk_f32 v232, v77, 0x3e38aa3b, v224
	v_fmamk_f32 v225, v78, 0x3e38aa3b, v224
	v_fmamk_f32 v238, v79, 0x3e38aa3b, v224
	v_fmamk_f32 v239, v80, 0x3e38aa3b, v224
	v_fmac_f32_e32 v224, 0x3e38aa3b, v81
	v_mov_b32_e32 v155, 0

; #define SBAR() __builtin_amdgcn_sched_barrier(0)
; #define SLOAD(i, k0) do { sr_[i].vs0 = *reinterpret_cast<const bf16x8*>(&Vh[(long)((k0) + sr) * LDP + sc]); sr_[i].vs1 = *reinterpret_cast<const bf16x8*>(&Vh[(long)((k0) + 32 + sr) * LDP + sc]); \
;     sr_[i].ks0 = *reinterpret_cast<const bf16x8*>(&Kh[(long)((k0) + ksr) * LDP + ksc]); if (DK == 128) sr_[i].ks1 = *reinterpret_cast<const bf16x8*>(&Kh[(long)((k0) + 32 + ksr) * LDP + ksc]); } while (0)
; #define SWAIT() do { if (SD == 1) asm volatile("s_waitcnt vmcnt(0)" ::: "memory"); else if (DK == 128) asm volatile("s_waitcnt vmcnt(4)" ::: "memory"); else asm volatile("s_waitcnt vmcnt(3)" ::: "memory"); } while (0)
; #define RESC(a) do { if (__any((a) < 1.f)) { if (hi == 0) al_l[r32] = (a); asm volatile("s_waitcnt lgkmcnt(0)" ::: "memory"); \
;     _Pragma("unroll") for (int d = 0; d < 4; ++d) _Pragma("unroll") for (int r = 0; r < 16; ++r) o[d][r] *= al_l[crow(r, hi)]; } } while (0)
; #define HOOK(P0, P1, j) do { if (NA) na_hook(P0, P1, krow0 + (j), q_row, q_col, win_r, win_c, rpb, inv_scale, hi); } while (0)
; template <int DK, bool NA, bool QL, int SD> ...
;     ...
;     __syncthreads(); SWAIT(); SWRITE(0, SE);
;     RESC(alB); __syncthreads();
;     SBAR(); qkt<DK, QL>(pA0, pA1, K_lds, qr, ql, r32, hi); HOOK(pA0, pA1, j + 1);
;     finishSM(pB0, pB1, alB, l_reg, pa0, pa1, pa2, pa3); SBAR();
;     if (SD == 1 || j + 3 < NT) SLOAD(SE, (j + 1 + SD) * KVBLK); SBAR();
;     pv_d0(o, vb0 + (int)SHM_V, pa0, pa1, pa2, pa3); partialSM(pA0, pA1, m_reg, mnA, alA, C, thrRaw);
.Lsb_d10_d:
	v_add_u32_e32 v180, 8, v180
	ds_write_b128 v214, v[114:117]
	ds_write_b128 v215, v[118:121]
	ds_read_b128 v[66:69], v212 offset:32768
	ds_read_b128 v[70:73], v212 offset:36864
	v_exp_f32_e32 v164, v233
	v_exp_f32_e32 v233, v224
	v_add_f32_e32 v224, 0, v138
	v_add_f32_e32 v224, v153, v224
	s_waitcnt lgkmcnt(1)
	v_mfma_f32_32x32x16_bf16 v[82:97], v[66:69], v[110:113], 0
	v_add_f32_e32 v224, v139, v224
	v_add_f32_e32 v224, v152, v224
	v_add_f32_e32 v224, v140, v224
	ds_read_b128 v[240:243], v216 offset:32768
	ds_read_b128 v[244:247], v216 offset:36864
	v_add_f32_e32 v224, v151, v224
	v_add_f32_e32 v224, v141, v224
	v_add_f32_e32 v224, v150, v224
	s_waitcnt lgkmcnt(2)
	v_mfma_f32_32x32x16_bf16 v[66:81], v[70:73], v[110:113], 0
	v_add_f32_e32 v224, v142, v224
	v_add_f32_e32 v224, v149, v224
	v_add_f32_e32 v224, v143, v224
	v_add_f32_e32 v224, v148, v224
	v_add_f32_e32 v224, v144, v224
	v_exp_f32_e32 v165, v234
	v_add_f32_e32 v224, v147, v224
	s_waitcnt lgkmcnt(1)
	v_mfma_f32_32x32x16_bf16 v[82:97], v[240:243], v[106:109], v[82:97]
	v_exp_f32_e32 v166, v235
	v_add_f32_e32 v224, v145, v224
	v_exp_f32_e32 v167, v236
	v_add_f32_e32 v224, v146, v224
	v_exp_f32_e32 v172, v237
	v_add_f32_e32 v224, v164, v224
	v_exp_f32_e32 v173, v226
	s_waitcnt lgkmcnt(0)
	v_mfma_f32_32x32x16_bf16 v[66:81], v[244:247], v[106:109], v[66:81]
	ds_read_b128 v[240:243], v217 offset:32768
	ds_read_b128 v[244:247], v217 offset:36864
	v_add_f32_e32 v224, v165, v224
	v_exp_f32_e32 v174, v227
	v_add_f32_e32 v224, v166, v224
	v_exp_f32_e32 v175, v228
	v_add_f32_e32 v224, v167, v224
	v_exp_f32_e32 v226, v229
	s_waitcnt lgkmcnt(1)
	v_mfma_f32_32x32x16_bf16 v[82:97], v[240:243], v[98:101], v[82:97]
	v_add_f32_e32 v224, v172, v224
	v_exp_f32_e32 v227, v230
	v_add_f32_e32 v224, v173, v224
	v_exp_f32_e32 v228, v231
	v_add_f32_e32 v224, v174, v224
	v_exp_f32_e32 v229, v232
	v_add_f32_e32 v224, v175, v224
	s_waitcnt lgkmcnt(0)
	v_mfma_f32_32x32x16_bf16 v[66:81], v[244:247], v[98:101], v[66:81]
	ds_read_b128 v[240:243], v218 offset:32768
	ds_read_b128 v[244:247], v218 offset:36864
	v_exp_f32_e32 v230, v225
	v_add_f32_e32 v224, v226, v224
	v_exp_f32_e32 v231, v238
	v_add_f32_e32 v224, v227, v224
	v_exp_f32_e32 v232, v239
	v_add_f32_e32 v224, v228, v224
	s_waitcnt lgkmcnt(1)
	v_mfma_f32_32x32x16_bf16 v[82:97], v[240:243], v[102:105], v[82:97]
	v_add_f32_e32 v224, v229, v224
	v_add_f32_e32 v224, v230, v224
	v_add_f32_e32 v224, v231, v224
	v_add_f32_e32 v224, v232, v224
	v_add_f32_e32 v224, v233, v224
	v_mov_b32_e32 v225, v224
	v_cvt_pk_bf16_f32 v138, v138, v153
	s_waitcnt lgkmcnt(0)
	v_mfma_f32_32x32x16_bf16 v[66:81], v[244:247], v[102:105], v[66:81]
	v_cvt_pk_bf16_f32 v139, v139, v152
	v_cvt_pk_bf16_f32 v140, v140, v151
	v_cvt_pk_bf16_f32 v141, v141, v150
	v_cvt_pk_bf16_f32 v142, v142, v149
	v_cvt_pk_bf16_f32 v143, v143, v148
	v_cvt_pk_bf16_f32 v144, v144, v147
	v_cvt_pk_bf16_f32 v145, v145, v146
	v_cvt_pk_bf16_f32 v146, v164, v165
	v_cvt_pk_bf16_f32 v147, v166, v167
	v_cvt_pk_bf16_f32 v148, v172, v173
	v_cvt_pk_bf16_f32 v149, v174, v175
	v_cvt_pk_bf16_f32 v150, v226, v227
	v_cvt_pk_bf16_f32 v151, v228, v229
	v_cvt_pk_bf16_f32 v152, v230, v231
	v_cvt_pk_bf16_f32 v153, v232, v233
	v_permlane32_swap_b32_e32 v224, v225
	v_permlane32_swap_b32_e32 v138, v140
	v_permlane32_swap_b32_e32 v139, v141
	v_permlane32_swap_b32_e32 v142, v144
	v_permlane32_swap_b32_e32 v143, v145
	v_permlane32_swap_b32_e32 v146, v148
	v_permlane32_swap_b32_e32 v147, v149
	v_permlane32_swap_b32_e32 v150, v152
	v_permlane32_swap_b32_e32 v151, v153
	s_cmp_gt_u32 s9, 60
	s_cselect_b64 s[4:5], -1, 0
	s_and_b64 vcc, exec, s[4:5]
	s_cbranch_vccnz .Lod_d1
	v_add_co_u32_e32 v114, vcc, 0xe180000, v160
	s_nop 1
	v_addc_co_u32_e32 v115, vcc, 0, v161, vcc
	v_add_co_u32_e32 v118, vcc, 0xe1d0000, v160
	s_nop 1
	v_addc_co_u32_e32 v119, vcc, 0, v161, vcc
	v_add_co_u32_e32 v122, vcc, 0xe180000, v176
	global_load_dwordx4 v[114:117], v[114:115], off offset:2048
	s_nop 0
	global_load_dwordx4 v[118:121], v[118:119], off offset:2048
	v_addc_co_u32_e32 v123, vcc, 0, v177, vcc
	global_load_dwordx4 v[122:125], v[122:123], off offset:1024
.LBB0_688:
	ds_read_b64_tr_b16 v[226:227], v210 offset:0
	ds_read_b64_tr_b16 v[228:229], v210 offset:0x800
	ds_read_b64_tr_b16 v[230:231], v210 offset:0x1000
	ds_read_b64_tr_b16 v[232:233], v210 offset:0x1800
	ds_read_b64_tr_b16 v[234:235], v210 offset:0x2000
	ds_read_b64_tr_b16 v[236:237], v210 offset:0x2800
	ds_read_b64_tr_b16 v[238:239], v210 offset:0x3000
	ds_read_b64_tr_b16 v[240:241], v210 offset:0x3800
	s_waitcnt lgkmcnt(6)
	s_nop 0
	v_mfma_f32_32x32x16_bf16 v[18:33], v[138:141], v[226:229], v[18:33]
	ds_read_b64_tr_b16 v[226:227], v210 offset:0x200
	ds_read_b64_tr_b16 v[228:229], v210 offset:0xa00
	s_waitcnt lgkmcnt(6)
	v_mfma_f32_32x32x16_bf16 v[18:33], v[142:145], v[230:233], v[18:33]
	ds_read_b64_tr_b16 v[230:231], v210 offset:0x1200
	ds_read_b64_tr_b16 v[232:233], v210 offset:0x1a00
	s_waitcnt lgkmcnt(6)
	v_mfma_f32_32x32x16_bf16 v[18:33], v[146:149], v[234:237], v[18:33]
	ds_read_b64_tr_b16 v[234:235], v210 offset:0x2200
	ds_read_b64_tr_b16 v[236:237], v210 offset:0x2a00
	s_waitcnt lgkmcnt(6)
	v_mfma_f32_32x32x16_bf16 v[18:33], v[150:153], v[238:241], v[18:33]
	ds_read_b64_tr_b16 v[238:239], v210 offset:0x3200
	ds_read_b64_tr_b16 v[240:241], v210 offset:0x3a00
	s_waitcnt lgkmcnt(6)
	v_mfma_f32_32x32x16_bf16 v[2:17], v[138:141], v[226:229], v[2:17]
	ds_read_b64_tr_b16 v[226:227], v210 offset:0x400
	ds_read_b64_tr_b16 v[228:229], v210 offset:0xc00
	s_waitcnt lgkmcnt(6)
	v_mfma_f32_32x32x16_bf16 v[2:17], v[142:145], v[230:233], v[2:17]
	ds_read_b64_tr_b16 v[230:231], v210 offset:0x1400
	ds_read_b64_tr_b16 v[232:233], v210 offset:0x1c00
	s_waitcnt lgkmcnt(6)
; #define SWAIT() do { if (SD == 1) asm volatile("s_waitcnt vmcnt(0)" ::: "memory"); else if (DK == 128) asm volatile("s_waitcnt vmcnt(4)" ::: "memory"); else asm volatile("s_waitcnt vmcnt(3)" ::: "memory"); } while (0)
; #define RESC(a) do { if (__any((a) < 1.f)) { if (hi == 0) al_l[r32] = (a); asm volatile("s_waitcnt lgkmcnt(0)" ::: "memory"); \
;     _Pragma("unroll") for (int d = 0; d < 4; ++d) _Pragma("unroll") for (int r = 0; r < 16; ++r) o[d][r] *= al_l[crow(r, hi)]; } } while (0)
; template <int DK, bool NA, bool QL, int SD> ...
;     ...
;     pv_d0(o, vb0 + (int)SHM_V, pa0, pa1, pa2, pa3); partialSM(pA0, pA1, m_reg, mnA, alA, C, thrRaw);
;     __syncthreads(); SWAIT(); SWRITE(1, SO);
;     RESC(alA); __syncthreads();
	v_mfma_f32_32x32x16_bf16 v[2:17], v[146:149], v[234:237], v[2:17]
	ds_read_b64_tr_b16 v[234:235], v210 offset:0x2400
	ds_read_b64_tr_b16 v[236:237], v210 offset:0x2c00
	s_waitcnt lgkmcnt(6)
	v_mfma_f32_32x32x16_bf16 v[2:17], v[150:153], v[238:241], v[2:17]
	ds_read_b64_tr_b16 v[238:239], v210 offset:0x3400
	ds_read_b64_tr_b16 v[240:241], v210 offset:0x3c00
	s_waitcnt lgkmcnt(6)
	v_mfma_f32_32x32x16_bf16 v[50:65], v[138:141], v[226:229], v[50:65]
	ds_read_b64_tr_b16 v[226:227], v210 offset:0x600
	ds_read_b64_tr_b16 v[228:229], v210 offset:0xe00
	s_waitcnt lgkmcnt(6)
	v_mfma_f32_32x32x16_bf16 v[50:65], v[142:145], v[230:233], v[50:65]
	ds_read_b64_tr_b16 v[230:231], v210 offset:0x1600
	ds_read_b64_tr_b16 v[232:233], v210 offset:0x1e00
	s_waitcnt lgkmcnt(6)
	v_mfma_f32_32x32x16_bf16 v[50:65], v[146:149], v[234:237], v[50:65]
	ds_read_b64_tr_b16 v[234:235], v210 offset:0x2600
	ds_read_b64_tr_b16 v[236:237], v210 offset:0x2e00
	s_waitcnt lgkmcnt(6)
	v_mfma_f32_32x32x16_bf16 v[50:65], v[150:153], v[238:241], v[50:65]
	ds_read_b64_tr_b16 v[238:239], v210 offset:0x3600
	ds_read_b64_tr_b16 v[240:241], v210 offset:0x3e00
	s_waitcnt lgkmcnt(6)
	v_mfma_f32_32x32x16_bf16 v[34:49], v[138:141], v[226:229], v[34:49]
	v_max_f32_e32 v138, v83, v83
	v_max_f32_e32 v139, v82, v82
	v_max_f32_e32 v138, v139, v138
	v_max3_f32 v138, v138, v84, v85
	v_max3_f32 v138, v138, v86, v87
	v_max3_f32 v138, v138, v88, v89
	v_max3_f32 v138, v138, v90, v91
	v_max3_f32 v138, v138, v92, v93
	v_max3_f32 v138, v138, v94, v95
	s_waitcnt lgkmcnt(4)
	v_mfma_f32_32x32x16_bf16 v[34:49], v[142:145], v[230:233], v[34:49]
	v_max3_f32 v138, v138, v96, v97
	v_max3_f32 v138, v138, v66, v67
	v_max3_f32 v138, v138, v68, v69
	v_max3_f32 v138, v138, v70, v71
	v_max3_f32 v138, v138, v72, v73
	v_max3_f32 v138, v138, v74, v75
	v_max3_f32 v138, v138, v76, v77
	v_max3_f32 v138, v138, v78, v79
	s_waitcnt lgkmcnt(2)
	v_mfma_f32_32x32x16_bf16 v[34:49], v[146:149], v[234:237], v[34:49]
	v_max3_f32 v138, v138, v80, v81
	v_mov_b32_e32 v139, v138
	s_nop 1
	v_permlane32_swap_b32_e32 v138, v139
	v_max_f32_e32 v139, v139, v139
	v_max_f32_e32 v138, v138, v138
	v_max_f32_e32 v138, v138, v139
	v_sub_f32_e32 v139, v138, v223
	s_mov_b32 s2, 0x42800000
	v_cmp_ge_f32_e32 vcc, s2, v139
	v_max_f32_e32 v139, v223, v223
	v_max_f32_e32 v138, v139, v138
	s_waitcnt lgkmcnt(0)
	v_mfma_f32_32x32x16_bf16 v[34:49], v[150:153], v[238:241], v[34:49]
	v_sub_f32_e32 v139, v223, v138
	v_mul_f32_e32 v139, 0x3e38aa3b, v139
	v_exp_f32_e32 v139, v139
	s_cmp_eq_u64 vcc, exec
	s_cselect_b64 s[2:3], -1, 0
	s_waitcnt vmcnt(3)
	v_cndmask_b32_e64 v143, v139, 1.0, s[2:3]
	v_cmp_gt_f32_e32 vcc, 1.0, v143
	v_mov_b64_e32 v[182:183], v[126:127]
	v_mov_b64_e32 v[184:185], v[128:129]
	v_mov_b64_e32 v[194:195], v[130:131]
	v_mov_b64_e32 v[196:197], v[132:133]
	ds_write_b128 v213, v[134:137] offset:49152
	s_mov_b64 s[6:7], exec
	s_mov_b64 exec, 1
	ds_add_u32 v162, v179
	s_mov_b64 exec, s[6:7]
	s_cbranch_vccz .LBB0_692
	s_and_saveexec_b64 s[6:7], s[0:1]
	ds_write_b32 v208, v143 offset:128
	s_or_b64 exec, exec, s[6:7]
	s_waitcnt lgkmcnt(0)
	v_add_u32_e32 v139, v207, v0
	ds_read_b128 v[126:129], v139 offset:128
	ds_read_b128 v[130:133], v139 offset:160
	ds_read_b128 v[134:137], v139 offset:224
	ds_read_b128 v[144:147], v139 offset:192
	s_waitcnt lgkmcnt(3)
	v_pk_mul_f32 v[50:51], v[126:127], v[50:51]
	v_pk_mul_f32 v[52:53], v[128:129], v[52:53]
	s_waitcnt lgkmcnt(2)
	v_pk_mul_f32 v[54:55], v[130:131], v[54:55]
	s_waitcnt lgkmcnt(1)
	v_pk_mul_f32 v[30:31], v[30:31], v[134:135]
	s_waitcnt lgkmcnt(0)
	v_pk_mul_f32 v[26:27], v[26:27], v[144:145]
	v_pk_mul_f32 v[22:23], v[22:23], v[130:131]
	v_pk_mul_f32 v[32:33], v[32:33], v[136:137]
	v_pk_mul_f32 v[28:29], v[28:29], v[146:147]
	v_pk_mul_f32 v[24:25], v[24:25], v[132:133]
	v_pk_mul_f32 v[20:21], v[20:21], v[128:129]
	v_pk_mul_f32 v[18:19], v[18:19], v[126:127]
	v_pk_mul_f32 v[14:15], v[134:135], v[14:15]
	v_pk_mul_f32 v[10:11], v[144:145], v[10:11]
	v_pk_mul_f32 v[6:7], v[130:131], v[6:7]
	v_pk_mul_f32 v[16:17], v[136:137], v[16:17]
	v_pk_mul_f32 v[12:13], v[146:147], v[12:13]
	v_pk_mul_f32 v[8:9], v[132:133], v[8:9]
	v_pk_mul_f32 v[4:5], v[128:129], v[4:5]
	v_pk_mul_f32 v[2:3], v[126:127], v[2:3]
	v_pk_mul_f32 v[56:57], v[132:133], v[56:57]
	v_pk_mul_f32 v[34:35], v[126:127], v[34:35]
	v_pk_mul_f32 v[36:37], v[36:37], v[128:129]
	v_pk_mul_f32 v[38:39], v[38:39], v[130:131]
	v_pk_mul_f32 v[40:41], v[40:41], v[132:133]
	v_pk_mul_f32 v[58:59], v[58:59], v[144:145]
	v_pk_mul_f32 v[42:43], v[42:43], v[144:145]
	v_pk_mul_f32 v[60:61], v[60:61], v[146:147]
	v_pk_mul_f32 v[44:45], v[44:45], v[146:147]
	v_pk_mul_f32 v[62:63], v[62:63], v[134:135]
	v_pk_mul_f32 v[46:47], v[46:47], v[134:135]
	v_pk_mul_f32 v[64:65], v[64:65], v[136:137]
	v_pk_mul_f32 v[48:49], v[48:49], v[136:137]
.LBB0_692:
	ds_read_b32 v178, v162
	v_cndmask_b32_e64 v142, v138, v223, s[2:3]
	v_mul_f32_e32 v132, 0xbe38aa3b, v142
	v_mov_b32_e32 v133, v132
	v_fmamk_f32 v82, v82, 0x3e38aa3b, v132
	v_fmamk_f32 v83, v83, 0x3e38aa3b, v132
	v_fmamk_f32 v84, v84, 0x3e38aa3b, v132
	v_fmamk_f32 v85, v85, 0x3e38aa3b, v132
	v_fmamk_f32 v86, v86, 0x3e38aa3b, v132
	v_fmamk_f32 v87, v87, 0x3e38aa3b, v132
	v_fmamk_f32 v88, v88, 0x3e38aa3b, v132
	v_fmamk_f32 v89, v89, 0x3e38aa3b, v132
	v_fmamk_f32 v90, v90, 0x3e38aa3b, v132
	v_fmamk_f32 v91, v91, 0x3e38aa3b, v132
	v_fmamk_f32 v92, v92, 0x3e38aa3b, v132
	v_fmamk_f32 v93, v93, 0x3e38aa3b, v132
	v_fmamk_f32 v94, v94, 0x3e38aa3b, v132
	v_fmamk_f32 v95, v95, 0x3e38aa3b, v132
	v_fmamk_f32 v96, v96, 0x3e38aa3b, v132
	v_fmac_f32_e32 v133, 0x3e38aa3b, v97
	s_mov_b32 s2, 0x3e38aa3b
	v_exp_f32_e32 v177, v82
	v_exp_f32_e32 v226, v83
	v_exp_f32_e32 v161, v84
	v_exp_f32_e32 v223, v85
	v_exp_f32_e32 v153, v86
	v_exp_f32_e32 v176, v87
	v_exp_f32_e32 v152, v88
	v_exp_f32_e32 v160, v89
	v_exp_f32_e32 v149, v90
	v_exp_f32_e32 v151, v91
	v_exp_f32_e32 v147, v92
	v_exp_f32_e32 v150, v93
	v_exp_f32_e32 v145, v94
	v_exp_f32_e32 v148, v95
	v_exp_f32_e32 v144, v96
	v_exp_f32_e32 v146, v133
	v_pk_fma_f32 v[138:139], v[66:67], s[2:3], v[132:133] op_sel_hi:[1,0,0]
	v_add_f32_e32 v66, v220, v221
	v_pk_fma_f32 v[136:137], v[68:69], s[2:3], v[132:133] op_sel_hi:[1,0,0]
	v_pk_fma_f32 v[130:131], v[70:71], s[2:3], v[132:133] op_sel_hi:[1,0,0]
	v_pk_fma_f32 v[128:129], v[72:73], s[2:3], v[132:133] op_sel_hi:[1,0,0]
	v_pk_fma_f32 v[126:127], v[74:75], s[2:3], v[132:133] op_sel_hi:[1,0,0]
	v_pk_fma_f32 v[140:141], v[76:77], s[2:3], v[132:133] op_sel_hi:[1,0,0]
	v_pk_fma_f32 v[134:135], v[78:79], s[2:3], v[132:133] op_sel_hi:[1,0,0]
	v_pk_fma_f32 v[132:133], v[80:81], s[2:3], v[132:133] op_sel_hi:[1,0,0]
	v_fmac_f32_e32 v66, v219, v209
	v_add_f32_e32 v209, v224, v225
	s_mov_b64 s[2:3], 0x140000
	v_fmac_f32_e32 v209, v66, v222
	s_add_i32 s9, s9, 2
	v_lshl_add_u64 v[156:157], v[156:157], 0, s[2:3]
	v_lshl_add_u64 v[158:159], v[158:159], 0, s[2:3]
	s_and_b64 vcc, exec, s[4:5]
	v_mov_b32_e32 v155, 0

; #define SWAIT() do { if (SD == 1) asm volatile("s_waitcnt vmcnt(0)" ::: "memory"); else if (DK == 128) asm volatile("s_waitcnt vmcnt(4)" ::: "memory"); else asm volatile("s_waitcnt vmcnt(3)" ::: "memory"); } while (0)
; #define RESC(a) do { if (__any((a) < 1.f)) { if (hi == 0) al_l[r32] = (a); asm volatile("s_waitcnt lgkmcnt(0)" ::: "memory"); \
;     _Pragma("unroll") for (int d = 0; d < 4; ++d) _Pragma("unroll") for (int r = 0; r < 16; ++r) o[d][r] *= al_l[crow(r, hi)]; } } while (0)
; template <int DK, bool NA, bool QL, int SD> ...
;     ...
;     __syncthreads(); SWAIT(); SWRITE(1, SO);
;     RESC(alA); __syncthreads();
;   }
.Lsb_d11_d:
	v_add_u32_e32 v180, 8, v180
	s_cbranch_vccnz .LBB0_694
	v_mov_b32_e32 v219, v143
	ds_write_b128 v214, v[182:185] offset:16384
	ds_write_b128 v215, v[194:197] offset:16384
	s_branch .LBB0_682

; #define SBAR() __builtin_amdgcn_sched_barrier(0)
; #define RESC(a) do { if (__any((a) < 1.f)) { if (hi == 0) al_l[r32] = (a); asm volatile("s_waitcnt lgkmcnt(0)" ::: "memory"); \
;     _Pragma("unroll") for (int d = 0; d < 4; ++d) _Pragma("unroll") for (int r = 0; r < 16; ++r) o[d][r] *= al_l[crow(r, hi)]; } } while (0)
; __device__ __forceinline__ void finishSM(f32x16& p0, f32x16& p1, float alpha, float& l_reg, bf16x8& pa0, bf16x8& pa1, bf16x8& pa2, bf16x8& pa3) {
; #pragma unroll
;   for (int r = 0; r < 16; ++r) p1[r] = __builtin_amdgcn_exp2f(p1[r]);
;   float ps = 0;
; #pragma unroll
;   for (int r = 0; r < 16; ++r) ps += p0[r];
; #pragma unroll
;   for (int r = 0; r < 16; ++r) ps += p1[r];
;   { auto rr = __builtin_amdgcn_permlane32_swap(__float_as_uint(ps), __float_as_uint(ps), false, false);
;     ps = __uint_as_float(rr[0]) + __uint_as_float(rr[1]); }
;   l_reg = l_reg * alpha + ps;
;     ...
;   PK4(p0, 0, pa0); PK4(p0, 8, pa1); PK4(p1, 0, pa2); PK4(p1, 8, pa3);
;     ...
; }
; template <int DK, bool NA, bool QL, int SD> ...
;     ...
;   __syncthreads(); RESC(alB);
;   finishSM(pB0, pB1, alB, l_reg, pa0, pa1, pa2, pa3); SBAR();
;   pv_d0(o, vb0 + (int)SHM_V, pa0, pa1, pa2, pa3);
.LBB0_698:
	v_cndmask_b32_e64 v101, v101, v142, s[2:3]
	v_mul_f32_e32 v101, 0xbe38aa3b, v101
	v_fmamk_f32 v82, v82, 0x3e38aa3b, v101
	v_fmamk_f32 v83, v83, 0x3e38aa3b, v101
	v_fmamk_f32 v102, v84, 0x3e38aa3b, v101
	v_exp_f32_e32 v84, v82
	v_fmamk_f32 v103, v86, 0x3e38aa3b, v101
	v_exp_f32_e32 v86, v83
	v_fmamk_f32 v85, v85, 0x3e38aa3b, v101
	v_exp_f32_e32 v82, v102
	v_fmamk_f32 v66, v66, 0x3e38aa3b, v101
	v_exp_f32_e32 v85, v85
	v_fmamk_f32 v104, v87, 0x3e38aa3b, v101
	v_fmamk_f32 v113, v96, 0x3e38aa3b, v101
	v_fmamk_f32 v96, v77, 0x3e38aa3b, v101
	v_exp_f32_e32 v77, v103
	v_exp_f32_e32 v102, v66
	v_add_f32_e32 v66, 0, v84
	v_fmamk_f32 v105, v88, 0x3e38aa3b, v101
	v_exp_f32_e32 v83, v104
	v_add_f32_e32 v66, v86, v66
	v_fmamk_f32 v106, v89, 0x3e38aa3b, v101
	v_fmamk_f32 v112, v95, 0x3e38aa3b, v101
	v_fmamk_f32 v95, v76, 0x3e38aa3b, v101
	v_exp_f32_e32 v76, v105
	v_add_f32_e32 v66, v82, v66
	v_fmamk_f32 v107, v90, 0x3e38aa3b, v101
	v_fmamk_f32 v114, v97, 0x3e38aa3b, v101
	v_fmamk_f32 v97, v78, 0x3e38aa3b, v101
	v_exp_f32_e32 v78, v106
	v_add_f32_e32 v66, v85, v66
	v_fmamk_f32 v108, v91, 0x3e38aa3b, v101
	v_fmamk_f32 v109, v92, 0x3e38aa3b, v101
	v_fmamk_f32 v92, v73, 0x3e38aa3b, v101
	v_exp_f32_e32 v73, v107
	v_add_f32_e32 v66, v77, v66
	v_fmamk_f32 v111, v94, 0x3e38aa3b, v101
	v_fmamk_f32 v94, v75, 0x3e38aa3b, v101
	v_exp_f32_e32 v75, v108
	v_add_f32_e32 v66, v83, v66
	v_fmamk_f32 v110, v93, 0x3e38aa3b, v101
	v_fmamk_f32 v90, v71, 0x3e38aa3b, v101
	v_exp_f32_e32 v71, v109
	v_add_f32_e32 v66, v76, v66
	v_fmamk_f32 v93, v74, 0x3e38aa3b, v101
	v_exp_f32_e32 v74, v110
	v_add_f32_e32 v66, v78, v66
	v_fmamk_f32 v88, v69, 0x3e38aa3b, v101
	v_exp_f32_e32 v69, v111
	v_add_f32_e32 v66, v73, v66
	v_fmamk_f32 v91, v72, 0x3e38aa3b, v101
	v_exp_f32_e32 v72, v112
	v_add_f32_e32 v66, v75, v66
	v_fmamk_f32 v87, v68, 0x3e38aa3b, v101
	v_exp_f32_e32 v68, v113
	v_add_f32_e32 v66, v71, v66
	v_fmamk_f32 v89, v70, 0x3e38aa3b, v101
	v_exp_f32_e32 v70, v114
	v_add_f32_e32 v66, v74, v66
	v_fmamk_f32 v67, v67, 0x3e38aa3b, v101
	v_add_f32_e32 v66, v69, v66
	v_exp_f32_e32 v103, v67
	v_add_f32_e32 v66, v72, v66
	v_exp_f32_e32 v87, v87
	v_add_f32_e32 v66, v68, v66
	v_exp_f32_e32 v88, v88
	v_add_f32_e32 v66, v70, v66
	v_exp_f32_e32 v89, v89
	v_add_f32_e32 v66, v102, v66
	v_exp_f32_e32 v90, v90
	v_add_f32_e32 v66, v103, v66
	v_exp_f32_e32 v91, v91
	v_add_f32_e32 v66, v87, v66
	v_exp_f32_e32 v92, v92
	v_add_f32_e32 v66, v88, v66
	v_exp_f32_e32 v93, v93
	v_add_f32_e32 v66, v89, v66
	v_exp_f32_e32 v94, v94
	v_add_f32_e32 v66, v90, v66
	v_exp_f32_e32 v95, v95
	v_add_f32_e32 v66, v91, v66
	v_exp_f32_e32 v96, v96
	v_add_f32_e32 v66, v92, v66
	v_fmamk_f32 v79, v79, 0x3e38aa3b, v101
	v_exp_f32_e32 v97, v97
	v_add_f32_e32 v66, v93, v66
	v_fmamk_f32 v80, v80, 0x3e38aa3b, v101
	v_exp_f32_e32 v104, v79
	v_add_f32_e32 v66, v94, v66
	v_fmac_f32_e32 v101, 0x3e38aa3b, v81
	v_exp_f32_e32 v105, v80
	v_add_f32_e32 v66, v95, v66
	v_exp_f32_e32 v101, v101
	v_add_f32_e32 v66, v96, v66
	v_add_f32_e32 v66, v97, v66
	v_add_f32_e32 v66, v104, v66
	v_add_f32_e32 v66, v105, v66
	v_add_f32_e32 v66, v101, v66
	v_mov_b32_e32 v67, v66
	s_nop 1
	v_permlane32_swap_b32_e32 v66, v67
	v_cvt_pk_bf16_f32 v80, v84, v86
	v_cvt_pk_bf16_f32 v81, v82, v85
	v_cvt_pk_bf16_f32 v82, v77, v83
	v_cvt_pk_bf16_f32 v83, v76, v78
	v_cvt_pk_bf16_f32 v76, v73, v75
	v_cvt_pk_bf16_f32 v77, v71, v74
	v_cvt_pk_bf16_f32 v78, v69, v72
	v_cvt_pk_bf16_f32 v79, v68, v70
	v_cvt_pk_bf16_f32 v68, v102, v103
	v_cvt_pk_bf16_f32 v69, v87, v88
	v_cvt_pk_bf16_f32 v70, v89, v90
	v_cvt_pk_bf16_f32 v71, v91, v92
	v_cvt_pk_bf16_f32 v72, v93, v94
	v_cvt_pk_bf16_f32 v73, v95, v96
	v_cvt_pk_bf16_f32 v74, v97, v104
	v_cvt_pk_bf16_f32 v75, v105, v101
	s_nop 0
	v_permlane32_swap_b32_e32 v80, v82
	v_permlane32_swap_b32_e32 v81, v83
	v_permlane32_swap_b32_e32 v76, v78
	v_permlane32_swap_b32_e32 v77, v79
	v_permlane32_swap_b32_e32 v68, v70
	v_permlane32_swap_b32_e32 v69, v71
	v_permlane32_swap_b32_e32 v72, v74
	v_permlane32_swap_b32_e32 v73, v75
	ds_read_b64_tr_b16 v[84:85], v210 offset:0
	ds_read_b64_tr_b16 v[86:87], v210 offset:0x800
	ds_read_b64_tr_b16 v[88:89], v210 offset:0x1000
	ds_read_b64_tr_b16 v[90:91], v210 offset:0x1800
	ds_read_b64_tr_b16 v[92:93], v210 offset:0x2000
	ds_read_b64_tr_b16 v[94:95], v210 offset:0x2800
	ds_read_b64_tr_b16 v[102:103], v210 offset:0x3000
	ds_read_b64_tr_b16 v[104:105], v210 offset:0x3800
	s_waitcnt lgkmcnt(0)
	s_nop 0
	v_mfma_f32_32x32x16_bf16 v[18:33], v[80:83], v[84:87], v[18:33]
	ds_read_b64_tr_b16 v[84:85], v210 offset:0x200
	ds_read_b64_tr_b16 v[86:87], v210 offset:0xa00
	v_mfma_f32_32x32x16_bf16 v[18:33], v[76:79], v[88:91], v[18:33]
	ds_read_b64_tr_b16 v[88:89], v210 offset:0x1200
	ds_read_b64_tr_b16 v[90:91], v210 offset:0x1a00
	v_mfma_f32_32x32x16_bf16 v[18:33], v[68:71], v[92:95], v[18:33]
	ds_read_b64_tr_b16 v[92:93], v210 offset:0x2200
	ds_read_b64_tr_b16 v[94:95], v210 offset:0x2a00
	v_mfma_f32_32x32x16_bf16 v[18:33], v[72:75], v[102:105], v[18:33]
	ds_read_b64_tr_b16 v[102:103], v210 offset:0x3200
	ds_read_b64_tr_b16 v[104:105], v210 offset:0x3a00
	s_waitcnt lgkmcnt(0)
	v_mfma_f32_32x32x16_bf16 v[2:17], v[80:83], v[84:87], v[2:17]
	ds_read_b64_tr_b16 v[84:85], v210 offset:0x400
	ds_read_b64_tr_b16 v[86:87], v210 offset:0xc00
	v_mfma_f32_32x32x16_bf16 v[2:17], v[76:79], v[88:91], v[2:17]
	ds_read_b64_tr_b16 v[88:89], v210 offset:0x1400
	ds_read_b64_tr_b16 v[90:91], v210 offset:0x1c00
	v_mfma_f32_32x32x16_bf16 v[2:17], v[68:71], v[92:95], v[2:17]
	ds_read_b64_tr_b16 v[92:93], v210 offset:0x2400
	ds_read_b64_tr_b16 v[94:95], v210 offset:0x2c00
	v_mfma_f32_32x32x16_bf16 v[2:17], v[72:75], v[102:105], v[2:17]
	ds_read_b64_tr_b16 v[102:103], v210 offset:0x3400
	ds_read_b64_tr_b16 v[104:105], v210 offset:0x3c00
	s_waitcnt lgkmcnt(0)
; __device__ __forceinline__ int opaque_tid() { int t = threadIdx.x; asm volatile("" : "+v"(t)); return t; }
; __device__ __forceinline__ int crow(int r, int hi) { return (r & 3) + 8 * (r >> 2) + 4 * hi; }
; __device__ __forceinline__ unsigned cvtpk(float lo, float hi) { unsigned r; asm volatile("v_cvt_pk_bf16_f32 %0, %1, %2" : "=v"(r) : "v"(lo), "v"(hi)); return r; }
; template <int DK, bool NA, bool QL, int SD> ...
;     ...
;   pv_d0(o, vb0 + (int)SHM_V, pa0, pa1, pa2, pa3);
;   if (hi == 0) li_l[r32] = l_reg; asm volatile("s_waitcnt vmcnt(0) lgkmcnt(0)" ::: "memory");
; #pragma unroll
;   for (int r = 0; r < 16; ++r) { const float rl = __builtin_amdgcn_rcpf(li_l[crow(r, hi)]);
; #pragma unroll
;     for (int d = 0; d < 4; ++d) o[d][r] *= rl; }
; __global__ void __launch_bounds__(NTHR) mega_fwd(Params p) {
;     ...
;                     { const int t2 = opaque_tid(); v4u* STv = (v4u*)((char*)lds + 69632) + t2;
; #pragma unroll
;                       for (int k = 0; k < 8; ++k) { const int d = k >> 1, r0 = 8 * (k & 1); v4u w;
;                           w.x = att::cvtpk(o[d][r0], o[d][r0 + 1]); w.y = att::cvtpk(o[d][r0 + 2], o[d][r0 + 3]); w.z = att::cvtpk(o[d][r0 + 4], o[d][r0 + 5]); w.w = att::cvtpk(o[d][r0 + 6], o[d][r0 + 7]);
;                           STv[k * 512] = w; } }
	v_mfma_f32_32x32x16_bf16 v[50:65], v[80:83], v[84:87], v[50:65]
	ds_read_b64_tr_b16 v[84:85], v210 offset:0x600
	ds_read_b64_tr_b16 v[86:87], v210 offset:0xe00
	v_mfma_f32_32x32x16_bf16 v[50:65], v[76:79], v[88:91], v[50:65]
	ds_read_b64_tr_b16 v[88:89], v210 offset:0x1600
	ds_read_b64_tr_b16 v[90:91], v210 offset:0x1e00
	v_mfma_f32_32x32x16_bf16 v[50:65], v[68:71], v[92:95], v[50:65]
	ds_read_b64_tr_b16 v[92:93], v210 offset:0x2600
	ds_read_b64_tr_b16 v[94:95], v210 offset:0x2e00
	v_mfma_f32_32x32x16_bf16 v[50:65], v[72:75], v[102:105], v[50:65]
	ds_read_b64_tr_b16 v[102:103], v210 offset:0x3600
	ds_read_b64_tr_b16 v[104:105], v210 offset:0x3e00
	s_waitcnt lgkmcnt(0)
	v_mfma_f32_32x32x16_bf16 v[34:49], v[80:83], v[84:87], v[34:49]
	v_mfma_f32_32x32x16_bf16 v[34:49], v[76:79], v[88:91], v[34:49]
	v_mfma_f32_32x32x16_bf16 v[34:49], v[68:71], v[92:95], v[34:49]
	v_mfma_f32_32x32x16_bf16 v[34:49], v[72:75], v[102:105], v[34:49]
	s_and_saveexec_b64 s[2:3], s[0:1]
	v_add_f32_e32 v68, v98, v99
	v_fmac_f32_e32 v68, v209, v143
	v_add_f32_e32 v66, v66, v67
	v_fmac_f32_e32 v66, v68, v100
	ds_write_b32 v208, v66
	s_or_b64 exec, exec, s[2:3]
	s_waitcnt vmcnt(0) lgkmcnt(0)
	v_add_u32_e32 v0, v207, v0
	ds_read_b128 v[66:69], v0
	ds_read_b128 v[70:73], v0 offset:32
	v_readlane_b32 s0, v253, 17
	v_readlane_b32 s1, v253, 18
	s_movk_i32 s3, 0x2800
	s_waitcnt lgkmcnt(1)
	v_rcp_f32_e32 v66, v66
	v_rcp_f32_e32 v67, v67
	s_cmp_lg_u32 0, -1
	s_cselect_b32 s2, 0, 0
	v_mul_f32_e32 v75, v66, v2
	v_rcp_f32_e32 v2, v68
	v_mul_f32_e32 v68, v67, v3
	v_rcp_f32_e32 v3, v69
	v_mul_f32_e32 v74, v66, v18
	v_mul_f32_e32 v50, v66, v50
	v_mul_f32_e32 v34, v66, v34
	v_mul_f32_e32 v66, v67, v19
	v_mul_f32_e32 v51, v67, v51
	v_mul_f32_e32 v35, v67, v35
	v_mul_f32_e32 v67, v2, v20
	v_mul_f32_e32 v69, v2, v4
	v_mul_f32_e32 v52, v2, v52
	v_mul_f32_e32 v36, v2, v36
	v_mul_f32_e32 v76, v3, v21
	s_waitcnt lgkmcnt(0)
	v_rcp_f32_e32 v2, v70
	v_mul_f32_e32 v70, v3, v5
	v_mul_f32_e32 v53, v3, v53
	v_mul_f32_e32 v37, v3, v37
	v_rcp_f32_e32 v3, v71
	v_mul_f32_e32 v22, v2, v22
	v_mul_f32_e32 v6, v2, v6
	v_mul_f32_e32 v54, v2, v54
	v_mul_f32_e32 v38, v2, v38
	v_mul_f32_e32 v23, v3, v23
	v_mul_f32_e32 v7, v3, v7
	v_mul_f32_e32 v55, v3, v55
	v_mul_f32_e32 v39, v3, v39
	ds_read_b128 v[2:5], v0 offset:64
	v_rcp_f32_e32 v18, v72
	v_rcp_f32_e32 v71, v73
	s_mov_b32 s12, s13
	s_mov_b32 s14, s13
	v_mul_f32_e32 v24, v18, v24
	v_mul_f32_e32 v8, v18, v8
	v_mul_f32_e32 v56, v18, v56
	v_mul_f32_e32 v40, v18, v40
	ds_read_b128 v[18:21], v0 offset:96
	s_waitcnt lgkmcnt(1)
	v_rcp_f32_e32 v0, v2
	v_rcp_f32_e32 v2, v3
	v_rcp_f32_e32 v3, v4
	v_mul_f32_e32 v25, v71, v25
	v_mul_f32_e32 v26, v0, v26
	v_mul_f32_e32 v10, v0, v10
	v_mul_f32_e32 v58, v0, v58
	v_mul_f32_e32 v0, v0, v42
	v_mul_f32_e32 v27, v2, v27
	v_mul_f32_e32 v11, v2, v11
	v_mul_f32_e32 v42, v2, v59
	v_mul_f32_e32 v43, v2, v43
	v_rcp_f32_e32 v2, v5
	v_mul_f32_e32 v28, v3, v28
	v_mul_f32_e32 v12, v3, v12
	v_mul_f32_e32 v59, v3, v60
	v_mul_f32_e32 v44, v3, v44
	v_mul_f32_e32 v29, v2, v29
	s_waitcnt lgkmcnt(0)
	v_rcp_f32_e32 v3, v18
	v_mul_f32_e32 v13, v2, v13
	v_mul_f32_e32 v18, v2, v61
	v_mul_f32_e32 v45, v2, v45
	v_rcp_f32_e32 v2, v19
	v_mul_f32_e32 v30, v3, v30
	v_mul_f32_e32 v14, v3, v14
	v_mul_f32_e32 v19, v3, v62
	v_mul_f32_e32 v46, v3, v46
	v_mul_f32_e32 v31, v2, v31
	v_rcp_f32_e32 v3, v20
	v_mul_f32_e32 v15, v2, v15
	v_mul_f32_e32 v20, v2, v63
	v_mul_f32_e32 v47, v2, v47
	v_rcp_f32_e32 v2, v21
	v_mul_f32_e32 v32, v3, v32
	v_mul_f32_e32 v16, v3, v16
	v_mul_f32_e32 v21, v3, v64
	v_mul_f32_e32 v33, v2, v33
	v_mul_f32_e32 v17, v2, v17
	v_mul_f32_e32 v60, v2, v65
	v_mul_f32_e32 v49, v2, v49
	v_mov_b32_e32 v2, v188
	v_mul_f32_e32 v48, v3, v48
	v_lshl_add_u32 v2, v2, 4, 0
	v_add_u32_e32 v61, 0x11000, v2
	v_cvt_pk_bf16_f32 v2, v74, v66
	v_cvt_pk_bf16_f32 v3, v67, v76
	v_cvt_pk_bf16_f32 v4, v22, v23
	v_cvt_pk_bf16_f32 v5, v24, v25
	ds_write_b128 v61, v[2:5]
	v_cvt_pk_bf16_f32 v2, v26, v27
	v_cvt_pk_bf16_f32 v3, v28, v29
	v_cvt_pk_bf16_f32 v4, v30, v31
	v_cvt_pk_bf16_f32 v5, v32, v33
	v_mul_f32_e32 v9, v71, v9
	ds_write_b128 v61, v[2:5] offset:8192
	v_cvt_pk_bf16_f32 v2, v75, v68
	v_cvt_pk_bf16_f32 v3, v69, v70
	v_cvt_pk_bf16_f32 v4, v6, v7
	v_cvt_pk_bf16_f32 v5, v8, v9
	ds_write_b128 v61, v[2:5] offset:16384
	v_cvt_pk_bf16_f32 v2, v10, v11
	v_cvt_pk_bf16_f32 v3, v12, v13
	v_cvt_pk_bf16_f32 v4, v14, v15
	v_cvt_pk_bf16_f32 v5, v16, v17
	v_mul_f32_e32 v57, v71, v57
	ds_write_b128 v61, v[2:5] offset:24576
	v_cvt_pk_bf16_f32 v2, v50, v51
	v_cvt_pk_bf16_f32 v3, v52, v53
	v_cvt_pk_bf16_f32 v4, v54, v55
	v_cvt_pk_bf16_f32 v5, v56, v57
	ds_write_b128 v61, v[2:5] offset:32768
	v_cvt_pk_bf16_f32 v2, v58, v42
	v_cvt_pk_bf16_f32 v3, v59, v18
	v_cvt_pk_bf16_f32 v4, v19, v20
	v_cvt_pk_bf16_f32 v5, v21, v60
	v_mul_f32_e32 v41, v71, v41
	ds_write_b128 v61, v[2:5] offset:40960
	v_cvt_pk_bf16_f32 v2, v34, v35
	v_cvt_pk_bf16_f32 v3, v36, v37
	v_cvt_pk_bf16_f32 v4, v38, v39
	v_cvt_pk_bf16_f32 v5, v40, v41
	v_mov_b32_e32 v74, v188
	ds_write_b128 v61, v[2:5] offset:49152
	v_cvt_pk_bf16_f32 v2, v0, v43
	v_cvt_pk_bf16_f32 v3, v44, v45
	v_cvt_pk_bf16_f32 v4, v46, v47
	v_cvt_pk_bf16_f32 v5, v48, v49
	ds_write_b128 v61, v[2:5] offset:57344
	v_mov_b64_e32 v[50:51], s[0:1]
	v_ashrrev_i32_e32 v75, 4, v74
	v_lshlrev_b32_e32 v16, 3, v74
	v_and_b32_e32 v0, 0x78, v16
	v_add_u32_e32 v17, 32, v75
	v_mad_i64_i32 v[2:3], s[0:1], v75, s3, v[50:51]
	v_lshlrev_b32_e32 v52, 1, v0
	v_mov_b32_e32 v53, v1
	v_mad_i64_i32 v[4:5], s[0:1], v17, s3, v[50:51]
	v_ashrrev_i32_e32 v72, 3, v74
	v_lshl_add_u64 v[2:3], v[2:3], 0, v[52:53]
	v_lshl_add_u64 v[6:7], v[4:5], 0, v[52:53]
	v_lshlrev_b32_e32 v22, 4, v74
; __device__ __forceinline__ int v_st(int k, int c) { const int kk = (k & ~0xC) | ((k & 4) << 1) | ((k & 8) >> 1); return ((kk >> 3) * 4 + (c >> 5)) * 512 + ((kk & 7) * 32 + (c & 31)) * 2; }
; __device__ __forceinline__ int v_rd_base(int lane) { return ((lane & 3) << 3) | (((lane >> 2) & 3) << 6) | (((lane >> 4) & 1) << 5) | (((lane >> 5) & 1) << 8); }
; #define SLOAD(i, k0) do { sr_[i].vs0 = *reinterpret_cast<const bf16x8*>(&Vh[(long)((k0) + sr) * LDP + sc]); sr_[i].vs1 = *reinterpret_cast<const bf16x8*>(&Vh[(long)((k0) + 32 + sr) * LDP + sc]); \
;     sr_[i].ks0 = *reinterpret_cast<const bf16x8*>(&Kh[(long)((k0) + ksr) * LDP + ksc]); if (DK == 128) sr_[i].ks1 = *reinterpret_cast<const bf16x8*>(&Kh[(long)((k0) + 32 + ksr) * LDP + ksc]); } while (0)
; #define HOOK(P0, P1, j) do { if (NA) na_hook(P0, P1, krow0 + (j), q_row, q_col, win_r, win_c, rpb, inv_scale, hi); } while (0)
; template <int DK, bool NA, bool QL, int SD> ...
;     ...
;   const bf16* Qw = Qb + (long)(wid * 32 + r32) * LDP + hi * 8;
; #pragma unroll
;   for (int d0 = 0; d0 < DK / 16; ++d0) { const bf16x8 qv = *reinterpret_cast<const bf16x8*>(Qw + d0 * 16); if (QL) *reinterpret_cast<bf16x8*>(ql + d0 * 1024) = qv; else qr[d0] = qv; }
;   const int sr = tid >> 4, sc = (tid & 15) * 8, vst0 = v_st(sr, sc), vst1 = v_st(32 + sr, sc);
;   const int ksr = DK == 128 ? sr : (tid >> 3), ksc = DK == 128 ? sc : (tid & 7) * 8;
;   const int vb0 = (int)(uintptr_t)V_lds + v_rd_base(lane);
;   struct { bf16x8 vs0, vs1, ks0, ks1; } sr_[SD];
;     ...
;   f32x16 pA0, pA1, pB0, pB1; float mnA, mnB, alA, alB; bf16x8 pa0, pa1, pa2, pa3;
;   constexpr int SE = 0, SO = SD - 1;
;   SLOAD(SE, 0); asm volatile("s_waitcnt vmcnt(0)" ::: "memory"); SWRITE(0, SE); __syncthreads();
;   qkt<DK, QL>(pA0, pA1, K_lds, qr, ql, r32, hi); HOOK(pA0, pA1, 0); partialSM(pA0, pA1, m_reg, mnA, alA, C, thrRaw);
	global_load_dwordx4 v[2:5], v[2:3], off offset:2048
	s_nop 0
	global_load_dwordx4 v[6:9], v[6:7], off offset:2048
	v_mad_i64_i32 v[10:11], s[0:1], v72, s3, v[50:51]
	v_and_b32_e32 v56, 0x70, v22
	v_mov_b32_e32 v57, v1
	v_ashrrev_i32_e32 v0, 1, v74
	s_movk_i32 s0, 0xffe0
	v_lshl_add_u64 v[10:11], v[10:11], 0, v[56:57]
	v_bfi_b32 v0, s0, v0, v74
	v_readlane_b32 s0, v253, 9
	global_load_dwordx4 v[10:13], v[10:11], off offset:1152
	v_readlane_b32 s1, v253, 10
	v_bfe_u32 v18, v16, 5, 2
	v_and_b32_e32 v19, 3, v75
	v_mov_b64_e32 v[14:15], s[0:1]
	v_mad_i64_i32 v[14:15], s[0:1], v0, s3, v[14:15]
	v_lshrrev_b32_e32 v0, 1, v74
	v_and_b32_e32 v0, 16, v0
	v_lshl_add_u64 v[14:15], v[14:15], 0, v[0:1]
	global_load_dwordx4 v[110:113], v[14:15], off offset:128
	global_load_dwordx4 v[106:109], v[14:15], off offset:160
	global_load_dwordx4 v[102:105], v[14:15], off offset:192
	global_load_dwordx4 v[98:101], v[14:15], off offset:224
	v_add_u32_e32 v84, 64, v75
	v_add_u32_e32 v88, 0x60, v75
	v_add_u32_e32 v92, 64, v72
	v_mad_i64_i32 v[84:85], s[0:1], v84, s3, v[50:51]
	v_mad_i64_i32 v[88:89], s[0:1], v88, s3, v[50:51]
	v_mad_i64_i32 v[92:93], s[0:1], v92, s3, v[50:51]
	v_lshl_add_u64 v[84:85], v[84:85], 0, v[52:53]
	v_lshl_add_u64 v[88:89], v[88:89], 0, v[52:53]
	v_lshl_add_u64 v[92:93], v[92:93], 0, v[56:57]
	global_load_dwordx4 v[84:87], v[84:85], off offset:2048
	global_load_dwordx4 v[88:91], v[88:89], off offset:2048
	global_load_dwordx4 v[92:95], v[92:93], off offset:1152
	v_and_b32_e32 v14, 0xfffff0, v75
	v_lshlrev_b32_e32 v15, 1, v75
	v_and_or_b32 v14, v15, 8, v14
	v_lshrrev_b32_e32 v15, 1, v75
	v_lshrrev_b32_e32 v14, 1, v14
	v_or_b32_e32 v14, v14, v18
	v_and_or_b32 v15, v15, 4, v19
	v_lshlrev_b32_e32 v14, 9, v14
	v_lshlrev_b32_e32 v15, 6, v15
	v_and_b32_e32 v19, 48, v22
	v_and_b32_e32 v20, 0xfffff0, v17
	v_lshlrev_b32_e32 v17, 1, v17
	v_or3_b32 v14, v14, v15, v19
	v_and_or_b32 v17, v17, 8, v20
	v_lshrrev_b32_e32 v17, 1, v17
	v_add_u32_e32 v212, 0, v14
	v_and_b32_e32 v76, 31, v74
	v_or_b32_e32 v17, v17, v18
	s_waitcnt vmcnt(0)
	v_lshlrev_b32_e32 v17, 9, v17
	v_lshlrev_b32_e32 v26, 7, v76
	v_and_b32_e32 v27, 0x70, v16
	v_or3_b32 v15, v17, v15, v19
	v_add_u32_e32 v213, 0, v15
	v_and_b32_e32 v77, 63, v74
	v_lshlrev_b32_e32 v28, 3, v77
	v_and_b32_e32 v22, 0xc0, v22
	v_and_or_b32 v29, v28, 24, v22
	v_lshlrev_b32_e32 v22, 1, v74
	v_and_b32_e32 v30, 32, v22
	v_mad_i64_i32 v[58:59], s[0:1], v75, s3, 0
	v_mad_i64_i32 v[54:55], s[0:1], v72, s3, 0
	s_mov_b32 s15, s13
	s_mov_b32 s1, s13
	s_mov_b32 s16, s13
	s_mov_b32 s17, s13
	s_mov_b32 s18, s13
	s_mov_b32 s19, s13
	s_mov_b32 s20, s13
	s_mov_b32 s21, s13
	s_mov_b32 s22, s13
	s_mov_b32 s23, s13
	s_mov_b32 s24, s13
	s_mov_b32 s25, s13
	s_mov_b32 s26, s13
	s_mov_b32 s27, s13
	v_add_u32_e32 v68, 64, v72
	v_mov_b32_e32 v209, 0
	s_waitcnt vmcnt(6)
	ds_write_b128 v212, v[2:5]
	v_lshlrev_b32_e32 v2, 7, v72
	v_and_b32_e32 v3, 0x70, v74
	v_bitop3_b32 v2, v56, v2, v3 bitop3:0xde
	v_add_u32_e32 v214, 0, v2
	v_bitop3_b32 v2, v0, v26, v27 bitop3:0xde
	v_add_u32_e32 v215, 0, v2
	s_waitcnt vmcnt(5)
	ds_write_b128 v213, v[6:9]
	v_add_u32_e32 v72, 0x80, v72
	s_waitcnt vmcnt(4)
	ds_write_b128 v214, v[10:13] offset:32768
	s_waitcnt lgkmcnt(0)
	s_barrier
	ds_read_b128 v[2:5], v215 offset:32768
	ds_read_b128 v[6:9], v215 offset:36864
	s_waitcnt vmcnt(3) lgkmcnt(1)
	v_mfma_f32_32x32x16_bf16 v[34:49], v[2:5], v[110:113], 0
	v_and_b32_e32 v2, 0x3fffffc0, v74
	v_lshl_add_u32 v207, v2, 2, s8
	v_or_b32_e32 v2, 32, v0
	v_bitop3_b32 v2, v2, v26, v27 bitop3:0xde
	v_add_u32_e32 v216, 0, v2
	ds_read_b128 v[18:21], v216 offset:32768
	ds_read_b128 v[22:25], v216 offset:36864
	s_waitcnt vmcnt(2) lgkmcnt(1)
	v_mfma_f32_32x32x16_bf16 v[34:49], v[18:21], v[106:109], v[34:49]
	v_and_b32_e32 v18, 0x100, v28
	v_or3_b32 v78, v29, v30, v18
	v_or_b32_e32 v18, 64, v0
	v_bitop3_b32 v18, v18, v26, v27 bitop3:0xde
	v_add_u32_e32 v217, 0, v18
	ds_read_b128 v[18:21], v217 offset:32768
	s_mov_b32 s8, 1
	v_mfma_f32_32x32x16_bf16 v[2:17], v[6:9], v[110:113], 0
	v_add_u32_e32 v211, s2, v78
	v_writelane_b32 v254, s0, 62
	v_lshl_add_u32 v208, v76, 2, v207
	s_nop 0
	v_writelane_b32 v255, s2, 0
	v_writelane_b32 v255, s3, 1
	v_writelane_b32 v255, s4, 2
	s_waitcnt lgkmcnt(1)
	v_mfma_f32_32x32x16_bf16 v[2:17], v[22:25], v[106:109], v[2:17]
	ds_read_b128 v[22:25], v217 offset:36864
	v_writelane_b32 v255, s5, 3
	v_writelane_b32 v255, s6, 4
	v_writelane_b32 v255, s7, 5
	v_writelane_b32 v255, s8, 6
	v_writelane_b32 v255, s9, 7
	v_writelane_b32 v255, s10, 8
	s_waitcnt vmcnt(1) lgkmcnt(1)
	v_mfma_f32_32x32x16_bf16 v[34:49], v[18:21], v[102:105], v[34:49]
	v_or_b32_e32 v18, 0x60, v0
	v_bitop3_b32 v18, v18, v26, v27 bitop3:0xde
	v_add_u32_e32 v218, 0, v18
	ds_read_b128 v[18:21], v218 offset:32768
	ds_read_b128 v[60:63], v218 offset:36864
	v_writelane_b32 v255, s11, 9
	v_writelane_b32 v255, s12, 10
	s_waitcnt lgkmcnt(2)
	v_mfma_f32_32x32x16_bf16 v[2:17], v[22:25], v[102:105], v[2:17]
	v_writelane_b32 v255, s13, 11
	v_writelane_b32 v255, s14, 12
	v_writelane_b32 v254, s1, 63
	v_writelane_b32 v255, s15, 13
	v_mad_i64_i32 v[68:69], s[0:1], v68, s3, v[50:51]
	v_lshl_add_u64 v[68:69], v[68:69], 0, v[56:57]
	s_waitcnt vmcnt(0) lgkmcnt(1)
	v_mfma_f32_32x32x16_bf16 v[34:49], v[18:21], v[98:101], v[34:49]
	v_mov_b64_e32 v[32:33], s[26:27]
	v_mov_b64_e32 v[18:19], s[12:13]
	v_mov_b64_e32 v[30:31], s[24:25]
	v_mov_b64_e32 v[28:29], s[22:23]
	v_mov_b64_e32 v[26:27], s[20:21]
	v_mov_b64_e32 v[24:25], s[18:19]
	v_mov_b64_e32 v[22:23], s[16:17]
	s_waitcnt lgkmcnt(0)
; #define SLOAD(i, k0) do { sr_[i].vs0 = *reinterpret_cast<const bf16x8*>(&Vh[(long)((k0) + sr) * LDP + sc]); sr_[i].vs1 = *reinterpret_cast<const bf16x8*>(&Vh[(long)((k0) + 32 + sr) * LDP + sc]); \
;     sr_[i].ks0 = *reinterpret_cast<const bf16x8*>(&Kh[(long)((k0) + ksr) * LDP + ksc]); if (DK == 128) sr_[i].ks1 = *reinterpret_cast<const bf16x8*>(&Kh[(long)((k0) + 32 + ksr) * LDP + ksc]); } while (0)
; #define SWAIT() do { if (SD == 1) asm volatile("s_waitcnt vmcnt(0)" ::: "memory"); else if (DK == 128) asm volatile("s_waitcnt vmcnt(4)" ::: "memory"); else asm volatile("s_waitcnt vmcnt(3)" ::: "memory"); } while (0)
; __device__ __forceinline__ void partialSM(f32x16& p0, f32x16& p1, float& m_reg, float& mn, float& alpha, float C, float thrRaw) {
;   float pmax = p0[0];
; #pragma unroll
;   for (int r = 1; r < 16; ++r) pmax = fmaxf(pmax, p0[r]);
; #pragma unroll
;   for (int r = 0; r < 16; ++r) pmax = fmaxf(pmax, p1[r]);
;   { auto rr = __builtin_amdgcn_permlane32_swap(__float_as_uint(pmax), __float_as_uint(pmax), false, false);
;     pmax = fmaxf(__uint_as_float(rr[0]), __uint_as_float(rr[1])); }
;   if (__builtin_expect(__all(pmax - m_reg <= thrRaw), 1)) { mn = m_reg; alpha = 1.f; }
;   else { mn = fmaxf(m_reg, pmax); alpha = __builtin_amdgcn_exp2f((m_reg - mn) * C); m_reg = mn; }
;   float mnC = -mn * C;
; #pragma unroll
;   for (int r = 0; r < 16; ++r) p0[r] = fmaf(p0[r], C, mnC);
; #pragma unroll
;   for (int r = 0; r < 16; ++r) p1[r] = fmaf(p1[r], C, mnC);
; #pragma unroll
;   for (int r = 0; r < 16; ++r) p0[r] = __builtin_amdgcn_exp2f(p0[r]);
; }
; template <int DK, bool NA, bool QL, int SD> ...
;     ...
;   SLOAD(SO, KVBLK); if (SD == 2) { if (2 < NT) SLOAD(SE, 2 * KVBLK); }
;   SWAIT(); SWRITE(1, SO); __syncthreads();
	v_mfma_f32_32x32x16_bf16 v[2:17], v[60:63], v[98:101], v[2:17]
	s_nop 2
	v_max_f32_e32 v60, v35, v35
	v_max_f32_e32 v61, v34, v34
	v_max_f32_e32 v60, v61, v60
	v_max3_f32 v60, v60, v36, v37
	v_max3_f32 v60, v60, v38, v39
	v_max3_f32 v60, v60, v40, v41
	v_max3_f32 v60, v60, v42, v43
	v_max3_f32 v60, v60, v44, v45
	v_max3_f32 v60, v60, v46, v47
	v_max3_f32 v60, v60, v48, v49
	v_max3_f32 v60, v60, v2, v3
	v_max3_f32 v60, v60, v4, v5
	v_max3_f32 v60, v60, v6, v7
	v_max3_f32 v60, v60, v8, v9
	v_max3_f32 v73, v60, v10, v11
	v_max3_f32 v73, v73, v12, v13
	v_add_u32_e32 v60, 64, v75
	v_add_u32_e32 v62, 0x60, v75
	v_max3_f32 v73, v73, v14, v15
	v_mad_i64_i32 v[60:61], s[0:1], v60, s3, v[50:51]
	v_mad_i64_i32 v[62:63], s[0:1], v62, s3, v[50:51]
	v_max3_f32 v79, v73, v16, v17
	v_mad_i64_i32 v[72:73], s[0:1], v72, s3, v[50:51]
	v_lshl_add_u64 v[60:61], v[60:61], 0, v[52:53]
	v_lshl_add_u64 v[64:65], v[62:63], 0, v[52:53]
	v_lshl_add_u64 v[56:57], v[72:73], 0, v[56:57]
	s_nop 0
	v_add_u32_e32 v72, 0x80, v75
	v_mov_b64_e32 v[20:21], s[14:15]
	global_load_dwordx4 v[122:125], v[56:57], off offset:1152
	v_add_u32_e32 v56, 0xa0, v75
	v_mad_i64_i32 v[56:57], s[0:1], v56, s3, v[50:51]
	v_lshl_add_u64 v[56:57], v[56:57], 0, v[52:53]
	v_mad_i64_i32 v[50:51], s[0:1], v72, s3, v[50:51]
	v_lshl_add_u64 v[50:51], v[50:51], 0, v[52:53]
	global_load_dwordx4 v[118:121], v[56:57], off offset:2048
	global_load_dwordx4 v[114:117], v[50:51], off offset:2048
	v_mov_b32_e32 v50, v79
	s_nop 1
	v_permlane32_swap_b32_e32 v79, v50
	v_max_f32_e32 v50, v50, v50
	v_max_f32_e32 v51, v79, v79
	v_max_f32_e32 v50, v51, v50
	v_add_f32_e32 v51, 0x7149f2ca, v50
	s_mov_b32 s0, 0x42800000
	v_max_f32_e32 v50, 0xf149f2ca, v50
	v_cmp_ge_f32_e32 vcc, s0, v51
	v_sub_f32_e32 v51, 0xf149f2ca, v50
	v_mul_f32_e32 v51, 0x3e38aa3b, v51
	v_exp_f32_e32 v51, v51
	s_cmp_eq_u64 vcc, exec
	s_cselect_b64 vcc, -1, 0
	v_cndmask_b32_e32 v142, v50, v199, vcc
	v_mul_f32_e32 v50, 0xbe38aa3b, v142
	v_cndmask_b32_e64 v219, v51, 1.0, vcc
	v_mov_b32_e32 v51, v50
	v_fmac_f32_e32 v51, 0x3e38aa3b, v49
	s_mov_b32 s0, 0x3e38aa3b
	v_fmamk_f32 v34, v34, 0x3e38aa3b, v50
	v_fmamk_f32 v35, v35, 0x3e38aa3b, v50
	v_fmamk_f32 v36, v36, 0x3e38aa3b, v50
	v_fmamk_f32 v37, v37, 0x3e38aa3b, v50
	v_fmamk_f32 v38, v38, 0x3e38aa3b, v50
	v_fmamk_f32 v39, v39, 0x3e38aa3b, v50
	v_fmamk_f32 v40, v40, 0x3e38aa3b, v50
	v_fmamk_f32 v41, v41, 0x3e38aa3b, v50
	v_fmamk_f32 v42, v42, 0x3e38aa3b, v50
	v_fmamk_f32 v43, v43, 0x3e38aa3b, v50
	v_fmamk_f32 v44, v44, 0x3e38aa3b, v50
	v_fmamk_f32 v45, v45, 0x3e38aa3b, v50
	v_fmamk_f32 v46, v46, 0x3e38aa3b, v50
	v_fmamk_f32 v47, v47, 0x3e38aa3b, v50
	v_fmamk_f32 v48, v48, 0x3e38aa3b, v50
	v_pk_fma_f32 v[138:139], v[2:3], s[0:1], v[50:51] op_sel_hi:[1,0,0]
	s_addk_i32 s2, 0x4000
	v_and_b32_e32 v2, 15, v74
	v_exp_f32_e32 v177, v34
	v_exp_f32_e32 v226, v35
	v_exp_f32_e32 v161, v36
	v_exp_f32_e32 v223, v37
	v_exp_f32_e32 v153, v38
	v_exp_f32_e32 v176, v39
	v_exp_f32_e32 v152, v40
	v_exp_f32_e32 v160, v41
	v_exp_f32_e32 v149, v42
	v_exp_f32_e32 v151, v43
	v_exp_f32_e32 v147, v44
	v_exp_f32_e32 v150, v45
	v_exp_f32_e32 v145, v46
	v_exp_f32_e32 v148, v47
	v_exp_f32_e32 v144, v48
	v_exp_f32_e32 v146, v51
	v_add_u32_e32 v210, s2, v78
	v_lshl_or_b32 v58, v2, 4, v58
	v_readlane_b32 s2, v254, 34
	v_and_b32_e32 v2, 7, v74
	s_waitcnt vmcnt(3)
	v_readlane_b32 s3, v254, 35
	v_lshl_or_b32 v54, v2, 4, v54
	v_pk_fma_f32 v[132:133], v[16:17], s[0:1], v[50:51] op_sel_hi:[1,0,0]
	v_pk_fma_f32 v[134:135], v[14:15], s[0:1], v[50:51] op_sel_hi:[1,0,0]
	v_pk_fma_f32 v[140:141], v[12:13], s[0:1], v[50:51] op_sel_hi:[1,0,0]
	v_pk_fma_f32 v[126:127], v[10:11], s[0:1], v[50:51] op_sel_hi:[1,0,0]
	v_pk_fma_f32 v[128:129], v[8:9], s[0:1], v[50:51] op_sel_hi:[1,0,0]
	v_pk_fma_f32 v[130:131], v[6:7], s[0:1], v[50:51] op_sel_hi:[1,0,0]
	v_pk_fma_f32 v[136:137], v[4:5], s[0:1], v[50:51] op_sel_hi:[1,0,0]
	s_waitcnt vmcnt(5)
	ds_write_b128 v212, v[84:87] offset:16384
	s_waitcnt vmcnt(4)
	ds_write_b128 v213, v[88:91] offset:16384
	s_waitcnt vmcnt(3)
	ds_write_b128 v214, v[92:95] offset:49152
	v_lshl_add_u64 v[156:157], s[2:3], 0, v[58:59]
	v_lshl_add_u64 v[158:159], s[2:3], 0, v[54:55]
	v_mov_b64_e32 v[48:49], v[32:33]
	v_mov_b64_e32 v[64:65], v[32:33]
	v_mov_b64_e32 v[2:3], v[18:19]
	v_cmp_gt_u32_e64 s[0:1], 32, v77
	v_mov_b64_e32 v[46:47], v[30:31]
	v_mov_b64_e32 v[44:45], v[28:29]
	v_mov_b64_e32 v[42:43], v[26:27]
	v_mov_b64_e32 v[40:41], v[24:25]
	v_mov_b64_e32 v[38:39], v[22:23]
	v_mov_b64_e32 v[36:37], v[20:21]
	v_mov_b64_e32 v[34:35], v[18:19]
	v_mov_b64_e32 v[62:63], v[30:31]
	v_mov_b64_e32 v[60:61], v[28:29]
	v_mov_b64_e32 v[58:59], v[26:27]
	v_mov_b64_e32 v[56:57], v[24:25]
	v_mov_b64_e32 v[54:55], v[22:23]
	v_mov_b64_e32 v[52:53], v[20:21]
	v_mov_b64_e32 v[50:51], v[18:19]
	v_mov_b64_e32 v[4:5], v[20:21]
	v_mov_b64_e32 v[6:7], v[22:23]
	v_mov_b64_e32 v[8:9], v[24:25]
	v_mov_b64_e32 v[10:11], v[26:27]
	v_mov_b64_e32 v[12:13], v[28:29]
	v_mov_b64_e32 v[14:15], v[30:31]
	v_mov_b64_e32 v[16:17], v[32:33]
	v_mov_b32_e32 v162, 0x27e00
	v_mov_b32_e32 v178, 0
	v_mov_b32_e32 v179, 1
	v_mov_b32_e32 v180, 8
	ds_write_b32 v162, v178
	s_waitcnt lgkmcnt(0)
	s_barrier
; #define SBAR() __builtin_amdgcn_sched_barrier(0)
; #define SLOAD(i, k0) do { sr_[i].vs0 = *reinterpret_cast<const bf16x8*>(&Vh[(long)((k0) + sr) * LDP + sc]); sr_[i].vs1 = *reinterpret_cast<const bf16x8*>(&Vh[(long)((k0) + 32 + sr) * LDP + sc]); \
;     sr_[i].ks0 = *reinterpret_cast<const bf16x8*>(&Kh[(long)((k0) + ksr) * LDP + ksc]); if (DK == 128) sr_[i].ks1 = *reinterpret_cast<const bf16x8*>(&Kh[(long)((k0) + 32 + ksr) * LDP + ksc]); } while (0)
; #define HOOK(P0, P1, j) do { if (NA) na_hook(P0, P1, krow0 + (j), q_row, q_col, win_r, win_c, rpb, inv_scale, hi); } while (0)
; template <int DK, bool NA, bool QL, int SD> ...
;     ...
;     SBAR(); qkt<DK, QL>(pB0, pB1, (bf16*)((char*)K_lds + SHM_K), qr, ql, r32, hi); HOOK(pB0, pB1, j);
;     finishSM(pA0, pA1, alA, l_reg, pa0, pa1, pa2, pa3); SBAR();
;     SLOAD(SO, (j + SD) * KVBLK); SBAR();
;     pv_d0(o, vb0, pa0, pa1, pa2, pa3); partialSM(pB0, pB1, m_reg, mnB, alB, C, thrRaw);
.LBB0_701:
	ds_read_b128 v[66:69], v215 offset:49152
	ds_read_b128 v[70:73], v215 offset:53248
	v_exp_f32_e32 v143, v138
	v_add_f32_e32 v138, 0, v177
	v_add_f32_e32 v138, v226, v138
	s_waitcnt lgkmcnt(1)
	v_mfma_f32_32x32x16_bf16 v[82:97], v[66:69], v[110:113], 0
	v_add_f32_e32 v138, v161, v138
	v_add_f32_e32 v138, v223, v138
	v_add_f32_e32 v138, v153, v138
	ds_read_b128 v[228:231], v216 offset:49152
	ds_read_b128 v[232:235], v216 offset:53248
	v_add_f32_e32 v138, v176, v138
	v_add_f32_e32 v138, v152, v138
	v_add_f32_e32 v138, v160, v138
	s_waitcnt lgkmcnt(2)
	v_mfma_f32_32x32x16_bf16 v[66:81], v[70:73], v[110:113], 0
	v_add_f32_e32 v138, v149, v138
	v_add_f32_e32 v138, v151, v138
	v_add_f32_e32 v138, v147, v138
	v_add_f32_e32 v138, v150, v138
	v_add_f32_e32 v138, v145, v138
	v_exp_f32_e32 v164, v139
	v_add_f32_e32 v138, v148, v138
	s_waitcnt lgkmcnt(1)
	v_mfma_f32_32x32x16_bf16 v[82:97], v[228:231], v[106:109], v[82:97]
	v_exp_f32_e32 v136, v136
	v_add_f32_e32 v138, v144, v138
	v_exp_f32_e32 v137, v137
	v_add_f32_e32 v138, v146, v138
	v_exp_f32_e32 v130, v130
	v_add_f32_e32 v138, v143, v138
	v_exp_f32_e32 v131, v131
	s_waitcnt lgkmcnt(0)
	v_mfma_f32_32x32x16_bf16 v[66:81], v[232:235], v[106:109], v[66:81]
	ds_read_b128 v[228:231], v217 offset:49152
	ds_read_b128 v[232:235], v217 offset:53248
	v_add_f32_e32 v138, v164, v138
	v_exp_f32_e32 v128, v128
	v_add_f32_e32 v138, v136, v138
	v_exp_f32_e32 v129, v129
	v_add_f32_e32 v138, v137, v138
	v_exp_f32_e32 v126, v126
	s_waitcnt lgkmcnt(1)
	v_mfma_f32_32x32x16_bf16 v[82:97], v[228:231], v[102:105], v[82:97]
	v_add_f32_e32 v138, v130, v138
	v_exp_f32_e32 v127, v127
	v_add_f32_e32 v138, v131, v138
	v_exp_f32_e32 v165, v140
	v_add_f32_e32 v138, v128, v138
	v_exp_f32_e32 v166, v141
	v_add_f32_e32 v138, v129, v138
	s_waitcnt lgkmcnt(0)
	v_mfma_f32_32x32x16_bf16 v[66:81], v[232:235], v[102:105], v[66:81]
	ds_read_b128 v[228:231], v218 offset:49152
	ds_read_b128 v[232:235], v218 offset:53248
	v_exp_f32_e32 v134, v134
	v_add_f32_e32 v138, v126, v138
	v_exp_f32_e32 v135, v135
	v_add_f32_e32 v138, v127, v138
	v_exp_f32_e32 v132, v132
	v_add_f32_e32 v138, v165, v138
	s_waitcnt lgkmcnt(1)
	v_mfma_f32_32x32x16_bf16 v[82:97], v[228:231], v[98:101], v[82:97]
	v_exp_f32_e32 v133, v133
	v_add_f32_e32 v138, v166, v138
	v_add_f32_e32 v138, v134, v138
	v_add_f32_e32 v138, v135, v138
	v_add_f32_e32 v138, v132, v138
	v_add_f32_e32 v220, v133, v138
	v_mov_b32_e32 v221, v220
	s_waitcnt lgkmcnt(0)
	v_mfma_f32_32x32x16_bf16 v[66:81], v[232:235], v[98:101], v[66:81]
	v_cvt_pk_bf16_f32 v138, v177, v226
	v_cvt_pk_bf16_f32 v139, v161, v223
	v_cvt_pk_bf16_f32 v140, v153, v176
	v_cvt_pk_bf16_f32 v141, v152, v160
	v_cvt_pk_bf16_f32 v222, v149, v151
	v_cvt_pk_bf16_f32 v223, v147, v150
	v_cvt_pk_bf16_f32 v224, v145, v148
	v_permlane32_swap_b32_e32 v220, v221
	v_permlane32_swap_b32_e32 v138, v140
	v_cvt_pk_bf16_f32 v225, v144, v146
	v_permlane32_swap_b32_e32 v222, v224
	v_cvt_pk_bf16_f32 v144, v143, v164
	v_cvt_pk_bf16_f32 v145, v136, v137
	v_cvt_pk_bf16_f32 v146, v130, v131
	v_cvt_pk_bf16_f32 v147, v128, v129
	v_cvt_pk_bf16_f32 v148, v126, v127
	v_cvt_pk_bf16_f32 v149, v165, v166
	v_cvt_pk_bf16_f32 v150, v134, v135
	v_cvt_pk_bf16_f32 v151, v132, v133
	v_permlane32_swap_b32_e32 v139, v141
	v_permlane32_swap_b32_e32 v223, v225
	v_permlane32_swap_b32_e32 v144, v146
	v_permlane32_swap_b32_e32 v145, v147
	v_permlane32_swap_b32_e32 v148, v150
	v_permlane32_swap_b32_e32 v149, v151
	v_readlane_b32 s2, v254, 32
	v_readlane_b32 s3, v254, 33
	s_mov_b32 s4, 0xe0e0000
	s_mov_b32 s5, 0xe130000
	v_lshl_add_u64 v[160:161], v[156:157], 0, s[2:3]
	v_add_co_u32_e32 v126, vcc, s4, v160
	v_lshl_add_u64 v[176:177], v[158:159], 0, s[2:3]
	s_nop 0
	v_addc_co_u32_e32 v127, vcc, 0, v161, vcc
	v_add_co_u32_e32 v130, vcc, s5, v160
	s_nop 1
	v_addc_co_u32_e32 v131, vcc, 0, v161, vcc
	v_add_co_u32_e32 v134, vcc, s4, v176
	global_load_dwordx4 v[126:129], v[126:127], off offset:2048
	s_nop 0
	global_load_dwordx4 v[130:133], v[130:131], off offset:2048
	v_addc_co_u32_e32 v135, vcc, 0, v177, vcc
	global_load_dwordx4 v[134:137], v[134:135], off offset:1152
	ds_read_b64_tr_b16 v[226:227], v211 offset:0
	ds_read_b64_tr_b16 v[228:229], v211 offset:0x800
	ds_read_b64_tr_b16 v[230:231], v211 offset:0x1000
	ds_read_b64_tr_b16 v[232:233], v211 offset:0x1800
	ds_read_b64_tr_b16 v[234:235], v211 offset:0x2000
	ds_read_b64_tr_b16 v[236:237], v211 offset:0x2800
	ds_read_b64_tr_b16 v[238:239], v211 offset:0x3000
	ds_read_b64_tr_b16 v[240:241], v211 offset:0x3800
	s_waitcnt lgkmcnt(6)
	s_nop 0
	v_mfma_f32_32x32x16_bf16 v[2:17], v[138:141], v[226:229], v[2:17]
	ds_read_b64_tr_b16 v[226:227], v211 offset:0x200
	ds_read_b64_tr_b16 v[228:229], v211 offset:0xa00
	s_waitcnt lgkmcnt(6)
	v_mfma_f32_32x32x16_bf16 v[2:17], v[222:225], v[230:233], v[2:17]
	ds_read_b64_tr_b16 v[230:231], v211 offset:0x1200
	ds_read_b64_tr_b16 v[232:233], v211 offset:0x1a00
	s_waitcnt lgkmcnt(6)
	v_mfma_f32_32x32x16_bf16 v[2:17], v[144:147], v[234:237], v[2:17]
	ds_read_b64_tr_b16 v[234:235], v211 offset:0x2200
	ds_read_b64_tr_b16 v[236:237], v211 offset:0x2a00
	s_waitcnt lgkmcnt(6)
; #define SWAIT() do { if (SD == 1) asm volatile("s_waitcnt vmcnt(0)" ::: "memory"); else if (DK == 128) asm volatile("s_waitcnt vmcnt(4)" ::: "memory"); else asm volatile("s_waitcnt vmcnt(3)" ::: "memory"); } while (0)
; #define RESC(a) do { if (__any((a) < 1.f)) { if (hi == 0) al_l[r32] = (a); asm volatile("s_waitcnt lgkmcnt(0)" ::: "memory"); \
;     _Pragma("unroll") for (int d = 0; d < 4; ++d) _Pragma("unroll") for (int r = 0; r < 16; ++r) o[d][r] *= al_l[crow(r, hi)]; } } while (0)
; template <int DK, bool NA, bool QL, int SD> ...
;     ...
;     pv_d0(o, vb0, pa0, pa1, pa2, pa3); partialSM(pB0, pB1, m_reg, mnB, alB, C, thrRaw);
;     __syncthreads(); SWAIT(); SWRITE(0, SE);
;     RESC(alB); __syncthreads();
	v_mfma_f32_32x32x16_bf16 v[2:17], v[148:151], v[238:241], v[2:17]
	ds_read_b64_tr_b16 v[238:239], v211 offset:0x3200
	ds_read_b64_tr_b16 v[240:241], v211 offset:0x3a00
	s_waitcnt lgkmcnt(6)
	v_mfma_f32_32x32x16_bf16 v[50:65], v[138:141], v[226:229], v[50:65]
	ds_read_b64_tr_b16 v[226:227], v211 offset:0x400
	ds_read_b64_tr_b16 v[228:229], v211 offset:0xc00
	s_waitcnt lgkmcnt(6)
	v_mfma_f32_32x32x16_bf16 v[50:65], v[222:225], v[230:233], v[50:65]
	ds_read_b64_tr_b16 v[230:231], v211 offset:0x1400
	ds_read_b64_tr_b16 v[232:233], v211 offset:0x1c00
	s_waitcnt lgkmcnt(6)
	v_mfma_f32_32x32x16_bf16 v[50:65], v[144:147], v[234:237], v[50:65]
	ds_read_b64_tr_b16 v[234:235], v211 offset:0x2400
	ds_read_b64_tr_b16 v[236:237], v211 offset:0x2c00
	s_waitcnt lgkmcnt(6)
	v_mfma_f32_32x32x16_bf16 v[50:65], v[148:151], v[238:241], v[50:65]
	ds_read_b64_tr_b16 v[238:239], v211 offset:0x3400
	ds_read_b64_tr_b16 v[240:241], v211 offset:0x3c00
	s_waitcnt lgkmcnt(6)
	v_mfma_f32_32x32x16_bf16 v[34:49], v[138:141], v[226:229], v[34:49]
	ds_read_b64_tr_b16 v[226:227], v211 offset:0x600
	ds_read_b64_tr_b16 v[228:229], v211 offset:0xe00
	s_waitcnt lgkmcnt(6)
	v_mfma_f32_32x32x16_bf16 v[34:49], v[222:225], v[230:233], v[34:49]
	ds_read_b64_tr_b16 v[230:231], v211 offset:0x1600
	ds_read_b64_tr_b16 v[232:233], v211 offset:0x1e00
	s_waitcnt lgkmcnt(6)
	v_mfma_f32_32x32x16_bf16 v[34:49], v[144:147], v[234:237], v[34:49]
	ds_read_b64_tr_b16 v[234:235], v211 offset:0x2600
	ds_read_b64_tr_b16 v[236:237], v211 offset:0x2e00
	s_waitcnt lgkmcnt(6)
	v_mfma_f32_32x32x16_bf16 v[34:49], v[148:151], v[238:241], v[34:49]
	ds_read_b64_tr_b16 v[238:239], v211 offset:0x3600
	ds_read_b64_tr_b16 v[240:241], v211 offset:0x3e00
	s_waitcnt lgkmcnt(6)
	v_mfma_f32_32x32x16_bf16 v[18:33], v[138:141], v[226:229], v[18:33]
	v_max_f32_e32 v138, v83, v83
	v_max_f32_e32 v139, v82, v82
	v_max_f32_e32 v138, v139, v138
	v_max3_f32 v138, v138, v84, v85
	v_max3_f32 v138, v138, v86, v87
	v_max3_f32 v138, v138, v88, v89
	v_max3_f32 v138, v138, v90, v91
	v_max3_f32 v138, v138, v92, v93
	v_max3_f32 v138, v138, v94, v95
	s_waitcnt lgkmcnt(4)
	v_mfma_f32_32x32x16_bf16 v[18:33], v[222:225], v[230:233], v[18:33]
	v_max3_f32 v138, v138, v96, v97
	v_max3_f32 v138, v138, v66, v67
	v_max3_f32 v138, v138, v68, v69
	v_max3_f32 v138, v138, v70, v71
	v_max3_f32 v138, v138, v72, v73
	v_max3_f32 v138, v138, v74, v75
	v_max3_f32 v138, v138, v76, v77
	v_max3_f32 v138, v138, v78, v79
	s_waitcnt lgkmcnt(2)
	v_mfma_f32_32x32x16_bf16 v[18:33], v[144:147], v[234:237], v[18:33]
	v_max3_f32 v138, v138, v80, v81
	v_mov_b32_e32 v139, v138
	s_nop 1
	v_permlane32_swap_b32_e32 v138, v139
	v_max_f32_e32 v139, v139, v139
	v_max_f32_e32 v138, v138, v138
	v_max_f32_e32 v138, v138, v139
	v_sub_f32_e32 v139, v138, v142
	s_mov_b32 s2, 0x42800000
	v_cmp_ge_f32_e32 vcc, s2, v139
	v_max_f32_e32 v139, v142, v142
	v_max_f32_e32 v138, v139, v138
	s_waitcnt lgkmcnt(0)
	v_mfma_f32_32x32x16_bf16 v[18:33], v[148:151], v[238:241], v[18:33]
	v_sub_f32_e32 v139, v142, v138
	v_mul_f32_e32 v139, 0x3e38aa3b, v139
	v_exp_f32_e32 v139, v139
	s_cmp_eq_u64 vcc, exec
	s_cselect_b64 s[2:3], -1, 0
	s_waitcnt vmcnt(3)
	v_cndmask_b32_e64 v222, v139, 1.0, s[2:3]
	v_cmp_gt_f32_e32 vcc, 1.0, v222
	s_waitcnt vmcnt(3)
	ds_write_b128 v214, v[122:125] offset:32768
	s_mov_b64 s[6:7], exec
	s_mov_b64 exec, 1
	ds_add_u32 v162, v179
	s_mov_b64 exec, s[6:7]
	s_cbranch_vccz .LBB0_705
	s_and_saveexec_b64 s[4:5], s[0:1]
	ds_write_b32 v208, v222 offset:128
	s_or_b64 exec, exec, s[4:5]
	s_waitcnt lgkmcnt(0)
	v_add_u32_e32 v139, v207, v0
	ds_read_b128 v[144:147], v139 offset:224
	ds_read_b128 v[148:151], v139 offset:192
	ds_read_b128 v[224:227], v139 offset:160
	ds_read_b128 v[228:231], v139 offset:128
	s_waitcnt lgkmcnt(3)
	v_pk_mul_f32 v[14:15], v[14:15], v[144:145]
	s_waitcnt lgkmcnt(2)
	v_pk_mul_f32 v[10:11], v[10:11], v[148:149]
	s_waitcnt lgkmcnt(1)
	v_pk_mul_f32 v[6:7], v[6:7], v[224:225]
	v_pk_mul_f32 v[16:17], v[16:17], v[146:147]
	v_pk_mul_f32 v[12:13], v[12:13], v[150:151]
	v_pk_mul_f32 v[8:9], v[8:9], v[226:227]
	s_waitcnt lgkmcnt(0)
	v_pk_mul_f32 v[4:5], v[4:5], v[230:231]
	v_pk_mul_f32 v[2:3], v[2:3], v[228:229]
	v_pk_mul_f32 v[62:63], v[144:145], v[62:63]
	v_pk_mul_f32 v[58:59], v[148:149], v[58:59]
	v_pk_mul_f32 v[54:55], v[224:225], v[54:55]
	v_pk_mul_f32 v[64:65], v[146:147], v[64:65]
	v_pk_mul_f32 v[60:61], v[150:151], v[60:61]
	v_pk_mul_f32 v[56:57], v[226:227], v[56:57]
	v_pk_mul_f32 v[52:53], v[230:231], v[52:53]
	v_pk_mul_f32 v[50:51], v[228:229], v[50:51]
	v_pk_mul_f32 v[46:47], v[144:145], v[46:47]
	v_pk_mul_f32 v[42:43], v[148:149], v[42:43]
	v_pk_mul_f32 v[38:39], v[224:225], v[38:39]
	v_pk_mul_f32 v[48:49], v[146:147], v[48:49]
	v_pk_mul_f32 v[44:45], v[150:151], v[44:45]
	v_pk_mul_f32 v[40:41], v[226:227], v[40:41]
	v_pk_mul_f32 v[36:37], v[230:231], v[36:37]
	v_pk_mul_f32 v[34:35], v[228:229], v[34:35]
	v_pk_mul_f32 v[30:31], v[144:145], v[30:31]
	v_pk_mul_f32 v[26:27], v[148:149], v[26:27]
	v_pk_mul_f32 v[22:23], v[224:225], v[22:23]
	v_pk_mul_f32 v[32:33], v[146:147], v[32:33]
	v_pk_mul_f32 v[28:29], v[150:151], v[28:29]
	v_pk_mul_f32 v[24:25], v[226:227], v[24:25]
	v_pk_mul_f32 v[20:21], v[230:231], v[20:21]
	v_pk_mul_f32 v[18:19], v[228:229], v[18:19]

; #define SBAR() __builtin_amdgcn_sched_barrier(0)
; #define SLOAD(i, k0) do { sr_[i].vs0 = *reinterpret_cast<const bf16x8*>(&Vh[(long)((k0) + sr) * LDP + sc]); sr_[i].vs1 = *reinterpret_cast<const bf16x8*>(&Vh[(long)((k0) + 32 + sr) * LDP + sc]); \
;     sr_[i].ks0 = *reinterpret_cast<const bf16x8*>(&Kh[(long)((k0) + ksr) * LDP + ksc]); if (DK == 128) sr_[i].ks1 = *reinterpret_cast<const bf16x8*>(&Kh[(long)((k0) + 32 + ksr) * LDP + ksc]); } while (0)
; #define SWAIT() do { if (SD == 1) asm volatile("s_waitcnt vmcnt(0)" ::: "memory"); else if (DK == 128) asm volatile("s_waitcnt vmcnt(4)" ::: "memory"); else asm volatile("s_waitcnt vmcnt(3)" ::: "memory"); } while (0)
; #define RESC(a) do { if (__any((a) < 1.f)) { if (hi == 0) al_l[r32] = (a); asm volatile("s_waitcnt lgkmcnt(0)" ::: "memory"); \
;     _Pragma("unroll") for (int d = 0; d < 4; ++d) _Pragma("unroll") for (int r = 0; r < 16; ++r) o[d][r] *= al_l[crow(r, hi)]; } } while (0)
; #define HOOK(P0, P1, j) do { if (NA) na_hook(P0, P1, krow0 + (j), q_row, q_col, win_r, win_c, rpb, inv_scale, hi); } while (0)
; template <int DK, bool NA, bool QL, int SD> ...
;     ...
;     __syncthreads(); SWAIT(); SWRITE(0, SE);
;     RESC(alB); __syncthreads();
;     SBAR(); qkt<DK, QL>(pA0, pA1, K_lds, qr, ql, r32, hi); HOOK(pA0, pA1, j + 1);
;     finishSM(pB0, pB1, alB, l_reg, pa0, pa1, pa2, pa3); SBAR();
;     if (SD == 1 || j + 3 < NT) SLOAD(SE, (j + 1 + SD) * KVBLK); SBAR();
;     pv_d0(o, vb0 + (int)SHM_V, pa0, pa1, pa2, pa3); partialSM(pA0, pA1, m_reg, mnA, alA, C, thrRaw);
.Lsb_d20_d:
	v_add_u32_e32 v180, 8, v180
	ds_write_b128 v212, v[114:117]
	ds_write_b128 v213, v[118:121]
	ds_read_b128 v[66:69], v215 offset:32768
	ds_read_b128 v[70:73], v215 offset:36864
	v_exp_f32_e32 v164, v233
	v_exp_f32_e32 v233, v224
	v_add_f32_e32 v224, 0, v138
	v_add_f32_e32 v224, v153, v224
	s_waitcnt lgkmcnt(1)
	v_mfma_f32_32x32x16_bf16 v[82:97], v[66:69], v[110:113], 0
	v_add_f32_e32 v224, v139, v224
	v_add_f32_e32 v224, v152, v224
	v_add_f32_e32 v224, v140, v224
	ds_read_b128 v[240:243], v216 offset:32768
	ds_read_b128 v[244:247], v216 offset:36864
	v_add_f32_e32 v224, v151, v224
	v_add_f32_e32 v224, v141, v224
	v_add_f32_e32 v224, v150, v224
	s_waitcnt lgkmcnt(2)
	v_mfma_f32_32x32x16_bf16 v[66:81], v[70:73], v[110:113], 0
	v_add_f32_e32 v224, v142, v224
	v_add_f32_e32 v224, v149, v224
	v_add_f32_e32 v224, v143, v224
	v_add_f32_e32 v224, v148, v224
	v_add_f32_e32 v224, v144, v224
	v_exp_f32_e32 v165, v234
	v_add_f32_e32 v224, v147, v224
	s_waitcnt lgkmcnt(1)
	v_mfma_f32_32x32x16_bf16 v[82:97], v[240:243], v[106:109], v[82:97]
	v_exp_f32_e32 v166, v235
	v_add_f32_e32 v224, v145, v224
	v_exp_f32_e32 v167, v236
	v_add_f32_e32 v224, v146, v224
	v_exp_f32_e32 v172, v237
	v_add_f32_e32 v224, v164, v224
	v_exp_f32_e32 v173, v226
	s_waitcnt lgkmcnt(0)
	v_mfma_f32_32x32x16_bf16 v[66:81], v[244:247], v[106:109], v[66:81]
	ds_read_b128 v[240:243], v217 offset:32768
	ds_read_b128 v[244:247], v217 offset:36864
	v_add_f32_e32 v224, v165, v224
	v_exp_f32_e32 v174, v227
	v_add_f32_e32 v224, v166, v224
	v_exp_f32_e32 v175, v228
	v_add_f32_e32 v224, v167, v224
	v_exp_f32_e32 v226, v229
	s_waitcnt lgkmcnt(1)
	v_mfma_f32_32x32x16_bf16 v[82:97], v[240:243], v[102:105], v[82:97]
	v_add_f32_e32 v224, v172, v224
	v_exp_f32_e32 v227, v230
	v_add_f32_e32 v224, v173, v224
	v_exp_f32_e32 v228, v231
	v_add_f32_e32 v224, v174, v224
	v_exp_f32_e32 v229, v232
	v_add_f32_e32 v224, v175, v224
	s_waitcnt lgkmcnt(0)
	v_mfma_f32_32x32x16_bf16 v[66:81], v[244:247], v[102:105], v[66:81]
	ds_read_b128 v[240:243], v218 offset:32768
	ds_read_b128 v[244:247], v218 offset:36864
	v_exp_f32_e32 v230, v225
	v_add_f32_e32 v224, v226, v224
	v_exp_f32_e32 v231, v238
	v_add_f32_e32 v224, v227, v224
	v_exp_f32_e32 v232, v239
	v_add_f32_e32 v224, v228, v224
	s_waitcnt lgkmcnt(1)
	v_mfma_f32_32x32x16_bf16 v[82:97], v[240:243], v[98:101], v[82:97]
	v_add_f32_e32 v224, v229, v224
	v_add_f32_e32 v224, v230, v224
	v_add_f32_e32 v224, v231, v224
	v_add_f32_e32 v224, v232, v224
	v_add_f32_e32 v224, v233, v224
	v_mov_b32_e32 v225, v224
	v_cvt_pk_bf16_f32 v138, v138, v153
	s_waitcnt lgkmcnt(0)
	v_mfma_f32_32x32x16_bf16 v[66:81], v[244:247], v[98:101], v[66:81]
	v_cvt_pk_bf16_f32 v139, v139, v152
	v_cvt_pk_bf16_f32 v140, v140, v151
	v_cvt_pk_bf16_f32 v141, v141, v150
	v_cvt_pk_bf16_f32 v142, v142, v149
	v_cvt_pk_bf16_f32 v143, v143, v148
	v_cvt_pk_bf16_f32 v144, v144, v147
	v_cvt_pk_bf16_f32 v145, v145, v146
	v_cvt_pk_bf16_f32 v146, v164, v165
	v_cvt_pk_bf16_f32 v147, v166, v167
	v_cvt_pk_bf16_f32 v148, v172, v173
	v_cvt_pk_bf16_f32 v149, v174, v175
	v_cvt_pk_bf16_f32 v150, v226, v227
	v_cvt_pk_bf16_f32 v151, v228, v229
	v_cvt_pk_bf16_f32 v152, v230, v231
	v_cvt_pk_bf16_f32 v153, v232, v233
	v_permlane32_swap_b32_e32 v224, v225
	v_permlane32_swap_b32_e32 v138, v140
	v_permlane32_swap_b32_e32 v139, v141
	v_permlane32_swap_b32_e32 v142, v144
	v_permlane32_swap_b32_e32 v143, v145
	v_permlane32_swap_b32_e32 v146, v148
	v_permlane32_swap_b32_e32 v147, v149
	v_permlane32_swap_b32_e32 v150, v152
	v_permlane32_swap_b32_e32 v151, v153
	s_cmp_gt_u32 s8, 60
	s_cselect_b64 s[4:5], -1, 0
	s_and_b64 vcc, exec, s[4:5]
	s_cbranch_vccnz .Lod_d2
	v_add_co_u32_e32 v114, vcc, 0xe180000, v160
	s_nop 1
	v_addc_co_u32_e32 v115, vcc, 0, v161, vcc
	v_add_co_u32_e32 v118, vcc, 0xe1d0000, v160
	s_nop 1
	v_addc_co_u32_e32 v119, vcc, 0, v161, vcc
	v_add_co_u32_e32 v122, vcc, 0xe180000, v176
	global_load_dwordx4 v[114:117], v[114:115], off offset:2048
	s_nop 0
	global_load_dwordx4 v[118:121], v[118:119], off offset:2048
	v_addc_co_u32_e32 v123, vcc, 0, v177, vcc
	global_load_dwordx4 v[122:125], v[122:123], off offset:1152
.LBB0_707:
	ds_read_b64_tr_b16 v[226:227], v210 offset:0
	ds_read_b64_tr_b16 v[228:229], v210 offset:0x800
	ds_read_b64_tr_b16 v[230:231], v210 offset:0x1000
	ds_read_b64_tr_b16 v[232:233], v210 offset:0x1800
	ds_read_b64_tr_b16 v[234:235], v210 offset:0x2000
	ds_read_b64_tr_b16 v[236:237], v210 offset:0x2800
	ds_read_b64_tr_b16 v[238:239], v210 offset:0x3000
	ds_read_b64_tr_b16 v[240:241], v210 offset:0x3800
	s_waitcnt lgkmcnt(6)
	s_nop 0
	v_mfma_f32_32x32x16_bf16 v[2:17], v[138:141], v[226:229], v[2:17]
	ds_read_b64_tr_b16 v[226:227], v210 offset:0x200
	ds_read_b64_tr_b16 v[228:229], v210 offset:0xa00
	s_waitcnt lgkmcnt(6)
	v_mfma_f32_32x32x16_bf16 v[2:17], v[142:145], v[230:233], v[2:17]
	ds_read_b64_tr_b16 v[230:231], v210 offset:0x1200
	ds_read_b64_tr_b16 v[232:233], v210 offset:0x1a00
	s_waitcnt lgkmcnt(6)
	v_mfma_f32_32x32x16_bf16 v[2:17], v[146:149], v[234:237], v[2:17]
	ds_read_b64_tr_b16 v[234:235], v210 offset:0x2200
	ds_read_b64_tr_b16 v[236:237], v210 offset:0x2a00
	s_waitcnt lgkmcnt(6)
	v_mfma_f32_32x32x16_bf16 v[2:17], v[150:153], v[238:241], v[2:17]
	ds_read_b64_tr_b16 v[238:239], v210 offset:0x3200
	ds_read_b64_tr_b16 v[240:241], v210 offset:0x3a00
	s_waitcnt lgkmcnt(6)
	v_mfma_f32_32x32x16_bf16 v[50:65], v[138:141], v[226:229], v[50:65]
	ds_read_b64_tr_b16 v[226:227], v210 offset:0x400
	ds_read_b64_tr_b16 v[228:229], v210 offset:0xc00
	s_waitcnt lgkmcnt(6)
	v_mfma_f32_32x32x16_bf16 v[50:65], v[142:145], v[230:233], v[50:65]
	ds_read_b64_tr_b16 v[230:231], v210 offset:0x1400
	ds_read_b64_tr_b16 v[232:233], v210 offset:0x1c00
	s_waitcnt lgkmcnt(6)
; #define SBAR() __builtin_amdgcn_sched_barrier(0)
; __device__ __forceinline__ void partialSM(f32x16& p0, f32x16& p1, float& m_reg, float& mn, float& alpha, float C, float thrRaw) {
;   float pmax = p0[0];
; #pragma unroll
;   for (int r = 1; r < 16; ++r) pmax = fmaxf(pmax, p0[r]);
; #pragma unroll
;   for (int r = 0; r < 16; ++r) pmax = fmaxf(pmax, p1[r]);
;   { auto rr = __builtin_amdgcn_permlane32_swap(__float_as_uint(pmax), __float_as_uint(pmax), false, false);
;     pmax = fmaxf(__uint_as_float(rr[0]), __uint_as_float(rr[1])); }
;   if (__builtin_expect(__all(pmax - m_reg <= thrRaw), 1)) { mn = m_reg; alpha = 1.f; }
;   else { mn = fmaxf(m_reg, pmax); alpha = __builtin_amdgcn_exp2f((m_reg - mn) * C); m_reg = mn; }
;   float mnC = -mn * C;
; #pragma unroll
;   for (int r = 0; r < 16; ++r) p0[r] = fmaf(p0[r], C, mnC);
; #pragma unroll
;   for (int r = 0; r < 16; ++r) p1[r] = fmaf(p1[r], C, mnC);
; #pragma unroll
;   for (int r = 0; r < 16; ++r) p0[r] = __builtin_amdgcn_exp2f(p0[r]);
; }
; template <int D0> __device__ __forceinline__ void pv_one(f32x16& od, int vb, bf16x8 pa0, bf16x8 pa1, bf16x8 pa2, bf16x8 pa3) {
;   const s16x4 l0 = tr_read<v_rd_off(D0, 0, 0)>(vb), h0 = tr_read<v_rd_off(D0, 0, 1)>(vb), l1 = tr_read<v_rd_off(D0, 1, 0)>(vb), h1 = tr_read<v_rd_off(D0, 1, 1)>(vb);
;   const s16x4 l2 = tr_read<v_rd_off(D0, 2, 0)>(vb), h2 = tr_read<v_rd_off(D0, 2, 1)>(vb), l3 = tr_read<v_rd_off(D0, 3, 0)>(vb), h3 = tr_read<v_rd_off(D0, 3, 1)>(vb);
;   asm volatile("s_waitcnt lgkmcnt(0)" ::: "memory"); SBAR();
;     ...
;   od = __builtin_amdgcn_mfma_f32_32x32x16_bf16(pa0, PK(l0, h0), od, 0, 0, 0);
;   od = __builtin_amdgcn_mfma_f32_32x32x16_bf16(pa1, PK(l1, h1), od, 0, 0, 0);
;   od = __builtin_amdgcn_mfma_f32_32x32x16_bf16(pa2, PK(l2, h2), od, 0, 0, 0);
;   od = __builtin_amdgcn_mfma_f32_32x32x16_bf16(pa3, PK(l3, h3), od, 0, 0, 0);
;     ...
; }
; __device__ __forceinline__ void pv_d0(f32x16* o, int vb, bf16x8 pa0, bf16x8 pa1, bf16x8 pa2, bf16x8 pa3) {
;   pv_one<0>(o[0], vb, pa0, pa1, pa2, pa3); pv_one<1>(o[1], vb, pa0, pa1, pa2, pa3); pv_one<2>(o[2], vb, pa0, pa1, pa2, pa3); pv_one<3>(o[3], vb, pa0, pa1, pa2, pa3);
	v_mfma_f32_32x32x16_bf16 v[50:65], v[146:149], v[234:237], v[50:65]
	ds_read_b64_tr_b16 v[234:235], v210 offset:0x2400
	ds_read_b64_tr_b16 v[236:237], v210 offset:0x2c00
	s_waitcnt lgkmcnt(6)
	v_mfma_f32_32x32x16_bf16 v[50:65], v[150:153], v[238:241], v[50:65]
	ds_read_b64_tr_b16 v[238:239], v210 offset:0x3400
	ds_read_b64_tr_b16 v[240:241], v210 offset:0x3c00
	s_waitcnt lgkmcnt(6)
	v_mfma_f32_32x32x16_bf16 v[34:49], v[138:141], v[226:229], v[34:49]
	ds_read_b64_tr_b16 v[226:227], v210 offset:0x600
	ds_read_b64_tr_b16 v[228:229], v210 offset:0xe00
	s_waitcnt lgkmcnt(6)
	v_mfma_f32_32x32x16_bf16 v[34:49], v[142:145], v[230:233], v[34:49]
	ds_read_b64_tr_b16 v[230:231], v210 offset:0x1600
	ds_read_b64_tr_b16 v[232:233], v210 offset:0x1e00
	s_waitcnt lgkmcnt(6)
	v_mfma_f32_32x32x16_bf16 v[34:49], v[146:149], v[234:237], v[34:49]
	ds_read_b64_tr_b16 v[234:235], v210 offset:0x2600
	ds_read_b64_tr_b16 v[236:237], v210 offset:0x2e00
	s_waitcnt lgkmcnt(6)
	v_mfma_f32_32x32x16_bf16 v[34:49], v[150:153], v[238:241], v[34:49]
	ds_read_b64_tr_b16 v[238:239], v210 offset:0x3600
	ds_read_b64_tr_b16 v[240:241], v210 offset:0x3e00
	s_waitcnt lgkmcnt(6)
	v_mfma_f32_32x32x16_bf16 v[18:33], v[138:141], v[226:229], v[18:33]
	v_max_f32_e32 v138, v83, v83
	v_max_f32_e32 v139, v82, v82
	v_max_f32_e32 v138, v139, v138
	v_max3_f32 v138, v138, v84, v85
	v_max3_f32 v138, v138, v86, v87
	v_max3_f32 v138, v138, v88, v89
	v_max3_f32 v138, v138, v90, v91
	v_max3_f32 v138, v138, v92, v93
	v_max3_f32 v138, v138, v94, v95
	s_waitcnt lgkmcnt(4)
	v_mfma_f32_32x32x16_bf16 v[18:33], v[142:145], v[230:233], v[18:33]
	v_max3_f32 v138, v138, v96, v97
	v_max3_f32 v138, v138, v66, v67
	v_max3_f32 v138, v138, v68, v69
	v_max3_f32 v138, v138, v70, v71
	v_max3_f32 v138, v138, v72, v73
	v_max3_f32 v138, v138, v74, v75
	v_max3_f32 v138, v138, v76, v77
	v_max3_f32 v138, v138, v78, v79
	s_waitcnt lgkmcnt(2)
	v_mfma_f32_32x32x16_bf16 v[18:33], v[146:149], v[234:237], v[18:33]
	v_max3_f32 v138, v138, v80, v81
	v_mov_b32_e32 v139, v138
	s_nop 1
	v_permlane32_swap_b32_e32 v138, v139
	v_max_f32_e32 v139, v139, v139
	v_max_f32_e32 v138, v138, v138
	v_max_f32_e32 v138, v138, v139
	v_sub_f32_e32 v139, v138, v223
	s_mov_b32 s2, 0x42800000
	v_cmp_ge_f32_e32 vcc, s2, v139
	v_max_f32_e32 v139, v223, v223
	v_max_f32_e32 v138, v139, v138
	s_waitcnt lgkmcnt(0)
	v_mfma_f32_32x32x16_bf16 v[18:33], v[150:153], v[238:241], v[18:33]
	v_sub_f32_e32 v139, v223, v138
	v_mul_f32_e32 v139, 0x3e38aa3b, v139
	v_exp_f32_e32 v139, v139
	s_cmp_eq_u64 vcc, exec
	s_cselect_b64 s[2:3], -1, 0
	s_waitcnt vmcnt(3)
	v_cndmask_b32_e64 v143, v139, 1.0, s[2:3]
	v_cmp_gt_f32_e32 vcc, 1.0, v143
	v_mov_b64_e32 v[182:183], v[126:127]
	v_mov_b64_e32 v[184:185], v[128:129]
	v_mov_b64_e32 v[194:195], v[130:131]
	v_mov_b64_e32 v[196:197], v[132:133]
	ds_write_b128 v214, v[134:137] offset:49152
	s_mov_b64 s[6:7], exec
	s_mov_b64 exec, 1
	ds_add_u32 v162, v179
	s_mov_b64 exec, s[6:7]
	s_cbranch_vccz .LBB0_711
	s_and_saveexec_b64 s[6:7], s[0:1]
	ds_write_b32 v208, v143 offset:128
	s_or_b64 exec, exec, s[6:7]
	s_waitcnt lgkmcnt(0)
	v_add_u32_e32 v139, v207, v0
	ds_read_b128 v[126:129], v139 offset:224
	ds_read_b128 v[130:133], v139 offset:192
	ds_read_b128 v[134:137], v139 offset:160
	ds_read_b128 v[144:147], v139 offset:128
	s_waitcnt lgkmcnt(3)
	v_pk_mul_f32 v[14:15], v[14:15], v[126:127]
	s_waitcnt lgkmcnt(2)
	v_pk_mul_f32 v[10:11], v[10:11], v[130:131]
	s_waitcnt lgkmcnt(1)
	v_pk_mul_f32 v[6:7], v[6:7], v[134:135]
	v_pk_mul_f32 v[16:17], v[16:17], v[128:129]
	v_pk_mul_f32 v[12:13], v[12:13], v[132:133]
	v_pk_mul_f32 v[8:9], v[8:9], v[136:137]
	s_waitcnt lgkmcnt(0)
	v_pk_mul_f32 v[4:5], v[4:5], v[146:147]
	v_pk_mul_f32 v[2:3], v[2:3], v[144:145]
	v_pk_mul_f32 v[62:63], v[126:127], v[62:63]
	v_pk_mul_f32 v[58:59], v[130:131], v[58:59]
	v_pk_mul_f32 v[54:55], v[134:135], v[54:55]
	v_pk_mul_f32 v[64:65], v[128:129], v[64:65]
	v_pk_mul_f32 v[60:61], v[132:133], v[60:61]
	v_pk_mul_f32 v[56:57], v[136:137], v[56:57]
	v_pk_mul_f32 v[52:53], v[146:147], v[52:53]
	v_pk_mul_f32 v[50:51], v[144:145], v[50:51]
	v_pk_mul_f32 v[46:47], v[126:127], v[46:47]
	v_pk_mul_f32 v[42:43], v[130:131], v[42:43]
	v_pk_mul_f32 v[38:39], v[134:135], v[38:39]
	v_pk_mul_f32 v[48:49], v[128:129], v[48:49]
	v_pk_mul_f32 v[44:45], v[132:133], v[44:45]
	v_pk_mul_f32 v[40:41], v[136:137], v[40:41]
	v_pk_mul_f32 v[36:37], v[146:147], v[36:37]
	v_pk_mul_f32 v[34:35], v[144:145], v[34:35]
	v_pk_mul_f32 v[30:31], v[126:127], v[30:31]
	v_pk_mul_f32 v[26:27], v[130:131], v[26:27]
	v_pk_mul_f32 v[22:23], v[134:135], v[22:23]
	v_pk_mul_f32 v[32:33], v[128:129], v[32:33]
	v_pk_mul_f32 v[28:29], v[132:133], v[28:29]
	v_pk_mul_f32 v[24:25], v[136:137], v[24:25]
	v_pk_mul_f32 v[20:21], v[146:147], v[20:21]
	v_pk_mul_f32 v[18:19], v[144:145], v[18:19]
.LBB0_711:
	ds_read_b32 v178, v162
	v_cndmask_b32_e64 v142, v138, v223, s[2:3]
	v_mul_f32_e32 v132, 0xbe38aa3b, v142
	v_mov_b32_e32 v133, v132
	v_fmamk_f32 v82, v82, 0x3e38aa3b, v132
	v_fmamk_f32 v83, v83, 0x3e38aa3b, v132
	v_fmamk_f32 v84, v84, 0x3e38aa3b, v132
	v_fmamk_f32 v85, v85, 0x3e38aa3b, v132
	v_fmamk_f32 v86, v86, 0x3e38aa3b, v132
	v_fmamk_f32 v87, v87, 0x3e38aa3b, v132
	v_fmamk_f32 v88, v88, 0x3e38aa3b, v132
	v_fmamk_f32 v89, v89, 0x3e38aa3b, v132
	v_fmamk_f32 v90, v90, 0x3e38aa3b, v132
	v_fmamk_f32 v91, v91, 0x3e38aa3b, v132
	v_fmamk_f32 v92, v92, 0x3e38aa3b, v132
	v_fmamk_f32 v93, v93, 0x3e38aa3b, v132
	v_fmamk_f32 v94, v94, 0x3e38aa3b, v132
	v_fmamk_f32 v95, v95, 0x3e38aa3b, v132
	v_fmamk_f32 v96, v96, 0x3e38aa3b, v132
	v_fmac_f32_e32 v133, 0x3e38aa3b, v97
	s_mov_b32 s2, 0x3e38aa3b
	v_exp_f32_e32 v177, v82
	v_exp_f32_e32 v226, v83
	v_exp_f32_e32 v161, v84
	v_exp_f32_e32 v223, v85
	v_exp_f32_e32 v153, v86
	v_exp_f32_e32 v176, v87
	v_exp_f32_e32 v152, v88
	v_exp_f32_e32 v160, v89
	v_exp_f32_e32 v149, v90
	v_exp_f32_e32 v151, v91
	v_exp_f32_e32 v147, v92
	v_exp_f32_e32 v150, v93
	v_exp_f32_e32 v145, v94
	v_exp_f32_e32 v148, v95
	v_exp_f32_e32 v144, v96
	v_exp_f32_e32 v146, v133
	v_pk_fma_f32 v[138:139], v[66:67], s[2:3], v[132:133] op_sel_hi:[1,0,0]
	v_add_f32_e32 v66, v220, v221
	v_pk_fma_f32 v[136:137], v[68:69], s[2:3], v[132:133] op_sel_hi:[1,0,0]
	v_pk_fma_f32 v[130:131], v[70:71], s[2:3], v[132:133] op_sel_hi:[1,0,0]
	v_pk_fma_f32 v[128:129], v[72:73], s[2:3], v[132:133] op_sel_hi:[1,0,0]
	v_pk_fma_f32 v[126:127], v[74:75], s[2:3], v[132:133] op_sel_hi:[1,0,0]
	v_pk_fma_f32 v[140:141], v[76:77], s[2:3], v[132:133] op_sel_hi:[1,0,0]
	v_pk_fma_f32 v[134:135], v[78:79], s[2:3], v[132:133] op_sel_hi:[1,0,0]
	v_pk_fma_f32 v[132:133], v[80:81], s[2:3], v[132:133] op_sel_hi:[1,0,0]
	v_fmac_f32_e32 v66, v219, v209
	v_add_f32_e32 v209, v224, v225
	s_mov_b64 s[2:3], 0x140000
	v_fmac_f32_e32 v209, v66, v222
	s_add_i32 s8, s8, 2
	v_lshl_add_u64 v[156:157], v[156:157], 0, s[2:3]
	v_lshl_add_u64 v[158:159], v[158:159], 0, s[2:3]
	s_and_b64 vcc, exec, s[4:5]
	v_mov_b32_e32 v155, 0

; #define SWAIT() do { if (SD == 1) asm volatile("s_waitcnt vmcnt(0)" ::: "memory"); else if (DK == 128) asm volatile("s_waitcnt vmcnt(4)" ::: "memory"); else asm volatile("s_waitcnt vmcnt(3)" ::: "memory"); } while (0)
; #define RESC(a) do { if (__any((a) < 1.f)) { if (hi == 0) al_l[r32] = (a); asm volatile("s_waitcnt lgkmcnt(0)" ::: "memory"); \
;     _Pragma("unroll") for (int d = 0; d < 4; ++d) _Pragma("unroll") for (int r = 0; r < 16; ++r) o[d][r] *= al_l[crow(r, hi)]; } } while (0)
; template <int DK, bool NA, bool QL, int SD> ...
;     ...
;     __syncthreads(); SWAIT(); SWRITE(1, SO);
;     RESC(alA); __syncthreads();
;   }
.Lsb_d21_d:
	v_add_u32_e32 v180, 8, v180
	s_cbranch_vccnz .LBB0_713
	v_mov_b32_e32 v219, v143
	ds_write_b128 v212, v[182:185] offset:16384
	ds_write_b128 v213, v[194:197] offset:16384
	s_branch .LBB0_701
